# GEMM K-loops: MFMAs ordered A-operand-major (four consecutive MFMAs share the A fragment)
# baseline (speedup 1.0000x reference)
.Lgk0_loop:
	ds_read_b128 v[128:131], v233
	ds_read_b128 v[136:139], v237
	ds_read_b128 v[132:135], v233 offset:4096
	ds_read_b128 v[140:143], v237 offset:4096
	ds_read_b128 v[144:147], v237 offset:8192
	ds_read_b128 v[148:151], v237 offset:12288
	s_waitcnt lgkmcnt(6)
	v_mfma_f32_32x32x16_bf16 v[112:127], v[206:209], v[216:219], v[112:127]
	v_mfma_f32_32x32x16_bf16 v[96:111], v[206:209], v[220:223], v[96:111]
	v_mfma_f32_32x32x16_bf16 v[80:95], v[206:209], v[224:227], v[80:95]
	v_mfma_f32_32x32x16_bf16 v[64:79], v[206:209], v[228:231], v[64:79]
	v_mfma_f32_32x32x16_bf16 v[48:63], v[212:215], v[216:219], v[48:63]
	v_mfma_f32_32x32x16_bf16 v[32:47], v[212:215], v[220:223], v[32:47]
	v_mfma_f32_32x32x16_bf16 v[16:31], v[212:215], v[224:227], v[16:31]
	v_mfma_f32_32x32x16_bf16 v[0:15], v[212:215], v[228:231], v[0:15]
	ds_read_b128 v[206:209], v234
	ds_read_b128 v[216:219], v238
	ds_read_b128 v[212:215], v234 offset:4096
	ds_read_b128 v[220:223], v238 offset:4096
	ds_read_b128 v[224:227], v238 offset:8192
	ds_read_b128 v[228:231], v238 offset:12288
	s_waitcnt lgkmcnt(6)
	v_mfma_f32_32x32x16_bf16 v[112:127], v[128:131], v[136:139], v[112:127]
	v_mfma_f32_32x32x16_bf16 v[96:111], v[128:131], v[140:143], v[96:111]
	v_mfma_f32_32x32x16_bf16 v[80:95], v[128:131], v[144:147], v[80:95]
	v_mfma_f32_32x32x16_bf16 v[64:79], v[128:131], v[148:151], v[64:79]
	v_mfma_f32_32x32x16_bf16 v[48:63], v[132:135], v[136:139], v[48:63]
	v_mfma_f32_32x32x16_bf16 v[32:47], v[132:135], v[140:143], v[32:47]
	v_mfma_f32_32x32x16_bf16 v[16:31], v[132:135], v[144:147], v[16:31]
	v_mfma_f32_32x32x16_bf16 v[0:15], v[132:135], v[148:151], v[0:15]
	ds_read_b128 v[128:131], v235
	ds_read_b128 v[136:139], v239
	ds_read_b128 v[132:135], v235 offset:4096
	ds_read_b128 v[140:143], v239 offset:4096
	ds_read_b128 v[144:147], v239 offset:8192
	ds_read_b128 v[148:151], v239 offset:12288
	s_waitcnt lgkmcnt(6)
	v_mfma_f32_32x32x16_bf16 v[112:127], v[206:209], v[216:219], v[112:127]
	v_mfma_f32_32x32x16_bf16 v[96:111], v[206:209], v[220:223], v[96:111]
	v_mfma_f32_32x32x16_bf16 v[80:95], v[206:209], v[224:227], v[80:95]
	v_mfma_f32_32x32x16_bf16 v[64:79], v[206:209], v[228:231], v[64:79]
	v_mfma_f32_32x32x16_bf16 v[48:63], v[212:215], v[216:219], v[48:63]
	v_mfma_f32_32x32x16_bf16 v[32:47], v[212:215], v[220:223], v[32:47]
	v_mfma_f32_32x32x16_bf16 v[16:31], v[212:215], v[224:227], v[16:31]
	v_mfma_f32_32x32x16_bf16 v[0:15], v[212:215], v[228:231], v[0:15]
	s_waitcnt vmcnt(0) lgkmcnt(0)
	s_barrier
	ds_read_b128 v[206:209], v205
	ds_read_b128 v[216:219], v243
	ds_read_b128 v[212:215], v205 offset:4096
	ds_read_b128 v[220:223], v243 offset:4096
	ds_read_b128 v[224:227], v243 offset:8192
	ds_read_b128 v[228:231], v243 offset:12288
	s_add_u32 s94, s2, s92
	s_add_u32 s94, s94, 0x100
	s_and_b32 s94, s94, 0x780
	s_sub_u32 s94, s94, 0x80
	s_subb_u32 s95, 0, 0
	s_add_u32 s100, s96, s94
	s_addc_u32 s101, s97, s95
	s_add_u32 s94, s98, s94
	s_addc_u32 s95, s99, s95
	s_add_u32 s90, s88, s89
	s_add_u32 m0, s90, 0
	v_mfma_f32_32x32x16_bf16 v[112:127], v[128:131], v[136:139], v[112:127]
	global_load_lds_dwordx4 v152, s[100:101]
	s_add_u32 m0, s90, 32768
	v_mfma_f32_32x32x16_bf16 v[96:111], v[128:131], v[140:143], v[96:111]
	global_load_lds_dwordx4 v153, s[94:95]
	s_add_u32 m0, s90, 8192
	v_mfma_f32_32x32x16_bf16 v[80:95], v[128:131], v[144:147], v[80:95]
	global_load_lds_dwordx4 v154, s[100:101]
	s_add_u32 m0, s90, 40960
	v_mfma_f32_32x32x16_bf16 v[64:79], v[128:131], v[148:151], v[64:79]
	global_load_lds_dwordx4 v155, s[94:95]
	s_add_u32 m0, s90, 16384
	v_mfma_f32_32x32x16_bf16 v[48:63], v[132:135], v[136:139], v[48:63]
	global_load_lds_dwordx4 v156, s[100:101]
	s_add_u32 m0, s90, 49152
	v_mfma_f32_32x32x16_bf16 v[32:47], v[132:135], v[140:143], v[32:47]
	global_load_lds_dwordx4 v157, s[94:95]
	s_add_u32 m0, s90, 24576
	v_mfma_f32_32x32x16_bf16 v[16:31], v[132:135], v[144:147], v[16:31]
	global_load_lds_dwordx4 v158, s[100:101]
	s_add_u32 m0, s90, 57344
	v_mfma_f32_32x32x16_bf16 v[0:15], v[132:135], v[148:151], v[0:15]
	global_load_lds_dwordx4 v160, s[94:95]
	s_xor_b32 s89, s89, 0x10000
	s_add_i32 s6, s6, 1
	s_add_u32 s2, s2, 0x80
	s_addc_u32 s3, s3, 0
	ds_read_b128 v[128:131], v240
	ds_read_b128 v[136:139], v253
	ds_read_b128 v[132:135], v240 offset:4096
	ds_read_b128 v[140:143], v253 offset:4096
	ds_read_b128 v[144:147], v253 offset:8192
	ds_read_b128 v[148:151], v253 offset:12288
	s_waitcnt lgkmcnt(6)
	v_mfma_f32_32x32x16_bf16 v[112:127], v[206:209], v[216:219], v[112:127]
	v_mfma_f32_32x32x16_bf16 v[96:111], v[206:209], v[220:223], v[96:111]
	v_mfma_f32_32x32x16_bf16 v[80:95], v[206:209], v[224:227], v[80:95]
	v_mfma_f32_32x32x16_bf16 v[64:79], v[206:209], v[228:231], v[64:79]
	v_mfma_f32_32x32x16_bf16 v[48:63], v[212:215], v[216:219], v[48:63]
	v_mfma_f32_32x32x16_bf16 v[32:47], v[212:215], v[220:223], v[32:47]
	v_mfma_f32_32x32x16_bf16 v[16:31], v[212:215], v[224:227], v[16:31]
	v_mfma_f32_32x32x16_bf16 v[0:15], v[212:215], v[228:231], v[0:15]
	ds_read_b128 v[206:209], v241
	ds_read_b128 v[216:219], v254
	ds_read_b128 v[212:215], v241 offset:4096
	ds_read_b128 v[220:223], v254 offset:4096
	ds_read_b128 v[224:227], v254 offset:8192
	ds_read_b128 v[228:231], v254 offset:12288
	s_waitcnt lgkmcnt(6)
	v_mfma_f32_32x32x16_bf16 v[112:127], v[128:131], v[136:139], v[112:127]
	v_mfma_f32_32x32x16_bf16 v[96:111], v[128:131], v[140:143], v[96:111]
	v_mfma_f32_32x32x16_bf16 v[80:95], v[128:131], v[144:147], v[80:95]
	v_mfma_f32_32x32x16_bf16 v[64:79], v[128:131], v[148:151], v[64:79]
	v_mfma_f32_32x32x16_bf16 v[48:63], v[132:135], v[136:139], v[48:63]
	v_mfma_f32_32x32x16_bf16 v[32:47], v[132:135], v[140:143], v[32:47]
	v_mfma_f32_32x32x16_bf16 v[16:31], v[132:135], v[144:147], v[16:31]
	v_mfma_f32_32x32x16_bf16 v[0:15], v[132:135], v[148:151], v[0:15]
	ds_read_b128 v[128:131], v242
	ds_read_b128 v[136:139], v255
	ds_read_b128 v[132:135], v242 offset:4096
	ds_read_b128 v[140:143], v255 offset:4096
	ds_read_b128 v[144:147], v255 offset:8192
	ds_read_b128 v[148:151], v255 offset:12288
	s_waitcnt lgkmcnt(6)
	v_mfma_f32_32x32x16_bf16 v[112:127], v[206:209], v[216:219], v[112:127]
	v_mfma_f32_32x32x16_bf16 v[96:111], v[206:209], v[220:223], v[96:111]
	v_mfma_f32_32x32x16_bf16 v[80:95], v[206:209], v[224:227], v[80:95]
	v_mfma_f32_32x32x16_bf16 v[64:79], v[206:209], v[228:231], v[64:79]
	v_mfma_f32_32x32x16_bf16 v[48:63], v[212:215], v[216:219], v[48:63]
	v_mfma_f32_32x32x16_bf16 v[32:47], v[212:215], v[220:223], v[32:47]
	v_mfma_f32_32x32x16_bf16 v[16:31], v[212:215], v[224:227], v[16:31]
	v_mfma_f32_32x32x16_bf16 v[0:15], v[212:215], v[228:231], v[0:15]
	s_waitcnt vmcnt(0) lgkmcnt(0)
	s_barrier
	ds_read_b128 v[206:209], v232
	ds_read_b128 v[216:219], v236
	ds_read_b128 v[212:215], v232 offset:4096
	ds_read_b128 v[220:223], v236 offset:4096
	ds_read_b128 v[224:227], v236 offset:8192
	ds_read_b128 v[228:231], v236 offset:12288
	s_add_u32 s94, s2, s92
	s_add_u32 s94, s94, 0x100
	s_and_b32 s94, s94, 0x780
	s_sub_u32 s94, s94, 0x80
	s_subb_u32 s95, 0, 0
	s_add_u32 s100, s96, s94
	s_addc_u32 s101, s97, s95
	s_add_u32 s94, s98, s94
	s_addc_u32 s95, s99, s95
	s_add_u32 s90, s88, s89
	s_add_u32 m0, s90, 0
	v_mfma_f32_32x32x16_bf16 v[112:127], v[128:131], v[136:139], v[112:127]
	global_load_lds_dwordx4 v152, s[100:101]
	s_add_u32 m0, s90, 32768
	v_mfma_f32_32x32x16_bf16 v[96:111], v[128:131], v[140:143], v[96:111]
	global_load_lds_dwordx4 v153, s[94:95]
	s_add_u32 m0, s90, 8192
	v_mfma_f32_32x32x16_bf16 v[80:95], v[128:131], v[144:147], v[80:95]
	global_load_lds_dwordx4 v154, s[100:101]
	s_add_u32 m0, s90, 40960
	v_mfma_f32_32x32x16_bf16 v[64:79], v[128:131], v[148:151], v[64:79]
	global_load_lds_dwordx4 v155, s[94:95]
	s_add_u32 m0, s90, 16384
	v_mfma_f32_32x32x16_bf16 v[48:63], v[132:135], v[136:139], v[48:63]
	global_load_lds_dwordx4 v156, s[100:101]
	s_add_u32 m0, s90, 49152
	v_mfma_f32_32x32x16_bf16 v[32:47], v[132:135], v[140:143], v[32:47]
	global_load_lds_dwordx4 v157, s[94:95]
	s_add_u32 m0, s90, 24576
	v_mfma_f32_32x32x16_bf16 v[16:31], v[132:135], v[144:147], v[16:31]
	global_load_lds_dwordx4 v158, s[100:101]
	s_add_u32 m0, s90, 57344
	v_mfma_f32_32x32x16_bf16 v[0:15], v[132:135], v[148:151], v[0:15]
	global_load_lds_dwordx4 v160, s[94:95]
	s_xor_b32 s89, s89, 0x10000
	s_add_i32 s6, s6, 1
	s_add_u32 s2, s2, 0x80
	s_addc_u32 s3, s3, 0
	s_cmpk_eq_i32 s2, 0x700
	s_cbranch_scc0 .Lgk0_loop
	ds_read_b128 v[128:131], v233
	ds_read_b128 v[136:139], v237
	ds_read_b128 v[132:135], v233 offset:4096
	ds_read_b128 v[140:143], v237 offset:4096
	ds_read_b128 v[144:147], v237 offset:8192
	ds_read_b128 v[148:151], v237 offset:12288
	s_waitcnt lgkmcnt(6)
	v_mfma_f32_32x32x16_bf16 v[112:127], v[206:209], v[216:219], v[112:127]
	v_mfma_f32_32x32x16_bf16 v[96:111], v[206:209], v[220:223], v[96:111]
	v_mfma_f32_32x32x16_bf16 v[80:95], v[206:209], v[224:227], v[80:95]
	v_mfma_f32_32x32x16_bf16 v[64:79], v[206:209], v[228:231], v[64:79]
	v_mfma_f32_32x32x16_bf16 v[48:63], v[212:215], v[216:219], v[48:63]
	v_mfma_f32_32x32x16_bf16 v[32:47], v[212:215], v[220:223], v[32:47]
	v_mfma_f32_32x32x16_bf16 v[16:31], v[212:215], v[224:227], v[16:31]
	v_mfma_f32_32x32x16_bf16 v[0:15], v[212:215], v[228:231], v[0:15]
	ds_read_b128 v[206:209], v234
	ds_read_b128 v[216:219], v238
	ds_read_b128 v[212:215], v234 offset:4096
	ds_read_b128 v[220:223], v238 offset:4096
	ds_read_b128 v[224:227], v238 offset:8192
	ds_read_b128 v[228:231], v238 offset:12288
	s_waitcnt lgkmcnt(6)
	v_mfma_f32_32x32x16_bf16 v[112:127], v[128:131], v[136:139], v[112:127]
	v_mfma_f32_32x32x16_bf16 v[96:111], v[128:131], v[140:143], v[96:111]
	v_mfma_f32_32x32x16_bf16 v[80:95], v[128:131], v[144:147], v[80:95]
	v_mfma_f32_32x32x16_bf16 v[64:79], v[128:131], v[148:151], v[64:79]
	v_mfma_f32_32x32x16_bf16 v[48:63], v[132:135], v[136:139], v[48:63]
	v_mfma_f32_32x32x16_bf16 v[32:47], v[132:135], v[140:143], v[32:47]
	v_mfma_f32_32x32x16_bf16 v[16:31], v[132:135], v[144:147], v[16:31]
	v_mfma_f32_32x32x16_bf16 v[0:15], v[132:135], v[148:151], v[0:15]
	ds_read_b128 v[128:131], v235
	ds_read_b128 v[136:139], v239
	ds_read_b128 v[132:135], v235 offset:4096
	ds_read_b128 v[140:143], v239 offset:4096
	ds_read_b128 v[144:147], v239 offset:8192
	ds_read_b128 v[148:151], v239 offset:12288
	s_waitcnt lgkmcnt(6)
	v_mfma_f32_32x32x16_bf16 v[112:127], v[206:209], v[216:219], v[112:127]
	v_mfma_f32_32x32x16_bf16 v[96:111], v[206:209], v[220:223], v[96:111]
	v_mfma_f32_32x32x16_bf16 v[80:95], v[206:209], v[224:227], v[80:95]
	v_mfma_f32_32x32x16_bf16 v[64:79], v[206:209], v[228:231], v[64:79]
	v_mfma_f32_32x32x16_bf16 v[48:63], v[212:215], v[216:219], v[48:63]
	v_mfma_f32_32x32x16_bf16 v[32:47], v[212:215], v[220:223], v[32:47]
	v_mfma_f32_32x32x16_bf16 v[16:31], v[212:215], v[224:227], v[16:31]
	v_mfma_f32_32x32x16_bf16 v[0:15], v[212:215], v[228:231], v[0:15]
	s_waitcnt vmcnt(0) lgkmcnt(0)
	s_barrier
	ds_read_b128 v[206:209], v205
	ds_read_b128 v[216:219], v243
	ds_read_b128 v[212:215], v205 offset:4096
	ds_read_b128 v[220:223], v243 offset:4096
	ds_read_b128 v[224:227], v243 offset:8192
	ds_read_b128 v[228:231], v243 offset:12288
	v_mfma_f32_32x32x16_bf16 v[112:127], v[128:131], v[136:139], v[112:127]
	v_mfma_f32_32x32x16_bf16 v[96:111], v[128:131], v[140:143], v[96:111]
	v_mfma_f32_32x32x16_bf16 v[80:95], v[128:131], v[144:147], v[80:95]
	v_mfma_f32_32x32x16_bf16 v[64:79], v[128:131], v[148:151], v[64:79]
	v_mfma_f32_32x32x16_bf16 v[48:63], v[132:135], v[136:139], v[48:63]
	v_mfma_f32_32x32x16_bf16 v[32:47], v[132:135], v[140:143], v[32:47]
	v_mfma_f32_32x32x16_bf16 v[16:31], v[132:135], v[144:147], v[16:31]
	v_mfma_f32_32x32x16_bf16 v[0:15], v[132:135], v[148:151], v[0:15]
	s_xor_b32 s89, s89, 0x10000
	s_add_i32 s6, s6, 1
	s_add_u32 s2, s2, 0x80
	s_addc_u32 s3, s3, 0
	s_add_i32 s68, s4, s42
	s_cmpk_gt_i32 s68, 0x2ff
	s_cselect_b64 s[28:29], -1, 0
	s_and_b64 vcc, exec, s[28:29]
	s_cbranch_vccnz .LBB0_307
	s_mul_hi_i32 s2, s68, 0x2aaaaaab
	s_lshr_b32 s3, s2, 31
	s_add_i32 s2, s2, s3
	s_mul_i32 s3, s2, -6
	s_lshl_b32 s2, s2, 8
	v_add_u32_e32 v129, s2, v190
	s_add_i32 s3, s3, s68
	v_min_i32_e32 v132, 0x7fff, v129
	v_add_u32_e32 v129, s2, v163
	s_lshl_b32 s3, s3, 8
	v_add_u32_e32 v128, s2, v189
	v_min_i32_e32 v136, 0x7fff, v129
	v_add_u32_e32 v129, s2, v192
	v_min_i32_e32 v128, 0x7fff, v128
	v_add_u32_e32 v130, s3, v189
	v_add_u32_e32 v134, s3, v190
	v_add_u32_e32 v138, s3, v163
	v_min_i32_e32 v140, 0x7fff, v129
	v_add_u32_e32 v142, s3, v192
	v_ashrrev_i32_e32 v143, 31, v142
	v_ashrrev_i32_e32 v141, 31, v140
	v_ashrrev_i32_e32 v139, 31, v138
	v_ashrrev_i32_e32 v137, 31, v136
	v_ashrrev_i32_e32 v135, 31, v134
	v_ashrrev_i32_e32 v133, 31, v132
	v_ashrrev_i32_e32 v131, 31, v130
	v_ashrrev_i32_e32 v129, 31, v128
	v_lshlrev_b64 v[142:143], 11, v[142:143]
	v_lshlrev_b64 v[140:141], 11, v[140:141]
	v_lshlrev_b64 v[138:139], 11, v[138:139]
	v_lshlrev_b64 v[136:137], 11, v[136:137]
	v_lshlrev_b64 v[134:135], 11, v[134:135]
	v_lshlrev_b64 v[132:133], 11, v[132:133]
	v_lshlrev_b64 v[130:131], 11, v[130:131]
	v_lshlrev_b64 v[128:129], 11, v[128:129]
	v_lshl_add_u64 v[156:157], v[164:165], 0, v[142:143]
	v_lshl_add_u64 v[152:153], v[166:167], 0, v[140:141]
	v_lshl_add_u64 v[148:149], v[164:165], 0, v[138:139]
	v_lshl_add_u64 v[144:145], v[166:167], 0, v[136:137]
	v_lshl_add_u64 v[140:141], v[164:165], 0, v[134:135]
	v_lshl_add_u64 v[136:137], v[166:167], 0, v[132:133]
	v_lshl_add_u64 v[132:133], v[164:165], 0, v[130:131]
	v_lshl_add_u64 v[128:129], v[166:167], 0, v[128:129]
	s_add_u32 m0, s88, 0
	v_lshl_add_u64 v[128:129], v[128:129], 0, s[92:93]
	v_xor_b32_e32 v128, v159, v128
	global_load_lds_dwordx4 v[128:129], off
	s_add_u32 m0, s88, 32768
	v_lshl_add_u64 v[132:133], v[132:133], 0, s[92:93]
	v_xor_b32_e32 v132, v159, v132
	global_load_lds_dwordx4 v[132:133], off
	s_add_u32 m0, s88, 8192
	v_lshl_add_u64 v[136:137], v[136:137], 0, s[92:93]
	v_xor_b32_e32 v136, v159, v136
	global_load_lds_dwordx4 v[136:137], off
	s_add_u32 m0, s88, 40960
	v_lshl_add_u64 v[140:141], v[140:141], 0, s[92:93]
	v_xor_b32_e32 v140, v159, v140
	global_load_lds_dwordx4 v[140:141], off
	s_add_u32 m0, s88, 16384
	v_lshl_add_u64 v[144:145], v[144:145], 0, s[92:93]
	v_xor_b32_e32 v144, v159, v144
	global_load_lds_dwordx4 v[144:145], off
	s_add_u32 m0, s88, 49152
	v_lshl_add_u64 v[148:149], v[148:149], 0, s[92:93]
	v_xor_b32_e32 v148, v159, v148
	global_load_lds_dwordx4 v[148:149], off
	s_add_u32 m0, s88, 24576
	v_lshl_add_u64 v[152:153], v[152:153], 0, s[92:93]
	v_xor_b32_e32 v152, v159, v152
	global_load_lds_dwordx4 v[152:153], off
	s_add_u32 m0, s88, 57344
	v_lshl_add_u64 v[156:157], v[156:157], 0, s[92:93]
	v_xor_b32_e32 v156, v159, v156
	global_load_lds_dwordx4 v[156:157], off
.LBB0_307:
	ds_read_b128 v[128:131], v240
	ds_read_b128 v[136:139], v253
	ds_read_b128 v[132:135], v240 offset:4096
	ds_read_b128 v[140:143], v253 offset:4096
	ds_read_b128 v[144:147], v253 offset:8192
	ds_read_b128 v[148:151], v253 offset:12288
	s_waitcnt lgkmcnt(6)
	v_mfma_f32_32x32x16_bf16 v[112:127], v[206:209], v[216:219], v[112:127]
	v_mfma_f32_32x32x16_bf16 v[96:111], v[206:209], v[220:223], v[96:111]
	v_mfma_f32_32x32x16_bf16 v[80:95], v[206:209], v[224:227], v[80:95]
	v_mfma_f32_32x32x16_bf16 v[64:79], v[206:209], v[228:231], v[64:79]
	v_mfma_f32_32x32x16_bf16 v[48:63], v[212:215], v[216:219], v[48:63]
	v_mfma_f32_32x32x16_bf16 v[32:47], v[212:215], v[220:223], v[32:47]
	v_mfma_f32_32x32x16_bf16 v[16:31], v[212:215], v[224:227], v[16:31]
	v_mfma_f32_32x32x16_bf16 v[0:15], v[212:215], v[228:231], v[0:15]
	ds_read_b128 v[206:209], v241
	ds_read_b128 v[216:219], v254
	ds_read_b128 v[212:215], v241 offset:4096
	ds_read_b128 v[220:223], v254 offset:4096
	ds_read_b128 v[224:227], v254 offset:8192
	ds_read_b128 v[228:231], v254 offset:12288
	s_waitcnt lgkmcnt(6)
	v_mfma_f32_32x32x16_bf16 v[112:127], v[128:131], v[136:139], v[112:127]
	v_mfma_f32_32x32x16_bf16 v[96:111], v[128:131], v[140:143], v[96:111]
	v_mfma_f32_32x32x16_bf16 v[80:95], v[128:131], v[144:147], v[80:95]
	v_mfma_f32_32x32x16_bf16 v[64:79], v[128:131], v[148:151], v[64:79]
	v_mfma_f32_32x32x16_bf16 v[48:63], v[132:135], v[136:139], v[48:63]
	v_mfma_f32_32x32x16_bf16 v[32:47], v[132:135], v[140:143], v[32:47]
	v_mfma_f32_32x32x16_bf16 v[16:31], v[132:135], v[144:147], v[16:31]
	v_mfma_f32_32x32x16_bf16 v[0:15], v[132:135], v[148:151], v[0:15]
	ds_read_b128 v[128:131], v242
	ds_read_b128 v[136:139], v255
	ds_read_b128 v[132:135], v242 offset:4096
	ds_read_b128 v[140:143], v255 offset:4096
	ds_read_b128 v[144:147], v255 offset:8192
	ds_read_b128 v[148:151], v255 offset:12288
	s_waitcnt lgkmcnt(6)
	v_mfma_f32_32x32x16_bf16 v[112:127], v[206:209], v[216:219], v[112:127]
	v_mfma_f32_32x32x16_bf16 v[96:111], v[206:209], v[220:223], v[96:111]
	v_mfma_f32_32x32x16_bf16 v[80:95], v[206:209], v[224:227], v[80:95]
	v_mfma_f32_32x32x16_bf16 v[64:79], v[206:209], v[228:231], v[64:79]
	v_mfma_f32_32x32x16_bf16 v[48:63], v[212:215], v[216:219], v[48:63]
	v_mfma_f32_32x32x16_bf16 v[32:47], v[212:215], v[220:223], v[32:47]
	v_mfma_f32_32x32x16_bf16 v[16:31], v[212:215], v[224:227], v[16:31]
	v_mfma_f32_32x32x16_bf16 v[0:15], v[212:215], v[228:231], v[0:15]
	s_waitcnt vmcnt(0) lgkmcnt(0)
	s_barrier
	v_mfma_f32_32x32x16_bf16 v[112:127], v[128:131], v[136:139], v[112:127]
	v_mfma_f32_32x32x16_bf16 v[96:111], v[128:131], v[140:143], v[96:111]
	v_mfma_f32_32x32x16_bf16 v[80:95], v[128:131], v[144:147], v[80:95]
	v_mfma_f32_32x32x16_bf16 v[64:79], v[128:131], v[148:151], v[64:79]
	v_mfma_f32_32x32x16_bf16 v[48:63], v[132:135], v[136:139], v[48:63]
	v_mfma_f32_32x32x16_bf16 v[32:47], v[132:135], v[140:143], v[32:47]
	v_mfma_f32_32x32x16_bf16 v[16:31], v[132:135], v[144:147], v[16:31]
	v_mfma_f32_32x32x16_bf16 v[0:15], v[132:135], v[148:151], v[0:15]
	v_mbcnt_hi_u32_b32 v228, -1, v210
	v_and_b32_e32 v229, 31, v228
	v_lshrrev_b32_e32 v230, 5, v228
	v_lshlrev_b32_e32 v160, 3, v229
	v_lshlrev_b32_e32 v225, 2, v230
	s_lshr_b32 s90, s70, 6
	s_mul_i32 s91, s90, 0x1200
	s_add_u32 s91, s91, 0x12000
	v_mul_u32_u24_e32 v231, 0x240, v230
	v_lshl_add_u32 v231, v229, 1, v231
	v_add_u32_e32 v205, s91, v231
	v_lshrrev_b32_e32 v226, 3, v228
	v_and_b32_e32 v232, 7, v228
	v_lshlrev_b32_e32 v227, 4, v232
	v_mul_u32_u24_e32 v231, 0x90, v226
	v_add3_u32 v224, v231, v227, s91
	s_mul_i32 s92, s5, 6
	s_sub_u32 s93, s4, s92
	s_lshl_b32 s93, s93, 8
	s_lshl_b32 s92, s5, 8
	s_lshr_b32 s94, s90, 1
	s_lshl_b32 s94, s94, 6
	s_add_u32 s92, s92, s94
	s_and_b32 s94, s90, 1
	s_lshl_b32 s94, s94, 7
	s_add_u32 s93, s93, s94

.Lmq3q_tile:
	s_mul_hi_u32 s35, s30, 0xaaaaaaab
	s_lshr_b32 s35, s35, 2
	s_mul_i32 s36, s35, 6
	s_sub_u32 s36, s30, s36
	s_lshl_b32 s92, s35, 8
	s_add_u32 s92, s92, s31
	s_lshl_b32 s93, s36, 8
	s_add_u32 s93, s93, s34
	s_lshl_b32 s96, s92, 2
	v_lshl_add_u32 v212, v203, 2, s96
	s_waitcnt vmcnt(0)
	s_barrier
	s_add_u32 s20, s16, 128
	s_addc_u32 s21, s17, 0
	s_add_u32 s24, s18, 128
	s_addc_u32 s25, s19, 0
	s_add_u32 m0, s88, 65536
	s_nop 0
	global_load_lds_dwordx4 v192, s[20:21]
	s_add_u32 m0, s88, 98304
	s_nop 0
	global_load_lds_dwordx4 v192, s[24:25]
	s_add_u32 m0, s88, 73728
	s_nop 0
	global_load_lds_dwordx4 v194, s[20:21]
	s_add_u32 m0, s88, 106496
	s_nop 0
	global_load_lds_dwordx4 v194, s[24:25]
	s_add_u32 m0, s88, 81920
	s_nop 0
	global_load_lds_dwordx4 v196, s[20:21]
	s_add_u32 m0, s88, 114688
	s_nop 0
	global_load_lds_dwordx4 v196, s[24:25]
	s_add_u32 m0, s88, 90112
	s_nop 0
	global_load_lds_dwordx4 v198, s[20:21]
	s_add_u32 m0, s88, 122880
	s_nop 0
	global_load_lds_dwordx4 v198, s[24:25]
	global_load_dword v213, v212, s[8:9] offset:0
	global_load_dword v214, v212, s[8:9] offset:4
	global_load_dword v215, v212, s[8:9] offset:8
	global_load_dword v216, v212, s[8:9] offset:12
	global_load_dword v217, v212, s[8:9] offset:32
	global_load_dword v218, v212, s[8:9] offset:36
	global_load_dword v219, v212, s[8:9] offset:40
	global_load_dword v220, v212, s[8:9] offset:44
	global_load_dword v221, v212, s[8:9] offset:64
	global_load_dword v222, v212, s[8:9] offset:68
	global_load_dword v223, v212, s[8:9] offset:72
	global_load_dword v224, v212, s[8:9] offset:76
	global_load_dword v225, v212, s[8:9] offset:96
	global_load_dword v226, v212, s[8:9] offset:100
	global_load_dword v227, v212, s[8:9] offset:104
	global_load_dword v228, v212, s[8:9] offset:108
	global_load_dword v229, v212, s[8:9] offset:128
	global_load_dword v230, v212, s[8:9] offset:132
	global_load_dword v231, v212, s[8:9] offset:136
	global_load_dword v232, v212, s[8:9] offset:140
	global_load_dword v233, v212, s[8:9] offset:160
	global_load_dword v234, v212, s[8:9] offset:164
	global_load_dword v235, v212, s[8:9] offset:168
	global_load_dword v236, v212, s[8:9] offset:172
	global_load_dword v237, v212, s[8:9] offset:192
	global_load_dword v238, v212, s[8:9] offset:196
	global_load_dword v239, v212, s[8:9] offset:200
	global_load_dword v240, v212, s[8:9] offset:204
	global_load_dword v241, v212, s[8:9] offset:224
	global_load_dword v242, v212, s[8:9] offset:228
	global_load_dword v243, v212, s[8:9] offset:232
	global_load_dword v244, v212, s[8:9] offset:236
	ds_read_b128 v[160:163], v184
	ds_read_b128 v[168:171], v188
	ds_read_b128 v[164:167], v184 offset:4096
	ds_read_b128 v[172:175], v188 offset:4096
	ds_read_b128 v[176:179], v188 offset:8192
	ds_read_b128 v[180:183], v188 offset:12288
	ds_read_b128 v[128:131], v185
	ds_read_b128 v[136:139], v189
	ds_read_b128 v[132:135], v185 offset:4096
	ds_read_b128 v[140:143], v189 offset:4096
	ds_read_b128 v[144:147], v189 offset:8192
	ds_read_b128 v[148:151], v189 offset:12288
	s_waitcnt lgkmcnt(6)
	v_mfma_f32_32x32x16_bf16 v[112:127], v[160:163], v[168:171], 0
	v_mfma_f32_32x32x16_bf16 v[96:111], v[160:163], v[172:175], 0
	v_mfma_f32_32x32x16_bf16 v[80:95], v[160:163], v[176:179], 0
	v_mfma_f32_32x32x16_bf16 v[64:79], v[160:163], v[180:183], 0
	v_mfma_f32_32x32x16_bf16 v[48:63], v[164:167], v[168:171], 0
	v_mfma_f32_32x32x16_bf16 v[32:47], v[164:167], v[172:175], 0
	v_mfma_f32_32x32x16_bf16 v[16:31], v[164:167], v[176:179], 0
	v_mfma_f32_32x32x16_bf16 v[0:15], v[164:167], v[180:183], 0
	ds_read_b128 v[160:163], v186
	ds_read_b128 v[168:171], v190
	ds_read_b128 v[164:167], v186 offset:4096
	ds_read_b128 v[172:175], v190 offset:4096
	ds_read_b128 v[176:179], v190 offset:8192
	ds_read_b128 v[180:183], v190 offset:12288
	s_waitcnt lgkmcnt(6)
	v_mfma_f32_32x32x16_bf16 v[112:127], v[128:131], v[136:139], v[112:127]
	v_mfma_f32_32x32x16_bf16 v[96:111], v[128:131], v[140:143], v[96:111]
	v_mfma_f32_32x32x16_bf16 v[80:95], v[128:131], v[144:147], v[80:95]
	v_mfma_f32_32x32x16_bf16 v[64:79], v[128:131], v[148:151], v[64:79]
	v_mfma_f32_32x32x16_bf16 v[48:63], v[132:135], v[136:139], v[48:63]
	v_mfma_f32_32x32x16_bf16 v[32:47], v[132:135], v[140:143], v[32:47]
	v_mfma_f32_32x32x16_bf16 v[16:31], v[132:135], v[144:147], v[16:31]
	v_mfma_f32_32x32x16_bf16 v[0:15], v[132:135], v[148:151], v[0:15]
	ds_read_b128 v[128:131], v187
	ds_read_b128 v[136:139], v191
	ds_read_b128 v[132:135], v187 offset:4096
	ds_read_b128 v[140:143], v191 offset:4096
	ds_read_b128 v[144:147], v191 offset:8192
	ds_read_b128 v[148:151], v191 offset:12288
	s_waitcnt lgkmcnt(6)
	v_mfma_f32_32x32x16_bf16 v[112:127], v[160:163], v[168:171], v[112:127]
	v_mfma_f32_32x32x16_bf16 v[96:111], v[160:163], v[172:175], v[96:111]
	v_mfma_f32_32x32x16_bf16 v[80:95], v[160:163], v[176:179], v[80:95]
	v_mfma_f32_32x32x16_bf16 v[64:79], v[160:163], v[180:183], v[64:79]
	v_mfma_f32_32x32x16_bf16 v[48:63], v[164:167], v[168:171], v[48:63]
	v_mfma_f32_32x32x16_bf16 v[32:47], v[164:167], v[172:175], v[32:47]
	v_mfma_f32_32x32x16_bf16 v[16:31], v[164:167], v[176:179], v[16:31]
	v_mfma_f32_32x32x16_bf16 v[0:15], v[164:167], v[180:183], v[0:15]
	s_waitcnt vmcnt(0) lgkmcnt(0)
	s_barrier
	ds_read_b128 v[160:163], v246
	ds_read_b128 v[168:171], v250
	ds_read_b128 v[164:167], v246 offset:4096
	ds_read_b128 v[172:175], v250 offset:4096
	ds_read_b128 v[176:179], v250 offset:8192
	ds_read_b128 v[180:183], v250 offset:12288
	s_add_u32 s20, s16, 256
	s_addc_u32 s21, s17, 0
	s_add_u32 s24, s18, 256
	s_addc_u32 s25, s19, 0
	s_add_u32 m0, s88, 0
	v_mfma_f32_32x32x16_bf16 v[112:127], v[128:131], v[136:139], v[112:127]
	global_load_lds_dwordx4 v192, s[20:21]
	s_add_u32 m0, s88, 32768
	v_mfma_f32_32x32x16_bf16 v[96:111], v[128:131], v[140:143], v[96:111]
	global_load_lds_dwordx4 v192, s[24:25]
	s_add_u32 m0, s88, 8192
	v_mfma_f32_32x32x16_bf16 v[80:95], v[128:131], v[144:147], v[80:95]
	global_load_lds_dwordx4 v194, s[20:21]
	s_add_u32 m0, s88, 40960
	v_mfma_f32_32x32x16_bf16 v[64:79], v[128:131], v[148:151], v[64:79]
	global_load_lds_dwordx4 v194, s[24:25]
	s_add_u32 m0, s88, 16384
	v_mfma_f32_32x32x16_bf16 v[48:63], v[132:135], v[136:139], v[48:63]
	global_load_lds_dwordx4 v196, s[20:21]
	s_add_u32 m0, s88, 49152
	v_mfma_f32_32x32x16_bf16 v[32:47], v[132:135], v[140:143], v[32:47]
	global_load_lds_dwordx4 v196, s[24:25]
	s_add_u32 m0, s88, 24576
	v_mfma_f32_32x32x16_bf16 v[16:31], v[132:135], v[144:147], v[16:31]
	global_load_lds_dwordx4 v198, s[20:21]
	s_add_u32 m0, s88, 57344
	v_mfma_f32_32x32x16_bf16 v[0:15], v[132:135], v[148:151], v[0:15]
	global_load_lds_dwordx4 v198, s[24:25]
	ds_read_b128 v[128:131], v247
	ds_read_b128 v[136:139], v251
	ds_read_b128 v[132:135], v247 offset:4096
	ds_read_b128 v[140:143], v251 offset:4096
	ds_read_b128 v[144:147], v251 offset:8192
	ds_read_b128 v[148:151], v251 offset:12288
	s_waitcnt lgkmcnt(6)
	v_mfma_f32_32x32x16_bf16 v[112:127], v[160:163], v[168:171], v[112:127]
	v_mfma_f32_32x32x16_bf16 v[96:111], v[160:163], v[172:175], v[96:111]
	v_mfma_f32_32x32x16_bf16 v[80:95], v[160:163], v[176:179], v[80:95]
	v_mfma_f32_32x32x16_bf16 v[64:79], v[160:163], v[180:183], v[64:79]
	v_mfma_f32_32x32x16_bf16 v[48:63], v[164:167], v[168:171], v[48:63]
	v_mfma_f32_32x32x16_bf16 v[32:47], v[164:167], v[172:175], v[32:47]
	v_mfma_f32_32x32x16_bf16 v[16:31], v[164:167], v[176:179], v[16:31]
	v_mfma_f32_32x32x16_bf16 v[0:15], v[164:167], v[180:183], v[0:15]
	ds_read_b128 v[160:163], v248
	ds_read_b128 v[168:171], v252
	ds_read_b128 v[164:167], v248 offset:4096
	ds_read_b128 v[172:175], v252 offset:4096
	ds_read_b128 v[176:179], v252 offset:8192
	ds_read_b128 v[180:183], v252 offset:12288
	s_waitcnt lgkmcnt(6)
	v_mfma_f32_32x32x16_bf16 v[112:127], v[128:131], v[136:139], v[112:127]
	v_mfma_f32_32x32x16_bf16 v[96:111], v[128:131], v[140:143], v[96:111]
	v_mfma_f32_32x32x16_bf16 v[80:95], v[128:131], v[144:147], v[80:95]
	v_mfma_f32_32x32x16_bf16 v[64:79], v[128:131], v[148:151], v[64:79]
	v_mfma_f32_32x32x16_bf16 v[48:63], v[132:135], v[136:139], v[48:63]
	v_mfma_f32_32x32x16_bf16 v[32:47], v[132:135], v[140:143], v[32:47]
	v_mfma_f32_32x32x16_bf16 v[16:31], v[132:135], v[144:147], v[16:31]
	v_mfma_f32_32x32x16_bf16 v[0:15], v[132:135], v[148:151], v[0:15]
	ds_read_b128 v[128:131], v249
	ds_read_b128 v[136:139], v253
	ds_read_b128 v[132:135], v249 offset:4096
	ds_read_b128 v[140:143], v253 offset:4096
	ds_read_b128 v[144:147], v253 offset:8192
	ds_read_b128 v[148:151], v253 offset:12288
	s_waitcnt lgkmcnt(6)
	v_mfma_f32_32x32x16_bf16 v[112:127], v[160:163], v[168:171], v[112:127]
	v_mfma_f32_32x32x16_bf16 v[96:111], v[160:163], v[172:175], v[96:111]
	v_mfma_f32_32x32x16_bf16 v[80:95], v[160:163], v[176:179], v[80:95]
	v_mfma_f32_32x32x16_bf16 v[64:79], v[160:163], v[180:183], v[64:79]
	v_mfma_f32_32x32x16_bf16 v[48:63], v[164:167], v[168:171], v[48:63]
	v_mfma_f32_32x32x16_bf16 v[32:47], v[164:167], v[172:175], v[32:47]
	v_mfma_f32_32x32x16_bf16 v[16:31], v[164:167], v[176:179], v[16:31]
	v_mfma_f32_32x32x16_bf16 v[0:15], v[164:167], v[180:183], v[0:15]
	s_waitcnt vmcnt(0) lgkmcnt(0)
	s_barrier
	ds_read_b128 v[160:163], v184
	ds_read_b128 v[168:171], v188
	ds_read_b128 v[164:167], v184 offset:4096
	ds_read_b128 v[172:175], v188 offset:4096
	ds_read_b128 v[176:179], v188 offset:8192
	ds_read_b128 v[180:183], v188 offset:12288
	s_add_u32 s20, s16, 384
	s_addc_u32 s21, s17, 0
	s_add_u32 s24, s18, 384
	s_addc_u32 s25, s19, 0
	s_add_u32 m0, s88, 65536
	v_mfma_f32_32x32x16_bf16 v[112:127], v[128:131], v[136:139], v[112:127]
	global_load_lds_dwordx4 v192, s[20:21]
	s_add_u32 m0, s88, 98304
	v_mfma_f32_32x32x16_bf16 v[96:111], v[128:131], v[140:143], v[96:111]
	global_load_lds_dwordx4 v192, s[24:25]
	s_add_u32 m0, s88, 73728
	v_mfma_f32_32x32x16_bf16 v[80:95], v[128:131], v[144:147], v[80:95]
	global_load_lds_dwordx4 v194, s[20:21]
	s_add_u32 m0, s88, 106496
	v_mfma_f32_32x32x16_bf16 v[64:79], v[128:131], v[148:151], v[64:79]
	global_load_lds_dwordx4 v194, s[24:25]
	s_add_u32 m0, s88, 81920
	v_mfma_f32_32x32x16_bf16 v[48:63], v[132:135], v[136:139], v[48:63]
	global_load_lds_dwordx4 v196, s[20:21]
	s_add_u32 m0, s88, 114688
	v_mfma_f32_32x32x16_bf16 v[32:47], v[132:135], v[140:143], v[32:47]
	global_load_lds_dwordx4 v196, s[24:25]
	s_add_u32 m0, s88, 90112
	v_mfma_f32_32x32x16_bf16 v[16:31], v[132:135], v[144:147], v[16:31]
	global_load_lds_dwordx4 v198, s[20:21]
	s_add_u32 m0, s88, 122880
	v_mfma_f32_32x32x16_bf16 v[0:15], v[132:135], v[148:151], v[0:15]
	global_load_lds_dwordx4 v198, s[24:25]
	ds_read_b128 v[128:131], v185
	ds_read_b128 v[136:139], v189
	ds_read_b128 v[132:135], v185 offset:4096
	ds_read_b128 v[140:143], v189 offset:4096
	ds_read_b128 v[144:147], v189 offset:8192
	ds_read_b128 v[148:151], v189 offset:12288
	s_waitcnt lgkmcnt(6)
	v_mfma_f32_32x32x16_bf16 v[112:127], v[160:163], v[168:171], v[112:127]
	v_mfma_f32_32x32x16_bf16 v[96:111], v[160:163], v[172:175], v[96:111]
	v_mfma_f32_32x32x16_bf16 v[80:95], v[160:163], v[176:179], v[80:95]
	v_mfma_f32_32x32x16_bf16 v[64:79], v[160:163], v[180:183], v[64:79]
	v_mfma_f32_32x32x16_bf16 v[48:63], v[164:167], v[168:171], v[48:63]
	v_mfma_f32_32x32x16_bf16 v[32:47], v[164:167], v[172:175], v[32:47]
	v_mfma_f32_32x32x16_bf16 v[16:31], v[164:167], v[176:179], v[16:31]
	v_mfma_f32_32x32x16_bf16 v[0:15], v[164:167], v[180:183], v[0:15]
	ds_read_b128 v[160:163], v186
	ds_read_b128 v[168:171], v190
	ds_read_b128 v[164:167], v186 offset:4096
	ds_read_b128 v[172:175], v190 offset:4096
	ds_read_b128 v[176:179], v190 offset:8192
	ds_read_b128 v[180:183], v190 offset:12288
	s_waitcnt lgkmcnt(6)
	v_mfma_f32_32x32x16_bf16 v[112:127], v[128:131], v[136:139], v[112:127]
	v_mfma_f32_32x32x16_bf16 v[96:111], v[128:131], v[140:143], v[96:111]
	v_mfma_f32_32x32x16_bf16 v[80:95], v[128:131], v[144:147], v[80:95]
	v_mfma_f32_32x32x16_bf16 v[64:79], v[128:131], v[148:151], v[64:79]
	v_mfma_f32_32x32x16_bf16 v[48:63], v[132:135], v[136:139], v[48:63]
	v_mfma_f32_32x32x16_bf16 v[32:47], v[132:135], v[140:143], v[32:47]
	v_mfma_f32_32x32x16_bf16 v[16:31], v[132:135], v[144:147], v[16:31]
	v_mfma_f32_32x32x16_bf16 v[0:15], v[132:135], v[148:151], v[0:15]
	ds_read_b128 v[128:131], v187
	ds_read_b128 v[136:139], v191
	ds_read_b128 v[132:135], v187 offset:4096
	ds_read_b128 v[140:143], v191 offset:4096
	ds_read_b128 v[144:147], v191 offset:8192
	ds_read_b128 v[148:151], v191 offset:12288
	s_waitcnt lgkmcnt(6)
	v_mfma_f32_32x32x16_bf16 v[112:127], v[160:163], v[168:171], v[112:127]
	v_mfma_f32_32x32x16_bf16 v[96:111], v[160:163], v[172:175], v[96:111]
	v_mfma_f32_32x32x16_bf16 v[80:95], v[160:163], v[176:179], v[80:95]
	v_mfma_f32_32x32x16_bf16 v[64:79], v[160:163], v[180:183], v[64:79]
	v_mfma_f32_32x32x16_bf16 v[48:63], v[164:167], v[168:171], v[48:63]
	v_mfma_f32_32x32x16_bf16 v[32:47], v[164:167], v[172:175], v[32:47]
	v_mfma_f32_32x32x16_bf16 v[16:31], v[164:167], v[176:179], v[16:31]
	v_mfma_f32_32x32x16_bf16 v[0:15], v[164:167], v[180:183], v[0:15]
	s_waitcnt vmcnt(0) lgkmcnt(0)
	s_barrier
	ds_read_b128 v[160:163], v246
	ds_read_b128 v[168:171], v250
	ds_read_b128 v[164:167], v246 offset:4096
	ds_read_b128 v[172:175], v250 offset:4096
	ds_read_b128 v[176:179], v250 offset:8192
	ds_read_b128 v[180:183], v250 offset:12288
	s_add_u32 s37, s30, s42
	s_cmp_ge_u32 s37, 768
	s_cbranch_scc1 .Lmq3q_nonext2
	s_mul_hi_u32 s38, s37, 0xaaaaaaab
	s_lshr_b32 s38, s38, 2
	s_mul_i32 s39, s38, 6
	s_sub_u32 s39, s37, s39
	s_lshl_b32 s98, s38, 17
	s_add_u32 s16, s4, s98
	s_addc_u32 s17, s5, 0
	s_lshl_b32 s98, s39, 17
	s_add_u32 s18, s6, s98
	s_addc_u32 s19, s7, 0
	s_add_u32 m0, s88, 0
	v_mfma_f32_32x32x16_bf16 v[112:127], v[128:131], v[136:139], v[112:127]
	global_load_lds_dwordx4 v192, s[16:17]
	s_add_u32 m0, s88, 32768
	v_mfma_f32_32x32x16_bf16 v[96:111], v[128:131], v[140:143], v[96:111]
	global_load_lds_dwordx4 v192, s[18:19]
	s_add_u32 m0, s88, 8192
	v_mfma_f32_32x32x16_bf16 v[80:95], v[128:131], v[144:147], v[80:95]
	global_load_lds_dwordx4 v194, s[16:17]
	s_add_u32 m0, s88, 40960
	v_mfma_f32_32x32x16_bf16 v[64:79], v[128:131], v[148:151], v[64:79]
	global_load_lds_dwordx4 v194, s[18:19]
	s_add_u32 m0, s88, 16384
	v_mfma_f32_32x32x16_bf16 v[48:63], v[132:135], v[136:139], v[48:63]
	global_load_lds_dwordx4 v196, s[16:17]
	s_add_u32 m0, s88, 49152
	v_mfma_f32_32x32x16_bf16 v[32:47], v[132:135], v[140:143], v[32:47]
	global_load_lds_dwordx4 v196, s[18:19]
	s_add_u32 m0, s88, 24576
	v_mfma_f32_32x32x16_bf16 v[16:31], v[132:135], v[144:147], v[16:31]
	global_load_lds_dwordx4 v198, s[16:17]
	s_add_u32 m0, s88, 57344
	v_mfma_f32_32x32x16_bf16 v[0:15], v[132:135], v[148:151], v[0:15]
	global_load_lds_dwordx4 v198, s[18:19]
	s_branch .Lmq3q_join2
.Lmq3q_nonext2:
	v_mfma_f32_32x32x16_bf16 v[112:127], v[128:131], v[136:139], v[112:127]
	v_mfma_f32_32x32x16_bf16 v[96:111], v[128:131], v[140:143], v[96:111]
	v_mfma_f32_32x32x16_bf16 v[80:95], v[128:131], v[144:147], v[80:95]
	v_mfma_f32_32x32x16_bf16 v[64:79], v[128:131], v[148:151], v[64:79]
	v_mfma_f32_32x32x16_bf16 v[48:63], v[132:135], v[136:139], v[48:63]
	v_mfma_f32_32x32x16_bf16 v[32:47], v[132:135], v[140:143], v[32:47]
	v_mfma_f32_32x32x16_bf16 v[16:31], v[132:135], v[144:147], v[16:31]
	v_mfma_f32_32x32x16_bf16 v[0:15], v[132:135], v[148:151], v[0:15]
.Lmq3q_join2:
	ds_read_b128 v[128:131], v247
	ds_read_b128 v[136:139], v251
	ds_read_b128 v[132:135], v247 offset:4096
	ds_read_b128 v[140:143], v251 offset:4096
	ds_read_b128 v[144:147], v251 offset:8192
	ds_read_b128 v[148:151], v251 offset:12288
	s_waitcnt lgkmcnt(6)
	v_mfma_f32_32x32x16_bf16 v[112:127], v[160:163], v[168:171], v[112:127]
	v_mfma_f32_32x32x16_bf16 v[96:111], v[160:163], v[172:175], v[96:111]
	v_mfma_f32_32x32x16_bf16 v[80:95], v[160:163], v[176:179], v[80:95]
	v_mfma_f32_32x32x16_bf16 v[64:79], v[160:163], v[180:183], v[64:79]
	v_mfma_f32_32x32x16_bf16 v[48:63], v[164:167], v[168:171], v[48:63]
	v_mfma_f32_32x32x16_bf16 v[32:47], v[164:167], v[172:175], v[32:47]
	v_mfma_f32_32x32x16_bf16 v[16:31], v[164:167], v[176:179], v[16:31]
	v_mfma_f32_32x32x16_bf16 v[0:15], v[164:167], v[180:183], v[0:15]
	ds_read_b128 v[160:163], v248
	ds_read_b128 v[168:171], v252
	ds_read_b128 v[164:167], v248 offset:4096
	ds_read_b128 v[172:175], v252 offset:4096
	ds_read_b128 v[176:179], v252 offset:8192
	ds_read_b128 v[180:183], v252 offset:12288
	s_waitcnt lgkmcnt(6)
	v_mfma_f32_32x32x16_bf16 v[112:127], v[128:131], v[136:139], v[112:127]
	v_mfma_f32_32x32x16_bf16 v[96:111], v[128:131], v[140:143], v[96:111]
	v_mfma_f32_32x32x16_bf16 v[80:95], v[128:131], v[144:147], v[80:95]
	v_mfma_f32_32x32x16_bf16 v[64:79], v[128:131], v[148:151], v[64:79]
	v_mfma_f32_32x32x16_bf16 v[48:63], v[132:135], v[136:139], v[48:63]
	v_mfma_f32_32x32x16_bf16 v[32:47], v[132:135], v[140:143], v[32:47]
	v_mfma_f32_32x32x16_bf16 v[16:31], v[132:135], v[144:147], v[16:31]
	v_mfma_f32_32x32x16_bf16 v[0:15], v[132:135], v[148:151], v[0:15]
	ds_read_b128 v[128:131], v249
	ds_read_b128 v[136:139], v253
	ds_read_b128 v[132:135], v249 offset:4096
	ds_read_b128 v[140:143], v253 offset:4096
	ds_read_b128 v[144:147], v253 offset:8192
	ds_read_b128 v[148:151], v253 offset:12288
	s_waitcnt lgkmcnt(6)
	v_mfma_f32_32x32x16_bf16 v[112:127], v[160:163], v[168:171], v[112:127]
	v_mfma_f32_32x32x16_bf16 v[96:111], v[160:163], v[172:175], v[96:111]
	v_mfma_f32_32x32x16_bf16 v[80:95], v[160:163], v[176:179], v[80:95]
	v_mfma_f32_32x32x16_bf16 v[64:79], v[160:163], v[180:183], v[64:79]
	v_mfma_f32_32x32x16_bf16 v[48:63], v[164:167], v[168:171], v[48:63]
	v_mfma_f32_32x32x16_bf16 v[32:47], v[164:167], v[172:175], v[32:47]
	v_mfma_f32_32x32x16_bf16 v[16:31], v[164:167], v[176:179], v[16:31]
	v_mfma_f32_32x32x16_bf16 v[0:15], v[164:167], v[180:183], v[0:15]
	s_waitcnt vmcnt(0) lgkmcnt(0)
	s_barrier
	v_mfma_f32_32x32x16_bf16 v[112:127], v[128:131], v[136:139], v[112:127]
	v_mul_f32_e32 v213, 0x3b800000, v213
	v_mul_f32_e32 v214, 0x3b800000, v214
	v_mul_f32_e32 v215, 0x3b800000, v215
	v_mul_f32_e32 v216, 0x3b800000, v216
	v_add_f32_e32 v213, 0x358637bd, v213
	v_add_f32_e32 v214, 0x358637bd, v214
	v_add_f32_e32 v215, 0x358637bd, v215
	v_add_f32_e32 v216, 0x358637bd, v216
	v_rsq_f32_e32 v213, v213
	v_rsq_f32_e32 v214, v214
	v_rsq_f32_e32 v215, v215
	v_rsq_f32_e32 v216, v216
	v_mul_f32_e32 v213, 0x3dd53b94, v213
	v_mul_f32_e32 v214, 0x3dd53b94, v214
	v_mul_f32_e32 v215, 0x3dd53b94, v215
	v_mul_f32_e32 v216, 0x3dd53b94, v216
	v_mfma_f32_32x32x16_bf16 v[96:111], v[128:131], v[140:143], v[96:111]
	v_mul_f32_e32 v217, 0x3b800000, v217
	v_mul_f32_e32 v218, 0x3b800000, v218
	v_mul_f32_e32 v219, 0x3b800000, v219
	v_mul_f32_e32 v220, 0x3b800000, v220
	v_add_f32_e32 v217, 0x358637bd, v217
	v_add_f32_e32 v218, 0x358637bd, v218
	v_add_f32_e32 v219, 0x358637bd, v219
	v_add_f32_e32 v220, 0x358637bd, v220
	v_rsq_f32_e32 v217, v217
	v_rsq_f32_e32 v218, v218
	v_rsq_f32_e32 v219, v219
	v_rsq_f32_e32 v220, v220
	v_mul_f32_e32 v217, 0x3dd53b94, v217
	v_mul_f32_e32 v218, 0x3dd53b94, v218
	v_mul_f32_e32 v219, 0x3dd53b94, v219
	v_mul_f32_e32 v220, 0x3dd53b94, v220
	v_mfma_f32_32x32x16_bf16 v[80:95], v[128:131], v[144:147], v[80:95]
	v_mul_f32_e32 v221, 0x3b800000, v221
	v_mul_f32_e32 v222, 0x3b800000, v222
	v_mul_f32_e32 v223, 0x3b800000, v223
	v_mul_f32_e32 v224, 0x3b800000, v224
	v_add_f32_e32 v221, 0x358637bd, v221
	v_add_f32_e32 v222, 0x358637bd, v222
	v_add_f32_e32 v223, 0x358637bd, v223
	v_add_f32_e32 v224, 0x358637bd, v224
	v_rsq_f32_e32 v221, v221
	v_rsq_f32_e32 v222, v222
	v_rsq_f32_e32 v223, v223
	v_rsq_f32_e32 v224, v224
	v_mul_f32_e32 v221, 0x3dd53b94, v221
	v_mul_f32_e32 v222, 0x3dd53b94, v222
	v_mul_f32_e32 v223, 0x3dd53b94, v223
	v_mul_f32_e32 v224, 0x3dd53b94, v224
	v_mfma_f32_32x32x16_bf16 v[64:79], v[128:131], v[148:151], v[64:79]
	v_mul_f32_e32 v225, 0x3b800000, v225
	v_mul_f32_e32 v226, 0x3b800000, v226
	v_mul_f32_e32 v227, 0x3b800000, v227
	v_mul_f32_e32 v228, 0x3b800000, v228
	v_add_f32_e32 v225, 0x358637bd, v225
	v_add_f32_e32 v226, 0x358637bd, v226
	v_add_f32_e32 v227, 0x358637bd, v227
	v_add_f32_e32 v228, 0x358637bd, v228
	v_rsq_f32_e32 v225, v225
	v_rsq_f32_e32 v226, v226
	v_rsq_f32_e32 v227, v227
	v_rsq_f32_e32 v228, v228
	v_mul_f32_e32 v225, 0x3dd53b94, v225
	v_mul_f32_e32 v226, 0x3dd53b94, v226
	v_mul_f32_e32 v227, 0x3dd53b94, v227
	v_mul_f32_e32 v228, 0x3dd53b94, v228
	v_mfma_f32_32x32x16_bf16 v[48:63], v[132:135], v[136:139], v[48:63]
	v_mul_f32_e32 v229, 0x3b800000, v229
	v_mul_f32_e32 v230, 0x3b800000, v230
	v_mul_f32_e32 v231, 0x3b800000, v231
	v_mul_f32_e32 v232, 0x3b800000, v232
	v_add_f32_e32 v229, 0x358637bd, v229
	v_add_f32_e32 v230, 0x358637bd, v230
	v_add_f32_e32 v231, 0x358637bd, v231
	v_add_f32_e32 v232, 0x358637bd, v232
	v_rsq_f32_e32 v229, v229
	v_rsq_f32_e32 v230, v230
	v_rsq_f32_e32 v231, v231
	v_rsq_f32_e32 v232, v232
	v_mul_f32_e32 v229, 0x3dd53b94, v229
	v_mul_f32_e32 v230, 0x3dd53b94, v230
	v_mul_f32_e32 v231, 0x3dd53b94, v231
	v_mul_f32_e32 v232, 0x3dd53b94, v232
	v_mfma_f32_32x32x16_bf16 v[32:47], v[132:135], v[140:143], v[32:47]
	v_mul_f32_e32 v233, 0x3b800000, v233
	v_mul_f32_e32 v234, 0x3b800000, v234
	v_mul_f32_e32 v235, 0x3b800000, v235
	v_mul_f32_e32 v236, 0x3b800000, v236
	v_add_f32_e32 v233, 0x358637bd, v233
	v_add_f32_e32 v234, 0x358637bd, v234
	v_add_f32_e32 v235, 0x358637bd, v235
	v_add_f32_e32 v236, 0x358637bd, v236
	v_rsq_f32_e32 v233, v233
	v_rsq_f32_e32 v234, v234
	v_rsq_f32_e32 v235, v235
	v_rsq_f32_e32 v236, v236
	v_mul_f32_e32 v233, 0x3dd53b94, v233
	v_mul_f32_e32 v234, 0x3dd53b94, v234
	v_mul_f32_e32 v235, 0x3dd53b94, v235
	v_mul_f32_e32 v236, 0x3dd53b94, v236
	v_mfma_f32_32x32x16_bf16 v[16:31], v[132:135], v[144:147], v[16:31]
	v_mul_f32_e32 v237, 0x3b800000, v237
	v_mul_f32_e32 v238, 0x3b800000, v238
	v_mul_f32_e32 v239, 0x3b800000, v239
	v_mul_f32_e32 v240, 0x3b800000, v240
	v_add_f32_e32 v237, 0x358637bd, v237
	v_add_f32_e32 v238, 0x358637bd, v238
	v_add_f32_e32 v239, 0x358637bd, v239
	v_add_f32_e32 v240, 0x358637bd, v240
	v_rsq_f32_e32 v237, v237
	v_rsq_f32_e32 v238, v238
	v_rsq_f32_e32 v239, v239
	v_rsq_f32_e32 v240, v240
	v_mul_f32_e32 v237, 0x3dd53b94, v237
	v_mul_f32_e32 v238, 0x3dd53b94, v238
	v_mul_f32_e32 v239, 0x3dd53b94, v239
	v_mul_f32_e32 v240, 0x3dd53b94, v240
	v_mfma_f32_32x32x16_bf16 v[0:15], v[132:135], v[148:151], v[0:15]
	v_mul_f32_e32 v241, 0x3b800000, v241
	v_mul_f32_e32 v242, 0x3b800000, v242
	v_mul_f32_e32 v243, 0x3b800000, v243
	v_mul_f32_e32 v244, 0x3b800000, v244
	v_add_f32_e32 v241, 0x358637bd, v241
	v_add_f32_e32 v242, 0x358637bd, v242
	v_add_f32_e32 v243, 0x358637bd, v243
	v_add_f32_e32 v244, 0x358637bd, v244
	v_rsq_f32_e32 v241, v241
	v_rsq_f32_e32 v242, v242
	v_rsq_f32_e32 v243, v243
	v_rsq_f32_e32 v244, v244
	v_mul_f32_e32 v241, 0x3dd53b94, v241
	v_mul_f32_e32 v242, 0x3dd53b94, v242
	v_mul_f32_e32 v243, 0x3dd53b94, v243
	v_mul_f32_e32 v244, 0x3dd53b94, v244
	s_nop 7
	s_add_u32 s94, s92, 0
	s_add_u32 s95, s93, 0
	s_lshr_b32 s90, s95, 6
	s_lshr_b32 s96, s94, 12
	s_and_b32 s97, s94, 0xfff
	s_mul_i32 s91, s90, 11
	s_lshr_b32 s91, s91, 5
	s_mul_i32 s98, s91, 3
	s_sub_u32 s98, s90, s98
	s_mul_i32 s89, s96, 0xc00000
	s_mul_i32 s91, s91, 0x180000
	s_add_u32 s89, s89, s91
	s_lshl_b32 s91, s98, 7
	s_add_u32 s89, s89, s91
	s_mul_i32 s91, s97, 0x180
	s_add_u32 s89, s89, s91
	s_movk_i32 s99, 0x180
	s_mov_b64 s[2:3], s[12:13]
	s_cmp_eq_u32 s98, 2
	s_cbranch_scc1 .Lmq3q_e00_rope

.Lmq3k_tile:
	s_lshr_b32 s35, s30, 3
	s_mul_i32 s36, s35, 8
	s_sub_u32 s36, s30, s36
	s_lshl_b32 s92, s35, 8
	s_add_u32 s92, s92, s31
	s_lshl_b32 s93, s36, 8
	s_add_u32 s93, s93, s34
	s_lshl_b32 s96, s92, 2
	v_lshl_add_u32 v212, v203, 2, s96
	s_waitcnt vmcnt(0)
	s_barrier
	s_add_u32 s20, s16, 128
	s_addc_u32 s21, s17, 0
	s_add_u32 s24, s18, 128
	s_addc_u32 s25, s19, 0
	s_add_u32 m0, s88, 65536
	s_nop 0
	global_load_lds_dwordx4 v192, s[20:21]
	s_add_u32 m0, s88, 98304
	s_nop 0
	global_load_lds_dwordx4 v192, s[24:25]
	s_add_u32 m0, s88, 73728
	s_nop 0
	global_load_lds_dwordx4 v194, s[20:21]
	s_add_u32 m0, s88, 106496
	s_nop 0
	global_load_lds_dwordx4 v194, s[24:25]
	s_add_u32 m0, s88, 81920
	s_nop 0
	global_load_lds_dwordx4 v196, s[20:21]
	s_add_u32 m0, s88, 114688
	s_nop 0
	global_load_lds_dwordx4 v196, s[24:25]
	s_add_u32 m0, s88, 90112
	s_nop 0
	global_load_lds_dwordx4 v198, s[20:21]
	s_add_u32 m0, s88, 122880
	s_nop 0
	global_load_lds_dwordx4 v198, s[24:25]
	global_load_dword v213, v212, s[8:9] offset:0
	global_load_dword v214, v212, s[8:9] offset:4
	global_load_dword v215, v212, s[8:9] offset:8
	global_load_dword v216, v212, s[8:9] offset:12
	global_load_dword v217, v212, s[8:9] offset:32
	global_load_dword v218, v212, s[8:9] offset:36
	global_load_dword v219, v212, s[8:9] offset:40
	global_load_dword v220, v212, s[8:9] offset:44
	global_load_dword v221, v212, s[8:9] offset:64
	global_load_dword v222, v212, s[8:9] offset:68
	global_load_dword v223, v212, s[8:9] offset:72
	global_load_dword v224, v212, s[8:9] offset:76
	global_load_dword v225, v212, s[8:9] offset:96
	global_load_dword v226, v212, s[8:9] offset:100
	global_load_dword v227, v212, s[8:9] offset:104
	global_load_dword v228, v212, s[8:9] offset:108
	global_load_dword v229, v212, s[8:9] offset:128
	global_load_dword v230, v212, s[8:9] offset:132
	global_load_dword v231, v212, s[8:9] offset:136
	global_load_dword v232, v212, s[8:9] offset:140
	global_load_dword v233, v212, s[8:9] offset:160
	global_load_dword v234, v212, s[8:9] offset:164
	global_load_dword v235, v212, s[8:9] offset:168
	global_load_dword v236, v212, s[8:9] offset:172
	global_load_dword v237, v212, s[8:9] offset:192
	global_load_dword v238, v212, s[8:9] offset:196
	global_load_dword v239, v212, s[8:9] offset:200
	global_load_dword v240, v212, s[8:9] offset:204
	global_load_dword v241, v212, s[8:9] offset:224
	global_load_dword v242, v212, s[8:9] offset:228
	global_load_dword v243, v212, s[8:9] offset:232
	global_load_dword v244, v212, s[8:9] offset:236
	ds_read_b128 v[160:163], v184
	ds_read_b128 v[168:171], v188
	ds_read_b128 v[164:167], v184 offset:4096
	ds_read_b128 v[172:175], v188 offset:4096
	ds_read_b128 v[176:179], v188 offset:8192
	ds_read_b128 v[180:183], v188 offset:12288
	ds_read_b128 v[128:131], v185
	ds_read_b128 v[136:139], v189
	ds_read_b128 v[132:135], v185 offset:4096
	ds_read_b128 v[140:143], v189 offset:4096
	ds_read_b128 v[144:147], v189 offset:8192
	ds_read_b128 v[148:151], v189 offset:12288
	s_waitcnt lgkmcnt(6)
	v_mfma_f32_32x32x16_bf16 v[112:127], v[160:163], v[168:171], 0
	v_mfma_f32_32x32x16_bf16 v[96:111], v[160:163], v[172:175], 0
	v_mfma_f32_32x32x16_bf16 v[80:95], v[160:163], v[176:179], 0
	v_mfma_f32_32x32x16_bf16 v[64:79], v[160:163], v[180:183], 0
	v_mfma_f32_32x32x16_bf16 v[48:63], v[164:167], v[168:171], 0
	v_mfma_f32_32x32x16_bf16 v[32:47], v[164:167], v[172:175], 0
	v_mfma_f32_32x32x16_bf16 v[16:31], v[164:167], v[176:179], 0
	v_mfma_f32_32x32x16_bf16 v[0:15], v[164:167], v[180:183], 0
	ds_read_b128 v[160:163], v186
	ds_read_b128 v[168:171], v190
	ds_read_b128 v[164:167], v186 offset:4096
	ds_read_b128 v[172:175], v190 offset:4096
	ds_read_b128 v[176:179], v190 offset:8192
	ds_read_b128 v[180:183], v190 offset:12288
	s_waitcnt lgkmcnt(6)
	v_mfma_f32_32x32x16_bf16 v[112:127], v[128:131], v[136:139], v[112:127]
	v_mfma_f32_32x32x16_bf16 v[96:111], v[128:131], v[140:143], v[96:111]
	v_mfma_f32_32x32x16_bf16 v[80:95], v[128:131], v[144:147], v[80:95]
	v_mfma_f32_32x32x16_bf16 v[64:79], v[128:131], v[148:151], v[64:79]
	v_mfma_f32_32x32x16_bf16 v[48:63], v[132:135], v[136:139], v[48:63]
	v_mfma_f32_32x32x16_bf16 v[32:47], v[132:135], v[140:143], v[32:47]
	v_mfma_f32_32x32x16_bf16 v[16:31], v[132:135], v[144:147], v[16:31]
	v_mfma_f32_32x32x16_bf16 v[0:15], v[132:135], v[148:151], v[0:15]
	ds_read_b128 v[128:131], v187
	ds_read_b128 v[136:139], v191
	ds_read_b128 v[132:135], v187 offset:4096
	ds_read_b128 v[140:143], v191 offset:4096
	ds_read_b128 v[144:147], v191 offset:8192
	ds_read_b128 v[148:151], v191 offset:12288
	s_waitcnt lgkmcnt(6)
	v_mfma_f32_32x32x16_bf16 v[112:127], v[160:163], v[168:171], v[112:127]
	v_mfma_f32_32x32x16_bf16 v[96:111], v[160:163], v[172:175], v[96:111]
	v_mfma_f32_32x32x16_bf16 v[80:95], v[160:163], v[176:179], v[80:95]
	v_mfma_f32_32x32x16_bf16 v[64:79], v[160:163], v[180:183], v[64:79]
	v_mfma_f32_32x32x16_bf16 v[48:63], v[164:167], v[168:171], v[48:63]
	v_mfma_f32_32x32x16_bf16 v[32:47], v[164:167], v[172:175], v[32:47]
	v_mfma_f32_32x32x16_bf16 v[16:31], v[164:167], v[176:179], v[16:31]
	v_mfma_f32_32x32x16_bf16 v[0:15], v[164:167], v[180:183], v[0:15]
	s_waitcnt vmcnt(0) lgkmcnt(0)
	s_barrier
	ds_read_b128 v[160:163], v246
	ds_read_b128 v[168:171], v250
	ds_read_b128 v[164:167], v246 offset:4096
	ds_read_b128 v[172:175], v250 offset:4096
	ds_read_b128 v[176:179], v250 offset:8192
	ds_read_b128 v[180:183], v250 offset:12288
	s_add_u32 s37, s30, s42
	s_cmp_ge_u32 s37, 1024
	s_cbranch_scc1 .Lmq3k_nonext0
	s_lshr_b32 s38, s37, 3
	s_mul_i32 s39, s38, 8
	s_sub_u32 s39, s37, s39
	s_lshl_b32 s98, s38, 16
	s_add_u32 s16, s4, s98
	s_addc_u32 s17, s5, 0
	s_lshl_b32 s98, s39, 16
	s_add_u32 s18, s6, s98
	s_addc_u32 s19, s7, 0
	s_add_u32 m0, s88, 0
	v_mfma_f32_32x32x16_bf16 v[112:127], v[128:131], v[136:139], v[112:127]
	global_load_lds_dwordx4 v192, s[16:17]
	s_add_u32 m0, s88, 32768
	v_mfma_f32_32x32x16_bf16 v[96:111], v[128:131], v[140:143], v[96:111]
	global_load_lds_dwordx4 v192, s[18:19]
	s_add_u32 m0, s88, 8192
	v_mfma_f32_32x32x16_bf16 v[80:95], v[128:131], v[144:147], v[80:95]
	global_load_lds_dwordx4 v194, s[16:17]
	s_add_u32 m0, s88, 40960
	v_mfma_f32_32x32x16_bf16 v[64:79], v[128:131], v[148:151], v[64:79]
	global_load_lds_dwordx4 v194, s[18:19]
	s_add_u32 m0, s88, 16384
	v_mfma_f32_32x32x16_bf16 v[48:63], v[132:135], v[136:139], v[48:63]
	global_load_lds_dwordx4 v196, s[16:17]
	s_add_u32 m0, s88, 49152
	v_mfma_f32_32x32x16_bf16 v[32:47], v[132:135], v[140:143], v[32:47]
	global_load_lds_dwordx4 v196, s[18:19]
	s_add_u32 m0, s88, 24576
	v_mfma_f32_32x32x16_bf16 v[16:31], v[132:135], v[144:147], v[16:31]
	global_load_lds_dwordx4 v198, s[16:17]
	s_add_u32 m0, s88, 57344
	v_mfma_f32_32x32x16_bf16 v[0:15], v[132:135], v[148:151], v[0:15]
	global_load_lds_dwordx4 v198, s[18:19]
	s_branch .Lmq3k_join0

.Lmq3k_join0:
	ds_read_b128 v[128:131], v247
	ds_read_b128 v[136:139], v251
	ds_read_b128 v[132:135], v247 offset:4096
	ds_read_b128 v[140:143], v251 offset:4096
	ds_read_b128 v[144:147], v251 offset:8192
	ds_read_b128 v[148:151], v251 offset:12288
	s_waitcnt lgkmcnt(6)
	v_mfma_f32_32x32x16_bf16 v[112:127], v[160:163], v[168:171], v[112:127]
	v_mfma_f32_32x32x16_bf16 v[96:111], v[160:163], v[172:175], v[96:111]
	v_mfma_f32_32x32x16_bf16 v[80:95], v[160:163], v[176:179], v[80:95]
	v_mfma_f32_32x32x16_bf16 v[64:79], v[160:163], v[180:183], v[64:79]
	v_mfma_f32_32x32x16_bf16 v[48:63], v[164:167], v[168:171], v[48:63]
	v_mfma_f32_32x32x16_bf16 v[32:47], v[164:167], v[172:175], v[32:47]
	v_mfma_f32_32x32x16_bf16 v[16:31], v[164:167], v[176:179], v[16:31]
	v_mfma_f32_32x32x16_bf16 v[0:15], v[164:167], v[180:183], v[0:15]
	ds_read_b128 v[160:163], v248
	ds_read_b128 v[168:171], v252
	ds_read_b128 v[164:167], v248 offset:4096
	ds_read_b128 v[172:175], v252 offset:4096
	ds_read_b128 v[176:179], v252 offset:8192
	ds_read_b128 v[180:183], v252 offset:12288
	s_waitcnt lgkmcnt(6)
	v_mfma_f32_32x32x16_bf16 v[112:127], v[128:131], v[136:139], v[112:127]
	v_mfma_f32_32x32x16_bf16 v[96:111], v[128:131], v[140:143], v[96:111]
	v_mfma_f32_32x32x16_bf16 v[80:95], v[128:131], v[144:147], v[80:95]
	v_mfma_f32_32x32x16_bf16 v[64:79], v[128:131], v[148:151], v[64:79]
	v_mfma_f32_32x32x16_bf16 v[48:63], v[132:135], v[136:139], v[48:63]
	v_mfma_f32_32x32x16_bf16 v[32:47], v[132:135], v[140:143], v[32:47]
	v_mfma_f32_32x32x16_bf16 v[16:31], v[132:135], v[144:147], v[16:31]
	v_mfma_f32_32x32x16_bf16 v[0:15], v[132:135], v[148:151], v[0:15]
	ds_read_b128 v[128:131], v249
	ds_read_b128 v[136:139], v253
	ds_read_b128 v[132:135], v249 offset:4096
	ds_read_b128 v[140:143], v253 offset:4096
	ds_read_b128 v[144:147], v253 offset:8192
	ds_read_b128 v[148:151], v253 offset:12288
	s_waitcnt lgkmcnt(6)
	v_mfma_f32_32x32x16_bf16 v[112:127], v[160:163], v[168:171], v[112:127]
	v_mfma_f32_32x32x16_bf16 v[96:111], v[160:163], v[172:175], v[96:111]
	v_mfma_f32_32x32x16_bf16 v[80:95], v[160:163], v[176:179], v[80:95]
	v_mfma_f32_32x32x16_bf16 v[64:79], v[160:163], v[180:183], v[64:79]
	v_mfma_f32_32x32x16_bf16 v[48:63], v[164:167], v[168:171], v[48:63]
	v_mfma_f32_32x32x16_bf16 v[32:47], v[164:167], v[172:175], v[32:47]
	v_mfma_f32_32x32x16_bf16 v[16:31], v[164:167], v[176:179], v[16:31]
	v_mfma_f32_32x32x16_bf16 v[0:15], v[164:167], v[180:183], v[0:15]
	s_waitcnt vmcnt(0) lgkmcnt(0)
	s_barrier
	v_mfma_f32_32x32x16_bf16 v[112:127], v[128:131], v[136:139], v[112:127]
	v_mul_f32_e32 v213, 0x3c000000, v213
	v_mul_f32_e32 v214, 0x3c000000, v214
	v_mul_f32_e32 v215, 0x3c000000, v215
	v_mul_f32_e32 v216, 0x3c000000, v216
	v_add_f32_e32 v213, 0x358637bd, v213
	v_add_f32_e32 v214, 0x358637bd, v214
	v_add_f32_e32 v215, 0x358637bd, v215
	v_add_f32_e32 v216, 0x358637bd, v216
	v_rsq_f32_e32 v213, v213
	v_rsq_f32_e32 v214, v214
	v_rsq_f32_e32 v215, v215
	v_rsq_f32_e32 v216, v216
	v_mfma_f32_32x32x16_bf16 v[96:111], v[128:131], v[140:143], v[96:111]
	v_mul_f32_e32 v217, 0x3c000000, v217
	v_mul_f32_e32 v218, 0x3c000000, v218
	v_mul_f32_e32 v219, 0x3c000000, v219
	v_mul_f32_e32 v220, 0x3c000000, v220
	v_add_f32_e32 v217, 0x358637bd, v217
	v_add_f32_e32 v218, 0x358637bd, v218
	v_add_f32_e32 v219, 0x358637bd, v219
	v_add_f32_e32 v220, 0x358637bd, v220
	v_rsq_f32_e32 v217, v217
	v_rsq_f32_e32 v218, v218
	v_rsq_f32_e32 v219, v219
	v_rsq_f32_e32 v220, v220
	v_mfma_f32_32x32x16_bf16 v[80:95], v[128:131], v[144:147], v[80:95]
	v_mul_f32_e32 v221, 0x3c000000, v221
	v_mul_f32_e32 v222, 0x3c000000, v222
	v_mul_f32_e32 v223, 0x3c000000, v223
	v_mul_f32_e32 v224, 0x3c000000, v224
	v_add_f32_e32 v221, 0x358637bd, v221
	v_add_f32_e32 v222, 0x358637bd, v222
	v_add_f32_e32 v223, 0x358637bd, v223
	v_add_f32_e32 v224, 0x358637bd, v224
	v_rsq_f32_e32 v221, v221
	v_rsq_f32_e32 v222, v222
	v_rsq_f32_e32 v223, v223
	v_rsq_f32_e32 v224, v224
	v_mfma_f32_32x32x16_bf16 v[64:79], v[128:131], v[148:151], v[64:79]
	v_mul_f32_e32 v225, 0x3c000000, v225
	v_mul_f32_e32 v226, 0x3c000000, v226
	v_mul_f32_e32 v227, 0x3c000000, v227
	v_mul_f32_e32 v228, 0x3c000000, v228
	v_add_f32_e32 v225, 0x358637bd, v225
	v_add_f32_e32 v226, 0x358637bd, v226
	v_add_f32_e32 v227, 0x358637bd, v227
	v_add_f32_e32 v228, 0x358637bd, v228
	v_rsq_f32_e32 v225, v225
	v_rsq_f32_e32 v226, v226
	v_rsq_f32_e32 v227, v227
	v_rsq_f32_e32 v228, v228
	v_mfma_f32_32x32x16_bf16 v[48:63], v[132:135], v[136:139], v[48:63]
	v_mul_f32_e32 v229, 0x3c000000, v229
	v_mul_f32_e32 v230, 0x3c000000, v230
	v_mul_f32_e32 v231, 0x3c000000, v231
	v_mul_f32_e32 v232, 0x3c000000, v232
	v_add_f32_e32 v229, 0x358637bd, v229
	v_add_f32_e32 v230, 0x358637bd, v230
	v_add_f32_e32 v231, 0x358637bd, v231
	v_add_f32_e32 v232, 0x358637bd, v232
	v_rsq_f32_e32 v229, v229
	v_rsq_f32_e32 v230, v230
	v_rsq_f32_e32 v231, v231
	v_rsq_f32_e32 v232, v232
	v_mfma_f32_32x32x16_bf16 v[32:47], v[132:135], v[140:143], v[32:47]
	v_mul_f32_e32 v233, 0x3c000000, v233
	v_mul_f32_e32 v234, 0x3c000000, v234
	v_mul_f32_e32 v235, 0x3c000000, v235
	v_mul_f32_e32 v236, 0x3c000000, v236
	v_add_f32_e32 v233, 0x358637bd, v233
	v_add_f32_e32 v234, 0x358637bd, v234
	v_add_f32_e32 v235, 0x358637bd, v235
	v_add_f32_e32 v236, 0x358637bd, v236
	v_rsq_f32_e32 v233, v233
	v_rsq_f32_e32 v234, v234
	v_rsq_f32_e32 v235, v235
	v_rsq_f32_e32 v236, v236
	v_mfma_f32_32x32x16_bf16 v[16:31], v[132:135], v[144:147], v[16:31]
	v_mul_f32_e32 v237, 0x3c000000, v237
	v_mul_f32_e32 v238, 0x3c000000, v238
	v_mul_f32_e32 v239, 0x3c000000, v239
	v_mul_f32_e32 v240, 0x3c000000, v240
	v_add_f32_e32 v237, 0x358637bd, v237
	v_add_f32_e32 v238, 0x358637bd, v238
	v_add_f32_e32 v239, 0x358637bd, v239
	v_add_f32_e32 v240, 0x358637bd, v240
	v_rsq_f32_e32 v237, v237
	v_rsq_f32_e32 v238, v238
	v_rsq_f32_e32 v239, v239
	v_rsq_f32_e32 v240, v240
	v_mfma_f32_32x32x16_bf16 v[0:15], v[132:135], v[148:151], v[0:15]
	v_mul_f32_e32 v241, 0x3c000000, v241
	v_mul_f32_e32 v242, 0x3c000000, v242
	v_mul_f32_e32 v243, 0x3c000000, v243
	v_mul_f32_e32 v244, 0x3c000000, v244
	v_add_f32_e32 v241, 0x358637bd, v241
	v_add_f32_e32 v242, 0x358637bd, v242
	v_add_f32_e32 v243, 0x358637bd, v243
	v_add_f32_e32 v244, 0x358637bd, v244
	v_rsq_f32_e32 v241, v241
	v_rsq_f32_e32 v242, v242
	v_rsq_f32_e32 v243, v243
	v_rsq_f32_e32 v244, v244
	s_nop 7
	s_add_u32 s94, s92, 0
	s_add_u32 s95, s93, 0
	s_lshr_b32 s90, s95, 6
	s_lshr_b32 s96, s94, 12
	s_and_b32 s97, s94, 0xfff
	s_lshr_b32 s91, s90, 2
	s_and_b32 s98, s90, 3
	s_cmp_lt_u32 s98, 2
	s_cbranch_scc0 .Lmq3k_e00_v
	s_mul_i32 s89, s96, 0xc00000
	s_mul_i32 s91, s91, 0x180000
	s_add_u32 s89, s89, s91
	s_lshl_b32 s91, s98, 7
	s_add_u32 s89, s89, s91
	s_mul_i32 s91, s97, 0x180
	s_add_u32 s89, s89, s91
	s_movk_i32 s99, 0x180
	s_mov_b64 s[2:3], s[12:13]
	s_branch .Lmq3k_e00_plain

.Lgk1_loop:
	ds_read_b128 v[128:131], v231
	ds_read_b128 v[136:139], v235
	ds_read_b128 v[132:135], v231 offset:4096
	ds_read_b128 v[140:143], v235 offset:4096
	ds_read_b128 v[144:147], v235 offset:8192
	ds_read_b128 v[148:151], v235 offset:12288
	s_waitcnt lgkmcnt(6)
	v_mfma_f32_32x32x16_bf16 v[112:127], v[188:191], v[196:199], v[112:127]
	v_mfma_f32_32x32x16_bf16 v[96:111], v[188:191], v[200:203], v[96:111]
	v_mfma_f32_32x32x16_bf16 v[80:95], v[188:191], v[204:207], v[80:95]
	v_mfma_f32_32x32x16_bf16 v[64:79], v[188:191], v[226:229], v[64:79]
	v_mfma_f32_32x32x16_bf16 v[48:63], v[192:195], v[196:199], v[48:63]
	v_mfma_f32_32x32x16_bf16 v[32:47], v[192:195], v[200:203], v[32:47]
	v_mfma_f32_32x32x16_bf16 v[16:31], v[192:195], v[204:207], v[16:31]
	v_mfma_f32_32x32x16_bf16 v[0:15], v[192:195], v[226:229], v[0:15]
	ds_read_b128 v[188:191], v232
	ds_read_b128 v[196:199], v236
	ds_read_b128 v[192:195], v232 offset:4096
	ds_read_b128 v[200:203], v236 offset:4096
	ds_read_b128 v[204:207], v236 offset:8192
	ds_read_b128 v[226:229], v236 offset:12288
	s_waitcnt lgkmcnt(6)
	v_mfma_f32_32x32x16_bf16 v[112:127], v[128:131], v[136:139], v[112:127]
	v_mfma_f32_32x32x16_bf16 v[96:111], v[128:131], v[140:143], v[96:111]
	v_mfma_f32_32x32x16_bf16 v[80:95], v[128:131], v[144:147], v[80:95]
	v_mfma_f32_32x32x16_bf16 v[64:79], v[128:131], v[148:151], v[64:79]
	v_mfma_f32_32x32x16_bf16 v[48:63], v[132:135], v[136:139], v[48:63]
	v_mfma_f32_32x32x16_bf16 v[32:47], v[132:135], v[140:143], v[32:47]
	v_mfma_f32_32x32x16_bf16 v[16:31], v[132:135], v[144:147], v[16:31]
	v_mfma_f32_32x32x16_bf16 v[0:15], v[132:135], v[148:151], v[0:15]
	ds_read_b128 v[128:131], v233
	ds_read_b128 v[136:139], v237
	ds_read_b128 v[132:135], v233 offset:4096
	ds_read_b128 v[140:143], v237 offset:4096
	ds_read_b128 v[144:147], v237 offset:8192
	ds_read_b128 v[148:151], v237 offset:12288
	s_waitcnt lgkmcnt(6)
	v_mfma_f32_32x32x16_bf16 v[112:127], v[188:191], v[196:199], v[112:127]
	v_mfma_f32_32x32x16_bf16 v[96:111], v[188:191], v[200:203], v[96:111]
	v_mfma_f32_32x32x16_bf16 v[80:95], v[188:191], v[204:207], v[80:95]
	v_mfma_f32_32x32x16_bf16 v[64:79], v[188:191], v[226:229], v[64:79]
	v_mfma_f32_32x32x16_bf16 v[48:63], v[192:195], v[196:199], v[48:63]
	v_mfma_f32_32x32x16_bf16 v[32:47], v[192:195], v[200:203], v[32:47]
	v_mfma_f32_32x32x16_bf16 v[16:31], v[192:195], v[204:207], v[16:31]
	v_mfma_f32_32x32x16_bf16 v[0:15], v[192:195], v[226:229], v[0:15]
	s_waitcnt vmcnt(0) lgkmcnt(0)
	s_barrier
	ds_read_b128 v[188:191], v208
	ds_read_b128 v[196:199], v241
	ds_read_b128 v[192:195], v208 offset:4096
	ds_read_b128 v[200:203], v241 offset:4096
	ds_read_b128 v[204:207], v241 offset:8192
	ds_read_b128 v[226:229], v241 offset:12288
	s_add_u32 s94, s2, s92
	s_add_u32 s94, s94, 0x100
	s_and_b32 s94, s94, 0x780
	s_sub_u32 s94, s94, 0x80
	s_subb_u32 s95, 0, 0
	s_add_u32 s100, s96, s94
	s_addc_u32 s101, s97, s95
	s_add_u32 s94, s98, s94
	s_addc_u32 s95, s99, s95
	s_add_u32 s90, s88, s89
	s_add_u32 m0, s90, 0
	v_mfma_f32_32x32x16_bf16 v[112:127], v[128:131], v[136:139], v[112:127]
	global_load_lds_dwordx4 v152, s[100:101]
	s_add_u32 m0, s90, 32768
	v_mfma_f32_32x32x16_bf16 v[96:111], v[128:131], v[140:143], v[96:111]
	global_load_lds_dwordx4 v153, s[94:95]
	s_add_u32 m0, s90, 8192
	v_mfma_f32_32x32x16_bf16 v[80:95], v[128:131], v[144:147], v[80:95]
	global_load_lds_dwordx4 v154, s[100:101]
	s_add_u32 m0, s90, 40960
	v_mfma_f32_32x32x16_bf16 v[64:79], v[128:131], v[148:151], v[64:79]
	global_load_lds_dwordx4 v155, s[94:95]
	s_add_u32 m0, s90, 16384
	v_mfma_f32_32x32x16_bf16 v[48:63], v[132:135], v[136:139], v[48:63]
	global_load_lds_dwordx4 v156, s[100:101]
	s_add_u32 m0, s90, 49152
	v_mfma_f32_32x32x16_bf16 v[32:47], v[132:135], v[140:143], v[32:47]
	global_load_lds_dwordx4 v157, s[94:95]
	s_add_u32 m0, s90, 24576
	v_mfma_f32_32x32x16_bf16 v[16:31], v[132:135], v[144:147], v[16:31]
	global_load_lds_dwordx4 v158, s[100:101]
	s_add_u32 m0, s90, 57344
	v_mfma_f32_32x32x16_bf16 v[0:15], v[132:135], v[148:151], v[0:15]
	global_load_lds_dwordx4 v168, s[94:95]
	s_xor_b32 s89, s89, 0x10000
	s_add_i32 s7, s7, 1
	s_add_u32 s2, s2, 0x80
	s_addc_u32 s3, s3, 0
	ds_read_b128 v[128:131], v238
	ds_read_b128 v[136:139], v253
	ds_read_b128 v[132:135], v238 offset:4096
	ds_read_b128 v[140:143], v253 offset:4096
	ds_read_b128 v[144:147], v253 offset:8192
	ds_read_b128 v[148:151], v253 offset:12288
	s_waitcnt lgkmcnt(6)
	v_mfma_f32_32x32x16_bf16 v[112:127], v[188:191], v[196:199], v[112:127]
	v_mfma_f32_32x32x16_bf16 v[96:111], v[188:191], v[200:203], v[96:111]
	v_mfma_f32_32x32x16_bf16 v[80:95], v[188:191], v[204:207], v[80:95]
	v_mfma_f32_32x32x16_bf16 v[64:79], v[188:191], v[226:229], v[64:79]
	v_mfma_f32_32x32x16_bf16 v[48:63], v[192:195], v[196:199], v[48:63]
	v_mfma_f32_32x32x16_bf16 v[32:47], v[192:195], v[200:203], v[32:47]
	v_mfma_f32_32x32x16_bf16 v[16:31], v[192:195], v[204:207], v[16:31]
	v_mfma_f32_32x32x16_bf16 v[0:15], v[192:195], v[226:229], v[0:15]
	ds_read_b128 v[188:191], v239
	ds_read_b128 v[196:199], v254
	ds_read_b128 v[192:195], v239 offset:4096
	ds_read_b128 v[200:203], v254 offset:4096
	ds_read_b128 v[204:207], v254 offset:8192
	ds_read_b128 v[226:229], v254 offset:12288
	s_waitcnt lgkmcnt(6)
	v_mfma_f32_32x32x16_bf16 v[112:127], v[128:131], v[136:139], v[112:127]
	v_mfma_f32_32x32x16_bf16 v[96:111], v[128:131], v[140:143], v[96:111]
	v_mfma_f32_32x32x16_bf16 v[80:95], v[128:131], v[144:147], v[80:95]
	v_mfma_f32_32x32x16_bf16 v[64:79], v[128:131], v[148:151], v[64:79]
	v_mfma_f32_32x32x16_bf16 v[48:63], v[132:135], v[136:139], v[48:63]
	v_mfma_f32_32x32x16_bf16 v[32:47], v[132:135], v[140:143], v[32:47]
	v_mfma_f32_32x32x16_bf16 v[16:31], v[132:135], v[144:147], v[16:31]
	v_mfma_f32_32x32x16_bf16 v[0:15], v[132:135], v[148:151], v[0:15]
	ds_read_b128 v[128:131], v240
	ds_read_b128 v[136:139], v255
	ds_read_b128 v[132:135], v240 offset:4096
	ds_read_b128 v[140:143], v255 offset:4096
	ds_read_b128 v[144:147], v255 offset:8192
	ds_read_b128 v[148:151], v255 offset:12288
	s_waitcnt lgkmcnt(6)
	v_mfma_f32_32x32x16_bf16 v[112:127], v[188:191], v[196:199], v[112:127]
	v_mfma_f32_32x32x16_bf16 v[96:111], v[188:191], v[200:203], v[96:111]
	v_mfma_f32_32x32x16_bf16 v[80:95], v[188:191], v[204:207], v[80:95]
	v_mfma_f32_32x32x16_bf16 v[64:79], v[188:191], v[226:229], v[64:79]
	v_mfma_f32_32x32x16_bf16 v[48:63], v[192:195], v[196:199], v[48:63]
	v_mfma_f32_32x32x16_bf16 v[32:47], v[192:195], v[200:203], v[32:47]
	v_mfma_f32_32x32x16_bf16 v[16:31], v[192:195], v[204:207], v[16:31]
	v_mfma_f32_32x32x16_bf16 v[0:15], v[192:195], v[226:229], v[0:15]
	s_waitcnt vmcnt(0) lgkmcnt(0)
	s_barrier
	ds_read_b128 v[188:191], v230
	ds_read_b128 v[196:199], v234
	ds_read_b128 v[192:195], v230 offset:4096
	ds_read_b128 v[200:203], v234 offset:4096
	ds_read_b128 v[204:207], v234 offset:8192
	ds_read_b128 v[226:229], v234 offset:12288
	s_add_u32 s94, s2, s92
	s_add_u32 s94, s94, 0x100
	s_and_b32 s94, s94, 0x780
	s_sub_u32 s94, s94, 0x80
	s_subb_u32 s95, 0, 0
	s_add_u32 s100, s96, s94
	s_addc_u32 s101, s97, s95
	s_add_u32 s94, s98, s94
	s_addc_u32 s95, s99, s95
	s_add_u32 s90, s88, s89
	s_add_u32 m0, s90, 0
	v_mfma_f32_32x32x16_bf16 v[112:127], v[128:131], v[136:139], v[112:127]
	global_load_lds_dwordx4 v152, s[100:101]
	s_add_u32 m0, s90, 32768
	v_mfma_f32_32x32x16_bf16 v[96:111], v[128:131], v[140:143], v[96:111]
	global_load_lds_dwordx4 v153, s[94:95]
	s_add_u32 m0, s90, 8192
	v_mfma_f32_32x32x16_bf16 v[80:95], v[128:131], v[144:147], v[80:95]
	global_load_lds_dwordx4 v154, s[100:101]
	s_add_u32 m0, s90, 40960
	v_mfma_f32_32x32x16_bf16 v[64:79], v[128:131], v[148:151], v[64:79]
	global_load_lds_dwordx4 v155, s[94:95]
	s_add_u32 m0, s90, 16384
	v_mfma_f32_32x32x16_bf16 v[48:63], v[132:135], v[136:139], v[48:63]
	global_load_lds_dwordx4 v156, s[100:101]
	s_add_u32 m0, s90, 49152
	v_mfma_f32_32x32x16_bf16 v[32:47], v[132:135], v[140:143], v[32:47]
	global_load_lds_dwordx4 v157, s[94:95]
	s_add_u32 m0, s90, 24576
	v_mfma_f32_32x32x16_bf16 v[16:31], v[132:135], v[144:147], v[16:31]
	global_load_lds_dwordx4 v158, s[100:101]
	s_add_u32 m0, s90, 57344
	v_mfma_f32_32x32x16_bf16 v[0:15], v[132:135], v[148:151], v[0:15]
	global_load_lds_dwordx4 v168, s[94:95]
	s_xor_b32 s89, s89, 0x10000
	s_add_i32 s7, s7, 1
	s_add_u32 s2, s2, 0x80
	s_addc_u32 s3, s3, 0
	s_cmpk_eq_i32 s2, 0x700
	s_cbranch_scc0 .Lgk1_loop
	ds_read_b128 v[128:131], v231
	ds_read_b128 v[136:139], v235
	ds_read_b128 v[132:135], v231 offset:4096
	ds_read_b128 v[140:143], v235 offset:4096
	ds_read_b128 v[144:147], v235 offset:8192
	ds_read_b128 v[148:151], v235 offset:12288
	s_waitcnt lgkmcnt(6)
	v_mfma_f32_32x32x16_bf16 v[112:127], v[188:191], v[196:199], v[112:127]
	v_mfma_f32_32x32x16_bf16 v[96:111], v[188:191], v[200:203], v[96:111]
	v_mfma_f32_32x32x16_bf16 v[80:95], v[188:191], v[204:207], v[80:95]
	v_mfma_f32_32x32x16_bf16 v[64:79], v[188:191], v[226:229], v[64:79]
	v_mfma_f32_32x32x16_bf16 v[48:63], v[192:195], v[196:199], v[48:63]
	v_mfma_f32_32x32x16_bf16 v[32:47], v[192:195], v[200:203], v[32:47]
	v_mfma_f32_32x32x16_bf16 v[16:31], v[192:195], v[204:207], v[16:31]
	v_mfma_f32_32x32x16_bf16 v[0:15], v[192:195], v[226:229], v[0:15]
	ds_read_b128 v[188:191], v232
	ds_read_b128 v[196:199], v236
	ds_read_b128 v[192:195], v232 offset:4096
	ds_read_b128 v[200:203], v236 offset:4096
	ds_read_b128 v[204:207], v236 offset:8192
	ds_read_b128 v[226:229], v236 offset:12288
	s_waitcnt lgkmcnt(6)
	v_mfma_f32_32x32x16_bf16 v[112:127], v[128:131], v[136:139], v[112:127]
	v_mfma_f32_32x32x16_bf16 v[96:111], v[128:131], v[140:143], v[96:111]
	v_mfma_f32_32x32x16_bf16 v[80:95], v[128:131], v[144:147], v[80:95]
	v_mfma_f32_32x32x16_bf16 v[64:79], v[128:131], v[148:151], v[64:79]
	v_mfma_f32_32x32x16_bf16 v[48:63], v[132:135], v[136:139], v[48:63]
	v_mfma_f32_32x32x16_bf16 v[32:47], v[132:135], v[140:143], v[32:47]
	v_mfma_f32_32x32x16_bf16 v[16:31], v[132:135], v[144:147], v[16:31]
	v_mfma_f32_32x32x16_bf16 v[0:15], v[132:135], v[148:151], v[0:15]
	ds_read_b128 v[128:131], v233
	ds_read_b128 v[136:139], v237
	ds_read_b128 v[132:135], v233 offset:4096
	ds_read_b128 v[140:143], v237 offset:4096
	ds_read_b128 v[144:147], v237 offset:8192
	ds_read_b128 v[148:151], v237 offset:12288
	s_waitcnt lgkmcnt(6)
	v_mfma_f32_32x32x16_bf16 v[112:127], v[188:191], v[196:199], v[112:127]
	v_mfma_f32_32x32x16_bf16 v[96:111], v[188:191], v[200:203], v[96:111]
	v_mfma_f32_32x32x16_bf16 v[80:95], v[188:191], v[204:207], v[80:95]
	v_mfma_f32_32x32x16_bf16 v[64:79], v[188:191], v[226:229], v[64:79]
	v_mfma_f32_32x32x16_bf16 v[48:63], v[192:195], v[196:199], v[48:63]
	v_mfma_f32_32x32x16_bf16 v[32:47], v[192:195], v[200:203], v[32:47]
	v_mfma_f32_32x32x16_bf16 v[16:31], v[192:195], v[204:207], v[16:31]
	v_mfma_f32_32x32x16_bf16 v[0:15], v[192:195], v[226:229], v[0:15]
	s_waitcnt vmcnt(0) lgkmcnt(0)
	s_barrier
	ds_read_b128 v[188:191], v208
	ds_read_b128 v[196:199], v241
	ds_read_b128 v[192:195], v208 offset:4096
	ds_read_b128 v[200:203], v241 offset:4096
	ds_read_b128 v[204:207], v241 offset:8192
	ds_read_b128 v[226:229], v241 offset:12288
	v_mfma_f32_32x32x16_bf16 v[112:127], v[128:131], v[136:139], v[112:127]
	v_mfma_f32_32x32x16_bf16 v[96:111], v[128:131], v[140:143], v[96:111]
	v_mfma_f32_32x32x16_bf16 v[80:95], v[128:131], v[144:147], v[80:95]
	v_mfma_f32_32x32x16_bf16 v[64:79], v[128:131], v[148:151], v[64:79]
	v_mfma_f32_32x32x16_bf16 v[48:63], v[132:135], v[136:139], v[48:63]
	v_mfma_f32_32x32x16_bf16 v[32:47], v[132:135], v[140:143], v[32:47]
	v_mfma_f32_32x32x16_bf16 v[16:31], v[132:135], v[144:147], v[16:31]
	v_mfma_f32_32x32x16_bf16 v[0:15], v[132:135], v[148:151], v[0:15]
	s_xor_b32 s89, s89, 0x10000
	s_add_i32 s7, s7, 1
	s_add_u32 s2, s2, 0x80
	s_addc_u32 s3, s3, 0
	s_add_i32 s54, s5, s42
	s_cmpk_gt_i32 s54, 0x1ff
	s_cselect_b64 s[20:21], -1, 0
	s_and_b64 vcc, exec, s[20:21]
	s_cbranch_vccnz .LBB0_1279
	s_ashr_i32 s2, s54, 31
	s_lshr_b32 s2, s2, 30
	s_add_i32 s2, s54, s2
	s_ashr_i32 s2, s2, 2
	s_lshl_b32 s3, s2, 8
	v_add_u32_e32 v129, s3, v213
	s_lshl_b32 s2, s2, 10
	s_lshl_b32 s7, s54, 8
	v_min_i32_e32 v132, 0x7fff, v129
	v_add_u32_e32 v129, s3, v171
	s_sub_i32 s2, s7, s2
	v_add_u32_e32 v128, s3, v212
	v_min_i32_e32 v136, 0x7fff, v129
	v_add_u32_e32 v129, s3, v215
	v_min_i32_e32 v128, 0x7fff, v128
	v_add_u32_e32 v130, s2, v212
	v_add_u32_e32 v134, s2, v213
	v_add_u32_e32 v138, s2, v171
	v_min_i32_e32 v140, 0x7fff, v129
	v_add_u32_e32 v142, s2, v215
	v_ashrrev_i32_e32 v143, 31, v142
	v_ashrrev_i32_e32 v141, 31, v140
	v_ashrrev_i32_e32 v139, 31, v138
	v_ashrrev_i32_e32 v137, 31, v136
	v_ashrrev_i32_e32 v135, 31, v134
	v_ashrrev_i32_e32 v133, 31, v132
	v_ashrrev_i32_e32 v131, 31, v130
	v_ashrrev_i32_e32 v129, 31, v128
	v_lshlrev_b64 v[142:143], 11, v[142:143]
	v_lshlrev_b64 v[140:141], 11, v[140:141]
	v_lshlrev_b64 v[138:139], 11, v[138:139]
	v_lshlrev_b64 v[136:137], 11, v[136:137]
	v_lshlrev_b64 v[134:135], 11, v[134:135]
	v_lshlrev_b64 v[132:133], 11, v[132:133]
	v_lshlrev_b64 v[130:131], 11, v[130:131]
	v_lshlrev_b64 v[128:129], 11, v[128:129]
	v_lshl_add_u64 v[156:157], v[172:173], 0, v[142:143]
	v_lshl_add_u64 v[152:153], v[174:175], 0, v[140:141]
	v_lshl_add_u64 v[148:149], v[172:173], 0, v[138:139]
	v_lshl_add_u64 v[144:145], v[174:175], 0, v[136:137]
	v_lshl_add_u64 v[140:141], v[172:173], 0, v[134:135]
	v_lshl_add_u64 v[136:137], v[174:175], 0, v[132:133]
	v_lshl_add_u64 v[132:133], v[172:173], 0, v[130:131]
	v_lshl_add_u64 v[128:129], v[174:175], 0, v[128:129]
	s_add_u32 m0, s88, 0
	v_lshl_add_u64 v[128:129], v[128:129], 0, s[92:93]
	v_xor_b32_e32 v128, v159, v128
	global_load_lds_dwordx4 v[128:129], off
	s_add_u32 m0, s88, 32768
	v_lshl_add_u64 v[132:133], v[132:133], 0, s[92:93]
	v_xor_b32_e32 v132, v159, v132
	global_load_lds_dwordx4 v[132:133], off
	s_add_u32 m0, s88, 8192
	v_lshl_add_u64 v[136:137], v[136:137], 0, s[92:93]
	v_xor_b32_e32 v136, v159, v136
	global_load_lds_dwordx4 v[136:137], off
	s_add_u32 m0, s88, 40960
	v_lshl_add_u64 v[140:141], v[140:141], 0, s[92:93]
	v_xor_b32_e32 v140, v159, v140
	global_load_lds_dwordx4 v[140:141], off
	s_add_u32 m0, s88, 16384
	v_lshl_add_u64 v[144:145], v[144:145], 0, s[92:93]
	v_xor_b32_e32 v144, v159, v144
	global_load_lds_dwordx4 v[144:145], off
	s_add_u32 m0, s88, 49152
	v_lshl_add_u64 v[148:149], v[148:149], 0, s[92:93]
	v_xor_b32_e32 v148, v159, v148
	global_load_lds_dwordx4 v[148:149], off
	s_add_u32 m0, s88, 24576
	v_lshl_add_u64 v[152:153], v[152:153], 0, s[92:93]
	v_xor_b32_e32 v152, v159, v152
	global_load_lds_dwordx4 v[152:153], off
	s_add_u32 m0, s88, 57344
	v_lshl_add_u64 v[156:157], v[156:157], 0, s[92:93]
	v_xor_b32_e32 v156, v159, v156
	global_load_lds_dwordx4 v[156:157], off
.LBB0_1279:
	ds_read_b128 v[128:131], v238
	ds_read_b128 v[136:139], v253
	ds_read_b128 v[132:135], v238 offset:4096
	ds_read_b128 v[140:143], v253 offset:4096
	ds_read_b128 v[144:147], v253 offset:8192
	ds_read_b128 v[148:151], v253 offset:12288
	s_waitcnt lgkmcnt(6)
	v_mfma_f32_32x32x16_bf16 v[112:127], v[188:191], v[196:199], v[112:127]
	v_mfma_f32_32x32x16_bf16 v[96:111], v[188:191], v[200:203], v[96:111]
	v_mfma_f32_32x32x16_bf16 v[80:95], v[188:191], v[204:207], v[80:95]
	v_mfma_f32_32x32x16_bf16 v[64:79], v[188:191], v[226:229], v[64:79]
	v_mfma_f32_32x32x16_bf16 v[48:63], v[192:195], v[196:199], v[48:63]
	v_mfma_f32_32x32x16_bf16 v[32:47], v[192:195], v[200:203], v[32:47]
	v_mfma_f32_32x32x16_bf16 v[16:31], v[192:195], v[204:207], v[16:31]
	v_mfma_f32_32x32x16_bf16 v[0:15], v[192:195], v[226:229], v[0:15]
	ds_read_b128 v[188:191], v239
	ds_read_b128 v[196:199], v254
	ds_read_b128 v[192:195], v239 offset:4096
	ds_read_b128 v[200:203], v254 offset:4096
	ds_read_b128 v[204:207], v254 offset:8192
	ds_read_b128 v[226:229], v254 offset:12288
	s_waitcnt lgkmcnt(6)
	v_mfma_f32_32x32x16_bf16 v[112:127], v[128:131], v[136:139], v[112:127]
	v_mfma_f32_32x32x16_bf16 v[96:111], v[128:131], v[140:143], v[96:111]
	v_mfma_f32_32x32x16_bf16 v[80:95], v[128:131], v[144:147], v[80:95]
	v_mfma_f32_32x32x16_bf16 v[64:79], v[128:131], v[148:151], v[64:79]
	v_mfma_f32_32x32x16_bf16 v[48:63], v[132:135], v[136:139], v[48:63]
	v_mfma_f32_32x32x16_bf16 v[32:47], v[132:135], v[140:143], v[32:47]
	v_mfma_f32_32x32x16_bf16 v[16:31], v[132:135], v[144:147], v[16:31]
	v_mfma_f32_32x32x16_bf16 v[0:15], v[132:135], v[148:151], v[0:15]
	ds_read_b128 v[128:131], v240
	ds_read_b128 v[136:139], v255
	ds_read_b128 v[132:135], v240 offset:4096
	ds_read_b128 v[140:143], v255 offset:4096
	ds_read_b128 v[144:147], v255 offset:8192
	ds_read_b128 v[148:151], v255 offset:12288
	s_waitcnt lgkmcnt(6)
	v_mfma_f32_32x32x16_bf16 v[112:127], v[188:191], v[196:199], v[112:127]
	v_mfma_f32_32x32x16_bf16 v[96:111], v[188:191], v[200:203], v[96:111]
	v_mfma_f32_32x32x16_bf16 v[80:95], v[188:191], v[204:207], v[80:95]
	v_mfma_f32_32x32x16_bf16 v[64:79], v[188:191], v[226:229], v[64:79]
	v_mfma_f32_32x32x16_bf16 v[48:63], v[192:195], v[196:199], v[48:63]
	v_mfma_f32_32x32x16_bf16 v[32:47], v[192:195], v[200:203], v[32:47]
	v_mfma_f32_32x32x16_bf16 v[16:31], v[192:195], v[204:207], v[16:31]
	v_mfma_f32_32x32x16_bf16 v[0:15], v[192:195], v[226:229], v[0:15]
	s_waitcnt vmcnt(0) lgkmcnt(0)
	s_barrier
	v_mfma_f32_32x32x16_bf16 v[112:127], v[128:131], v[136:139], v[112:127]
	v_mfma_f32_32x32x16_bf16 v[96:111], v[128:131], v[140:143], v[96:111]
	v_mfma_f32_32x32x16_bf16 v[80:95], v[128:131], v[144:147], v[80:95]
	v_mfma_f32_32x32x16_bf16 v[64:79], v[128:131], v[148:151], v[64:79]
	v_mfma_f32_32x32x16_bf16 v[48:63], v[132:135], v[136:139], v[48:63]
	v_mfma_f32_32x32x16_bf16 v[32:47], v[132:135], v[140:143], v[32:47]
	v_mfma_f32_32x32x16_bf16 v[16:31], v[132:135], v[144:147], v[16:31]
	v_mfma_f32_32x32x16_bf16 v[0:15], v[132:135], v[148:151], v[0:15]
	s_lshl_b32 s2, s5, 8
	s_sub_i32 s2, s2, s6
	v_mov_b32_e32 v168, v214
	s_add_i32 s55, s4, s30
	s_or_b32 s26, s2, s31
	s_ashr_i32 s27, s26, 31
	s_load_dwordx2 s[24:25], s[0:1], 0x140
	v_ashrrev_i32_e32 v180, 3, v168
	v_and_b32_e32 v183, -4, v180
	v_add_u32_e32 v225, s55, v183
	v_add_u32_e32 v190, 8, v225
	v_min_i32_e32 v190, 0x7fff, v190
	v_ashrrev_i32_e32 v190, 12, v190
	v_min_i32_e32 v184, 0x7fff, v225
	v_and_b32_e32 v182, 31, v168
	v_ashrrev_i32_e32 v184, 12, v184
	v_or_b32_e32 v180, s26, v182
	v_mul_hi_i32_i24_e32 v185, 0x3000, v184
	v_mul_i32_i24_e32 v184, 0x3000, v184
	v_ashrrev_i32_e32 v181, 31, v180
	s_waitcnt lgkmcnt(0)
	v_lshl_add_u64 v[184:185], s[24:25], 0, v[184:185]
	v_add_u32_e32 v188, 9, v225
	v_mul_hi_i32_i24_e32 v187, 0x3000, v190
	v_mul_i32_i24_e32 v186, 0x3000, v190
	v_min_i32_e32 v188, 0x7fff, v188
	v_add_u32_e32 v190, 10, v225
	v_ashrrev_i32_e32 v188, 12, v188
	v_min_i32_e32 v190, 0x7fff, v190
	v_mul_hi_i32_i24_e32 v189, 0x3000, v188
	v_mul_i32_i24_e32 v188, 0x3000, v188
	v_ashrrev_i32_e32 v190, 12, v190
	v_lshl_add_u64 v[188:189], s[24:25], 0, v[188:189]
	v_mul_hi_i32_i24_e32 v191, 0x3000, v190
	v_mul_i32_i24_e32 v190, 0x3000, v190
	v_lshl_add_u64 v[184:185], v[184:185], 0, s[18:19]
	v_lshlrev_b64 v[180:181], 2, v[180:181]
	v_lshl_add_u64 v[186:187], s[24:25], 0, v[186:187]
	v_lshl_add_u64 v[188:189], v[188:189], 0, s[18:19]
	v_lshl_add_u64 v[190:191], s[24:25], 0, v[190:191]
	v_lshl_add_u64 v[208:209], v[184:185], 0, v[180:181]
	v_lshl_add_u64 v[186:187], v[186:187], 0, s[18:19]
	v_lshl_add_u64 v[190:191], v[190:191], 0, s[18:19]
	v_lshl_add_u64 v[230:231], v[186:187], 0, v[180:181]
	v_lshl_add_u64 v[196:197], v[188:189], 0, v[180:181]
	v_lshl_add_u64 v[198:199], v[190:191], 0, v[180:181]
	global_load_dword v232, v[208:209], off
	global_load_dword v233, v[208:209], off offset:128
	global_load_dword v238, v[230:231], off
	global_load_dword v239, v[230:231], off offset:128
	global_load_dword v240, v[196:197], off
	global_load_dword v241, v[196:197], off offset:128
	global_load_dword v242, v[198:199], off
	global_load_dword v243, v[198:199], off offset:128
	v_add_u32_e32 v196, 17, v225
	v_min_i32_e32 v196, 0x7fff, v196
	v_add_u32_e32 v198, 18, v225
	v_ashrrev_i32_e32 v196, 12, v196
	v_min_i32_e32 v198, 0x7fff, v198
	v_mul_hi_i32_i24_e32 v197, 0x3000, v196
	v_mul_i32_i24_e32 v196, 0x3000, v196
	v_ashrrev_i32_e32 v198, 12, v198
	v_lshl_add_u64 v[196:197], s[24:25], 0, v[196:197]
	v_mul_hi_i32_i24_e32 v199, 0x3000, v198
	v_mul_i32_i24_e32 v198, 0x3000, v198
	v_add_u32_e32 v192, 11, v225
	v_add_u32_e32 v194, 16, v225
	v_min_i32_e32 v192, 0x7fff, v192
	v_min_i32_e32 v194, 0x7fff, v194
	v_ashrrev_i32_e32 v192, 12, v192
	v_ashrrev_i32_e32 v194, 12, v194
	v_mul_hi_i32_i24_e32 v193, 0x3000, v192
	v_mul_i32_i24_e32 v192, 0x3000, v192
	v_mul_hi_i32_i24_e32 v195, 0x3000, v194
	v_mul_i32_i24_e32 v194, 0x3000, v194
	v_lshl_add_u64 v[192:193], s[24:25], 0, v[192:193]
	v_lshl_add_u64 v[194:195], s[24:25], 0, v[194:195]
	v_lshl_add_u64 v[192:193], v[192:193], 0, s[18:19]
	v_lshl_add_u64 v[194:195], v[194:195], 0, s[18:19]
	v_lshl_add_u64 v[196:197], v[196:197], 0, s[18:19]
	v_lshl_add_u64 v[198:199], s[24:25], 0, v[198:199]
	v_lshl_add_u64 v[208:209], v[192:193], 0, v[180:181]
	v_lshl_add_u64 v[198:199], v[198:199], 0, s[18:19]
	v_lshl_add_u64 v[226:227], v[198:199], 0, v[180:181]
	s_waitcnt vmcnt(7)
	v_mul_f32_e32 v112, v112, v232
	v_lshl_add_u64 v[204:205], v[194:195], 0, v[180:181]
	v_lshl_add_u64 v[206:207], v[196:197], 0, v[180:181]
	s_waitcnt vmcnt(6)
	s_nop 2
	v_mul_f32_e32 v96, v96, v233
	v_mul_f32_e32 v97, v97, v233
	global_load_dword v234, v[208:209], off
	global_load_dword v235, v[208:209], off offset:128
	global_load_dword v236, v[204:205], off
	global_load_dword v237, v[204:205], off offset:128
	global_load_dword v244, v[206:207], off
	global_load_dword v245, v[206:207], off offset:128
	global_load_dword v246, v[226:227], off
	global_load_dword v247, v[226:227], off offset:128
	v_add_u32_e32 v204, 25, v225
	v_add_u32_e32 v206, 26, v225
	v_min_i32_e32 v204, 0x7fff, v204
	v_min_i32_e32 v206, 0x7fff, v206
	v_ashrrev_i32_e32 v204, 12, v204
	v_ashrrev_i32_e32 v206, 12, v206
	v_add_u32_e32 v200, 19, v225
	v_min_i32_e32 v200, 0x7fff, v200
	v_add_u32_e32 v202, 24, v225
	v_ashrrev_i32_e32 v200, 12, v200
	v_min_i32_e32 v202, 0x7fff, v202
	v_mul_hi_i32_i24_e32 v201, 0x3000, v200
	v_mul_i32_i24_e32 v200, 0x3000, v200
	v_ashrrev_i32_e32 v202, 12, v202
	v_mul_hi_i32_i24_e32 v205, 0x3000, v204
	v_mul_i32_i24_e32 v204, 0x3000, v204
	v_mul_hi_i32_i24_e32 v207, 0x3000, v206
	v_mul_i32_i24_e32 v206, 0x3000, v206
	v_lshl_add_u64 v[200:201], s[24:25], 0, v[200:201]
	v_mul_hi_i32_i24_e32 v203, 0x3000, v202
	v_mul_i32_i24_e32 v202, 0x3000, v202
	v_lshl_add_u64 v[204:205], s[24:25], 0, v[204:205]
	v_lshl_add_u64 v[206:207], s[24:25], 0, v[206:207]
	v_lshl_add_u64 v[200:201], v[200:201], 0, s[18:19]
	v_lshl_add_u64 v[202:203], s[24:25], 0, v[202:203]
	v_lshl_add_u64 v[204:205], v[204:205], 0, s[18:19]
	v_lshl_add_u64 v[206:207], v[206:207], 0, s[18:19]
	v_lshl_add_u64 v[208:209], v[200:201], 0, v[180:181]
	v_lshl_add_u64 v[202:203], v[202:203], 0, s[18:19]
	v_lshl_add_u64 v[228:229], v[204:205], 0, v[180:181]
	v_lshl_add_u64 v[230:231], v[206:207], 0, v[180:181]
	v_lshl_add_u64 v[226:227], v[202:203], 0, v[180:181]
	global_load_dword v248, v[208:209], off
	global_load_dword v249, v[208:209], off offset:128
	global_load_dword v250, v[226:227], off
	global_load_dword v251, v[226:227], off offset:128
	global_load_dword v252, v[228:229], off
	s_nop 0
	global_load_dword v228, v[228:229], off offset:128
	s_nop 0
	global_load_dword v229, v[230:231], off
	s_nop 0
	global_load_dword v230, v[230:231], off offset:128
	v_add_u32_e32 v208, 27, v225
	v_min_i32_e32 v208, 0x7fff, v208
	v_ashrrev_i32_e32 v208, 12, v208
	v_mul_hi_i32_i24_e32 v209, 0x3000, v208
	v_mul_i32_i24_e32 v208, 0x3000, v208
	v_lshl_add_u64 v[208:209], s[24:25], 0, v[208:209]
	v_lshl_add_u64 v[208:209], v[208:209], 0, s[18:19]
	v_lshl_add_u64 v[226:227], v[208:209], 0, v[180:181]
	global_load_dword v225, v[226:227], off
	s_nop 0
	global_load_dword v226, v[226:227], off offset:128
	v_mad_u64_u32 v[160:161], s[2:3], v183, s36, v[182:183]
	v_lshl_add_u32 v162, v160, 2, s34
	ds_write2_b32 v162, v112, v96 offset1:32
	v_mul_f32_e32 v96, v113, v232
	ds_write2_b32 v162, v96, v97 offset0:68 offset1:100
	v_mul_f32_e32 v96, v114, v232
	v_mul_f32_e32 v97, v98, v233
	ds_write2_b32 v162, v96, v97 offset0:136 offset1:168
	v_mul_f32_e32 v96, v115, v232
	v_mul_f32_e32 v97, v99, v233
	ds_write2_b32 v162, v96, v97 offset0:204 offset1:236
	s_waitcnt vmcnt(23)
	v_mul_f32_e32 v96, v116, v238
	s_waitcnt vmcnt(22)
	v_mul_f32_e32 v97, v100, v239
	v_add_u32_e32 v115, 0x800, v162
	ds_write2_b32 v115, v96, v97 offset0:32 offset1:64
	s_waitcnt vmcnt(21)
	v_mul_f32_e32 v96, v117, v240
	s_waitcnt vmcnt(20)
	v_mul_f32_e32 v97, v101, v241
	ds_write2_b32 v115, v96, v97 offset0:100 offset1:132
	s_waitcnt vmcnt(19)
	v_mul_f32_e32 v96, v118, v242
	s_waitcnt vmcnt(18)
	v_mul_f32_e32 v97, v102, v243
	ds_write2_b32 v115, v96, v97 offset0:168 offset1:200
	v_add_u32_e32 v116, 0xa00, v162
	v_add_u32_e32 v117, 0x1000, v162
	v_add_u32_e32 v118, 0x1400, v162
	v_ashrrev_i32_e32 v163, 4, v168
	v_and_b32_e32 v160, 15, v168
	v_mul_lo_u32 v161, v163, s37
	s_waitcnt vmcnt(17)
	v_mul_f32_e32 v96, v119, v234
	s_waitcnt vmcnt(16)
	v_mul_f32_e32 v97, v103, v235
	ds_write2_b32 v116, v96, v97 offset0:108 offset1:140
	s_waitcnt vmcnt(15)
	v_mul_f32_e32 v96, v120, v236
	s_waitcnt vmcnt(14)
	v_mul_f32_e32 v97, v104, v237
	ds_write2_b32 v117, v96, v97 offset0:64 offset1:96
	s_waitcnt vmcnt(13)
	v_mul_f32_e32 v96, v121, v244
	s_waitcnt vmcnt(12)
	v_mul_f32_e32 v97, v105, v245
	ds_write2_b32 v117, v96, v97 offset0:132 offset1:164
	s_waitcnt vmcnt(11)
	v_mul_f32_e32 v96, v122, v246
	s_waitcnt vmcnt(10)
	v_mul_f32_e32 v97, v106, v247
	ds_write2_b32 v117, v96, v97 offset0:200 offset1:232
	v_add_u32_e32 v119, 0x1800, v162
	v_add_u32_e32 v120, 0x1a00, v162
	v_lshl_add_u32 v164, v160, 4, s34
	v_lshlrev_b32_e32 v168, 2, v160
	v_add_u32_e32 v160, s55, v163
	v_add_u32_e32 v121, 0x1c00, v162
	v_cmp_gt_i32_e32 vcc, s38, v160
	v_add_u32_e32 v114, v164, v161
	v_ashrrev_i32_e32 v161, 31, v160
	s_waitcnt vmcnt(9)
	v_mul_f32_e32 v96, v123, v248
	s_waitcnt vmcnt(8)
	v_mul_f32_e32 v97, v107, v249
	ds_write2_b32 v118, v96, v97 offset0:12 offset1:44
	s_waitcnt vmcnt(7)
	v_mul_f32_e32 v96, v124, v250
	s_waitcnt vmcnt(6)
	v_mul_f32_e32 v97, v108, v251
	ds_write2_b32 v119, v96, v97 offset0:96 offset1:128
	s_waitcnt vmcnt(5)
	v_mul_f32_e32 v96, v125, v252
	s_waitcnt vmcnt(4)
	v_mul_f32_e32 v97, v109, v228
	ds_write2_b32 v119, v96, v97 offset0:164 offset1:196
	s_waitcnt vmcnt(3)
	v_mul_f32_e32 v96, v126, v229
	s_waitcnt vmcnt(2)
	v_mul_f32_e32 v97, v110, v230
	ds_write2_b32 v120, v96, v97 offset0:104 offset1:136
	s_waitcnt vmcnt(1)
	v_mul_f32_e32 v96, v127, v225
	s_waitcnt vmcnt(0)
	v_mul_f32_e32 v97, v111, v226
	ds_write2_b32 v121, v96, v97 offset0:44 offset1:76
	v_or_b32_e32 v96, s26, v168
	v_mov_b32_e32 v97, s27
	v_add_u32_e32 v128, 0, v160
	v_ashrrev_i32_e32 v129, 31, v128
	v_lshlrev_b64 v[128:129], 10, v[128:129]
	v_lshl_add_u64 v[128:129], v[128:129], 0, v[96:97]
	v_lshlrev_b64 v[128:129], 2, v[128:129]
	v_lshl_add_u64 v[128:129], s[16:17], 0, v[128:129]
	global_load_dwordx4 v[128:131], v[128:129], off
	v_add_u32_e32 v132, 4, v160
	v_ashrrev_i32_e32 v133, 31, v132
	v_lshlrev_b64 v[132:133], 10, v[132:133]
	v_lshl_add_u64 v[132:133], v[132:133], 0, v[96:97]
	v_lshlrev_b64 v[132:133], 2, v[132:133]
	v_lshl_add_u64 v[132:133], s[16:17], 0, v[132:133]
	global_load_dwordx4 v[132:135], v[132:133], off
	v_add_u32_e32 v136, 8, v160
	v_ashrrev_i32_e32 v137, 31, v136
	v_lshlrev_b64 v[136:137], 10, v[136:137]
	v_lshl_add_u64 v[136:137], v[136:137], 0, v[96:97]
	v_lshlrev_b64 v[136:137], 2, v[136:137]
	v_lshl_add_u64 v[136:137], s[16:17], 0, v[136:137]
	global_load_dwordx4 v[136:139], v[136:137], off
	v_add_u32_e32 v140, 12, v160
	v_ashrrev_i32_e32 v141, 31, v140
	v_lshlrev_b64 v[140:141], 10, v[140:141]
	v_lshl_add_u64 v[140:141], v[140:141], 0, v[96:97]
	v_lshlrev_b64 v[140:141], 2, v[140:141]
	v_lshl_add_u64 v[140:141], s[16:17], 0, v[140:141]
	global_load_dwordx4 v[140:143], v[140:141], off
	v_add_u32_e32 v144, 16, v160
	v_ashrrev_i32_e32 v145, 31, v144
	v_lshlrev_b64 v[144:145], 10, v[144:145]
	v_lshl_add_u64 v[144:145], v[144:145], 0, v[96:97]
	v_lshlrev_b64 v[144:145], 2, v[144:145]
	v_lshl_add_u64 v[144:145], s[16:17], 0, v[144:145]
	global_load_dwordx4 v[144:147], v[144:145], off
	v_add_u32_e32 v148, 20, v160
	v_ashrrev_i32_e32 v149, 31, v148
	v_lshlrev_b64 v[148:149], 10, v[148:149]
	v_lshl_add_u64 v[148:149], v[148:149], 0, v[96:97]
	v_lshlrev_b64 v[148:149], 2, v[148:149]
	v_lshl_add_u64 v[148:149], s[16:17], 0, v[148:149]
	global_load_dwordx4 v[148:151], v[148:149], off
	v_add_u32_e32 v152, 24, v160
	v_ashrrev_i32_e32 v153, 31, v152
	v_lshlrev_b64 v[152:153], 10, v[152:153]
	v_lshl_add_u64 v[152:153], v[152:153], 0, v[96:97]
	v_lshlrev_b64 v[152:153], 2, v[152:153]
	v_lshl_add_u64 v[152:153], s[16:17], 0, v[152:153]
	global_load_dwordx4 v[152:155], v[152:153], off
	v_add_u32_e32 v156, 28, v160
	v_ashrrev_i32_e32 v157, 31, v156
	v_lshlrev_b64 v[156:157], 10, v[156:157]
	v_lshl_add_u64 v[156:157], v[156:157], 0, v[96:97]
	v_lshlrev_b64 v[156:157], 2, v[156:157]
	v_lshl_add_u64 v[156:157], s[16:17], 0, v[156:157]
	global_load_dwordx4 v[156:159], v[156:157], off
	s_and_saveexec_b64 s[2:3], vcc
	s_cbranch_execz .LBB0_1281
	v_lshlrev_b64 v[98:99], 10, v[160:161]
	v_lshl_add_u64 v[98:99], v[98:99], 0, v[96:97]
	v_lshlrev_b64 v[106:107], 2, v[98:99]
	v_lshl_add_u64 v[98:99], s[16:17], 0, v[106:107]
	ds_read_b128 v[102:105], v114
	s_load_dwordx2 s[4:5], s[0:1], 0xb8
	s_waitcnt vmcnt(7) lgkmcnt(0)
	v_pk_add_f32 v[100:101], v[104:105], v[130:131]
	v_pk_add_f32 v[98:99], v[102:103], v[128:129]
	v_lshl_add_u64 v[102:103], s[4:5], 0, v[106:107]
	global_store_dwordx4 v[102:103], v[98:101], off

.Lgk2_loop:
	ds_read_b128 v[128:131], v233
	ds_read_b128 v[136:139], v237
	ds_read_b128 v[132:135], v233 offset:4096
	ds_read_b128 v[140:143], v237 offset:4096
	ds_read_b128 v[144:147], v237 offset:8192
	ds_read_b128 v[148:151], v237 offset:12288
	s_waitcnt lgkmcnt(6)
	v_mfma_f32_32x32x16_bf16 v[112:127], v[188:191], v[216:219], v[112:127]
	v_mfma_f32_32x32x16_bf16 v[96:111], v[188:191], v[220:223], v[96:111]
	v_mfma_f32_32x32x16_bf16 v[80:95], v[188:191], v[224:227], v[80:95]
	v_mfma_f32_32x32x16_bf16 v[64:79], v[188:191], v[228:231], v[64:79]
	v_mfma_f32_32x32x16_bf16 v[48:63], v[212:215], v[216:219], v[48:63]
	v_mfma_f32_32x32x16_bf16 v[32:47], v[212:215], v[220:223], v[32:47]
	v_mfma_f32_32x32x16_bf16 v[16:31], v[212:215], v[224:227], v[16:31]
	v_mfma_f32_32x32x16_bf16 v[0:15], v[212:215], v[228:231], v[0:15]
	ds_read_b128 v[188:191], v234
	ds_read_b128 v[216:219], v238
	ds_read_b128 v[212:215], v234 offset:4096
	ds_read_b128 v[220:223], v238 offset:4096
	ds_read_b128 v[224:227], v238 offset:8192
	ds_read_b128 v[228:231], v238 offset:12288
	s_waitcnt lgkmcnt(6)
	v_mfma_f32_32x32x16_bf16 v[112:127], v[128:131], v[136:139], v[112:127]
	v_mfma_f32_32x32x16_bf16 v[96:111], v[128:131], v[140:143], v[96:111]
	v_mfma_f32_32x32x16_bf16 v[80:95], v[128:131], v[144:147], v[80:95]
	v_mfma_f32_32x32x16_bf16 v[64:79], v[128:131], v[148:151], v[64:79]
	v_mfma_f32_32x32x16_bf16 v[48:63], v[132:135], v[136:139], v[48:63]
	v_mfma_f32_32x32x16_bf16 v[32:47], v[132:135], v[140:143], v[32:47]
	v_mfma_f32_32x32x16_bf16 v[16:31], v[132:135], v[144:147], v[16:31]
	v_mfma_f32_32x32x16_bf16 v[0:15], v[132:135], v[148:151], v[0:15]
	ds_read_b128 v[128:131], v235
	ds_read_b128 v[136:139], v239
	ds_read_b128 v[132:135], v235 offset:4096
	ds_read_b128 v[140:143], v239 offset:4096
	ds_read_b128 v[144:147], v239 offset:8192
	ds_read_b128 v[148:151], v239 offset:12288
	s_waitcnt lgkmcnt(6)
	v_mfma_f32_32x32x16_bf16 v[112:127], v[188:191], v[216:219], v[112:127]
	v_mfma_f32_32x32x16_bf16 v[96:111], v[188:191], v[220:223], v[96:111]
	v_mfma_f32_32x32x16_bf16 v[80:95], v[188:191], v[224:227], v[80:95]
	v_mfma_f32_32x32x16_bf16 v[64:79], v[188:191], v[228:231], v[64:79]
	v_mfma_f32_32x32x16_bf16 v[48:63], v[212:215], v[216:219], v[48:63]
	v_mfma_f32_32x32x16_bf16 v[32:47], v[212:215], v[220:223], v[32:47]
	v_mfma_f32_32x32x16_bf16 v[16:31], v[212:215], v[224:227], v[16:31]
	v_mfma_f32_32x32x16_bf16 v[0:15], v[212:215], v[228:231], v[0:15]
	s_waitcnt vmcnt(0) lgkmcnt(0)
	s_barrier
	ds_read_b128 v[188:191], v207
	ds_read_b128 v[216:219], v241
	ds_read_b128 v[212:215], v207 offset:4096
	ds_read_b128 v[220:223], v241 offset:4096
	ds_read_b128 v[224:227], v241 offset:8192
	ds_read_b128 v[228:231], v241 offset:12288
	s_add_u32 s94, s2, s92
	s_add_u32 s94, s94, 0x100
	s_and_b32 s94, s94, 0x780
	s_sub_u32 s94, s94, 0x80
	s_subb_u32 s95, 0, 0
	s_add_u32 s100, s96, s94
	s_addc_u32 s101, s97, s95
	s_add_u32 s94, s98, s94
	s_addc_u32 s95, s99, s95
	s_add_u32 s90, s88, s89
	s_add_u32 m0, s90, 0
	v_mfma_f32_32x32x16_bf16 v[112:127], v[128:131], v[136:139], v[112:127]
	global_load_lds_dwordx4 v152, s[100:101]
	s_add_u32 m0, s90, 32768
	v_mfma_f32_32x32x16_bf16 v[96:111], v[128:131], v[140:143], v[96:111]
	global_load_lds_dwordx4 v153, s[94:95]
	s_add_u32 m0, s90, 8192
	v_mfma_f32_32x32x16_bf16 v[80:95], v[128:131], v[144:147], v[80:95]
	global_load_lds_dwordx4 v154, s[100:101]
	s_add_u32 m0, s90, 40960
	v_mfma_f32_32x32x16_bf16 v[64:79], v[128:131], v[148:151], v[64:79]
	global_load_lds_dwordx4 v155, s[94:95]
	s_add_u32 m0, s90, 16384
	v_mfma_f32_32x32x16_bf16 v[48:63], v[132:135], v[136:139], v[48:63]
	global_load_lds_dwordx4 v156, s[100:101]
	s_add_u32 m0, s90, 49152
	v_mfma_f32_32x32x16_bf16 v[32:47], v[132:135], v[140:143], v[32:47]
	global_load_lds_dwordx4 v157, s[94:95]
	s_add_u32 m0, s90, 24576
	v_mfma_f32_32x32x16_bf16 v[16:31], v[132:135], v[144:147], v[16:31]
	global_load_lds_dwordx4 v158, s[100:101]
	s_add_u32 m0, s90, 57344
	v_mfma_f32_32x32x16_bf16 v[0:15], v[132:135], v[148:151], v[0:15]
	global_load_lds_dwordx4 v160, s[94:95]
	s_xor_b32 s89, s89, 0x10000
	s_add_i32 s5, s5, 1
	s_add_u32 s2, s2, 0x80
	s_addc_u32 s3, s3, 0
	ds_read_b128 v[128:131], v208
	ds_read_b128 v[136:139], v253
	ds_read_b128 v[132:135], v208 offset:4096
	ds_read_b128 v[140:143], v253 offset:4096
	ds_read_b128 v[144:147], v253 offset:8192
	ds_read_b128 v[148:151], v253 offset:12288
	s_waitcnt lgkmcnt(6)
	v_mfma_f32_32x32x16_bf16 v[112:127], v[188:191], v[216:219], v[112:127]
	v_mfma_f32_32x32x16_bf16 v[96:111], v[188:191], v[220:223], v[96:111]
	v_mfma_f32_32x32x16_bf16 v[80:95], v[188:191], v[224:227], v[80:95]
	v_mfma_f32_32x32x16_bf16 v[64:79], v[188:191], v[228:231], v[64:79]
	v_mfma_f32_32x32x16_bf16 v[48:63], v[212:215], v[216:219], v[48:63]
	v_mfma_f32_32x32x16_bf16 v[32:47], v[212:215], v[220:223], v[32:47]
	v_mfma_f32_32x32x16_bf16 v[16:31], v[212:215], v[224:227], v[16:31]
	v_mfma_f32_32x32x16_bf16 v[0:15], v[212:215], v[228:231], v[0:15]
	ds_read_b128 v[188:191], v209
	ds_read_b128 v[216:219], v254
	ds_read_b128 v[212:215], v209 offset:4096
	ds_read_b128 v[220:223], v254 offset:4096
	ds_read_b128 v[224:227], v254 offset:8192
	ds_read_b128 v[228:231], v254 offset:12288
	s_waitcnt lgkmcnt(6)
	v_mfma_f32_32x32x16_bf16 v[112:127], v[128:131], v[136:139], v[112:127]
	v_mfma_f32_32x32x16_bf16 v[96:111], v[128:131], v[140:143], v[96:111]
	v_mfma_f32_32x32x16_bf16 v[80:95], v[128:131], v[144:147], v[80:95]
	v_mfma_f32_32x32x16_bf16 v[64:79], v[128:131], v[148:151], v[64:79]
	v_mfma_f32_32x32x16_bf16 v[48:63], v[132:135], v[136:139], v[48:63]
	v_mfma_f32_32x32x16_bf16 v[32:47], v[132:135], v[140:143], v[32:47]
	v_mfma_f32_32x32x16_bf16 v[16:31], v[132:135], v[144:147], v[16:31]
	v_mfma_f32_32x32x16_bf16 v[0:15], v[132:135], v[148:151], v[0:15]
	ds_read_b128 v[128:131], v240
	ds_read_b128 v[136:139], v255
	ds_read_b128 v[132:135], v240 offset:4096
	ds_read_b128 v[140:143], v255 offset:4096
	ds_read_b128 v[144:147], v255 offset:8192
	ds_read_b128 v[148:151], v255 offset:12288
	s_waitcnt lgkmcnt(6)
	v_mfma_f32_32x32x16_bf16 v[112:127], v[188:191], v[216:219], v[112:127]
	v_mfma_f32_32x32x16_bf16 v[96:111], v[188:191], v[220:223], v[96:111]
	v_mfma_f32_32x32x16_bf16 v[80:95], v[188:191], v[224:227], v[80:95]
	v_mfma_f32_32x32x16_bf16 v[64:79], v[188:191], v[228:231], v[64:79]
	v_mfma_f32_32x32x16_bf16 v[48:63], v[212:215], v[216:219], v[48:63]
	v_mfma_f32_32x32x16_bf16 v[32:47], v[212:215], v[220:223], v[32:47]
	v_mfma_f32_32x32x16_bf16 v[16:31], v[212:215], v[224:227], v[16:31]
	v_mfma_f32_32x32x16_bf16 v[0:15], v[212:215], v[228:231], v[0:15]
	s_waitcnt vmcnt(0) lgkmcnt(0)
	s_barrier
	ds_read_b128 v[188:191], v232
	ds_read_b128 v[216:219], v236
	ds_read_b128 v[212:215], v232 offset:4096
	ds_read_b128 v[220:223], v236 offset:4096
	ds_read_b128 v[224:227], v236 offset:8192
	ds_read_b128 v[228:231], v236 offset:12288
	s_add_u32 s94, s2, s92
	s_add_u32 s94, s94, 0x100
	s_and_b32 s94, s94, 0x780
	s_sub_u32 s94, s94, 0x80
	s_subb_u32 s95, 0, 0
	s_add_u32 s100, s96, s94
	s_addc_u32 s101, s97, s95
	s_add_u32 s94, s98, s94
	s_addc_u32 s95, s99, s95
	s_add_u32 s90, s88, s89
	s_add_u32 m0, s90, 0
	v_mfma_f32_32x32x16_bf16 v[112:127], v[128:131], v[136:139], v[112:127]
	global_load_lds_dwordx4 v152, s[100:101]
	s_add_u32 m0, s90, 32768
	v_mfma_f32_32x32x16_bf16 v[96:111], v[128:131], v[140:143], v[96:111]
	global_load_lds_dwordx4 v153, s[94:95]
	s_add_u32 m0, s90, 8192
	v_mfma_f32_32x32x16_bf16 v[80:95], v[128:131], v[144:147], v[80:95]
	global_load_lds_dwordx4 v154, s[100:101]
	s_add_u32 m0, s90, 40960
	v_mfma_f32_32x32x16_bf16 v[64:79], v[128:131], v[148:151], v[64:79]
	global_load_lds_dwordx4 v155, s[94:95]
	s_add_u32 m0, s90, 16384
	v_mfma_f32_32x32x16_bf16 v[48:63], v[132:135], v[136:139], v[48:63]
	global_load_lds_dwordx4 v156, s[100:101]
	s_add_u32 m0, s90, 49152
	v_mfma_f32_32x32x16_bf16 v[32:47], v[132:135], v[140:143], v[32:47]
	global_load_lds_dwordx4 v157, s[94:95]
	s_add_u32 m0, s90, 24576
	v_mfma_f32_32x32x16_bf16 v[16:31], v[132:135], v[144:147], v[16:31]
	global_load_lds_dwordx4 v158, s[100:101]
	s_add_u32 m0, s90, 57344
	v_mfma_f32_32x32x16_bf16 v[0:15], v[132:135], v[148:151], v[0:15]
	global_load_lds_dwordx4 v160, s[94:95]
	s_xor_b32 s89, s89, 0x10000
	s_add_i32 s5, s5, 1
	s_add_u32 s2, s2, 0x80
	s_addc_u32 s3, s3, 0
	s_cmpk_eq_i32 s2, 0x700
	s_cbranch_scc0 .Lgk2_loop
	ds_read_b128 v[128:131], v233
	ds_read_b128 v[136:139], v237
	ds_read_b128 v[132:135], v233 offset:4096
	ds_read_b128 v[140:143], v237 offset:4096
	ds_read_b128 v[144:147], v237 offset:8192
	ds_read_b128 v[148:151], v237 offset:12288
	s_waitcnt lgkmcnt(6)
	v_mfma_f32_32x32x16_bf16 v[112:127], v[188:191], v[216:219], v[112:127]
	v_mfma_f32_32x32x16_bf16 v[96:111], v[188:191], v[220:223], v[96:111]
	v_mfma_f32_32x32x16_bf16 v[80:95], v[188:191], v[224:227], v[80:95]
	v_mfma_f32_32x32x16_bf16 v[64:79], v[188:191], v[228:231], v[64:79]
	v_mfma_f32_32x32x16_bf16 v[48:63], v[212:215], v[216:219], v[48:63]
	v_mfma_f32_32x32x16_bf16 v[32:47], v[212:215], v[220:223], v[32:47]
	v_mfma_f32_32x32x16_bf16 v[16:31], v[212:215], v[224:227], v[16:31]
	v_mfma_f32_32x32x16_bf16 v[0:15], v[212:215], v[228:231], v[0:15]
	ds_read_b128 v[188:191], v234
	ds_read_b128 v[216:219], v238
	ds_read_b128 v[212:215], v234 offset:4096
	ds_read_b128 v[220:223], v238 offset:4096
	ds_read_b128 v[224:227], v238 offset:8192
	ds_read_b128 v[228:231], v238 offset:12288
	s_waitcnt lgkmcnt(6)
	v_mfma_f32_32x32x16_bf16 v[112:127], v[128:131], v[136:139], v[112:127]
	v_mfma_f32_32x32x16_bf16 v[96:111], v[128:131], v[140:143], v[96:111]
	v_mfma_f32_32x32x16_bf16 v[80:95], v[128:131], v[144:147], v[80:95]
	v_mfma_f32_32x32x16_bf16 v[64:79], v[128:131], v[148:151], v[64:79]
	v_mfma_f32_32x32x16_bf16 v[48:63], v[132:135], v[136:139], v[48:63]
	v_mfma_f32_32x32x16_bf16 v[32:47], v[132:135], v[140:143], v[32:47]
	v_mfma_f32_32x32x16_bf16 v[16:31], v[132:135], v[144:147], v[16:31]
	v_mfma_f32_32x32x16_bf16 v[0:15], v[132:135], v[148:151], v[0:15]
	ds_read_b128 v[128:131], v235
	ds_read_b128 v[136:139], v239
	ds_read_b128 v[132:135], v235 offset:4096
	ds_read_b128 v[140:143], v239 offset:4096
	ds_read_b128 v[144:147], v239 offset:8192
	ds_read_b128 v[148:151], v239 offset:12288
	s_waitcnt lgkmcnt(6)
	v_mfma_f32_32x32x16_bf16 v[112:127], v[188:191], v[216:219], v[112:127]
	v_mfma_f32_32x32x16_bf16 v[96:111], v[188:191], v[220:223], v[96:111]
	v_mfma_f32_32x32x16_bf16 v[80:95], v[188:191], v[224:227], v[80:95]
	v_mfma_f32_32x32x16_bf16 v[64:79], v[188:191], v[228:231], v[64:79]
	v_mfma_f32_32x32x16_bf16 v[48:63], v[212:215], v[216:219], v[48:63]
	v_mfma_f32_32x32x16_bf16 v[32:47], v[212:215], v[220:223], v[32:47]
	v_mfma_f32_32x32x16_bf16 v[16:31], v[212:215], v[224:227], v[16:31]
	v_mfma_f32_32x32x16_bf16 v[0:15], v[212:215], v[228:231], v[0:15]
	s_waitcnt vmcnt(0) lgkmcnt(0)
	s_barrier
	ds_read_b128 v[188:191], v207
	ds_read_b128 v[216:219], v241
	ds_read_b128 v[212:215], v207 offset:4096
	ds_read_b128 v[220:223], v241 offset:4096
	ds_read_b128 v[224:227], v241 offset:8192
	ds_read_b128 v[228:231], v241 offset:12288
	v_mfma_f32_32x32x16_bf16 v[112:127], v[128:131], v[136:139], v[112:127]
	v_mfma_f32_32x32x16_bf16 v[96:111], v[128:131], v[140:143], v[96:111]
	v_mfma_f32_32x32x16_bf16 v[80:95], v[128:131], v[144:147], v[80:95]
	v_mfma_f32_32x32x16_bf16 v[64:79], v[128:131], v[148:151], v[64:79]
	v_mfma_f32_32x32x16_bf16 v[48:63], v[132:135], v[136:139], v[48:63]
	v_mfma_f32_32x32x16_bf16 v[32:47], v[132:135], v[140:143], v[32:47]
	v_mfma_f32_32x32x16_bf16 v[16:31], v[132:135], v[144:147], v[16:31]
	v_mfma_f32_32x32x16_bf16 v[0:15], v[132:135], v[148:151], v[0:15]
	s_xor_b32 s89, s89, 0x10000
	s_add_i32 s5, s5, 1
	s_add_u32 s2, s2, 0x80
	s_addc_u32 s3, s3, 0
	s_add_i32 s76, s8, s42
	s_cmpk_gt_i32 s76, 0x47f
	s_cselect_b64 s[50:51], -1, 0
	s_and_b64 vcc, exec, s[50:51]
	s_cbranch_vccnz .LBB0_1470
	s_mul_hi_i32 s2, s76, 0x38e38e39
	s_lshr_b32 s3, s2, 31
	s_ashr_i32 s2, s2, 1
	s_add_i32 s2, s2, s3
	s_mul_i32 s3, s2, -9
	s_lshl_b32 s2, s2, 8
	v_add_u32_e32 v129, s2, v194
	s_add_i32 s3, s3, s76
	v_min_i32_e32 v132, 0x7fff, v129
	v_add_u32_e32 v129, s2, v163
	s_lshl_b32 s3, s3, 8
	v_add_u32_e32 v128, s2, v193
	v_min_i32_e32 v136, 0x7fff, v129
	v_add_u32_e32 v129, s2, v196
	v_min_i32_e32 v128, 0x7fff, v128
	v_add_u32_e32 v130, s3, v193
	v_add_u32_e32 v134, s3, v194
	v_add_u32_e32 v138, s3, v163
	v_min_i32_e32 v140, 0x7fff, v129
	v_add_u32_e32 v142, s3, v196
	v_ashrrev_i32_e32 v143, 31, v142
	v_ashrrev_i32_e32 v141, 31, v140
	v_ashrrev_i32_e32 v139, 31, v138
	v_ashrrev_i32_e32 v137, 31, v136
	v_ashrrev_i32_e32 v135, 31, v134
	v_ashrrev_i32_e32 v133, 31, v132
	v_ashrrev_i32_e32 v131, 31, v130
	v_ashrrev_i32_e32 v129, 31, v128
	v_lshlrev_b64 v[142:143], 11, v[142:143]
	v_lshlrev_b64 v[140:141], 11, v[140:141]
	v_lshlrev_b64 v[138:139], 11, v[138:139]
	v_lshlrev_b64 v[136:137], 11, v[136:137]
	v_lshlrev_b64 v[134:135], 11, v[134:135]
	v_lshlrev_b64 v[132:133], 11, v[132:133]
	v_lshlrev_b64 v[130:131], 11, v[130:131]
	v_lshlrev_b64 v[128:129], 11, v[128:129]
	v_lshl_add_u64 v[156:157], v[164:165], 0, v[142:143]
	v_lshl_add_u64 v[152:153], v[166:167], 0, v[140:141]
	v_lshl_add_u64 v[148:149], v[164:165], 0, v[138:139]
	v_lshl_add_u64 v[144:145], v[166:167], 0, v[136:137]
	v_lshl_add_u64 v[140:141], v[164:165], 0, v[134:135]
	v_lshl_add_u64 v[136:137], v[166:167], 0, v[132:133]
	v_lshl_add_u64 v[132:133], v[164:165], 0, v[130:131]
	v_lshl_add_u64 v[128:129], v[166:167], 0, v[128:129]
	s_add_u32 m0, s88, 0
	v_lshl_add_u64 v[128:129], v[128:129], 0, s[92:93]
	v_xor_b32_e32 v128, v159, v128
	global_load_lds_dwordx4 v[128:129], off
	s_add_u32 m0, s88, 32768
	v_lshl_add_u64 v[132:133], v[132:133], 0, s[92:93]
	v_xor_b32_e32 v132, v159, v132
	global_load_lds_dwordx4 v[132:133], off
	s_add_u32 m0, s88, 8192
	v_lshl_add_u64 v[136:137], v[136:137], 0, s[92:93]
	v_xor_b32_e32 v136, v159, v136
	global_load_lds_dwordx4 v[136:137], off
	s_add_u32 m0, s88, 40960
	v_lshl_add_u64 v[140:141], v[140:141], 0, s[92:93]
	v_xor_b32_e32 v140, v159, v140
	global_load_lds_dwordx4 v[140:141], off
	s_add_u32 m0, s88, 16384
	v_lshl_add_u64 v[144:145], v[144:145], 0, s[92:93]
	v_xor_b32_e32 v144, v159, v144
	global_load_lds_dwordx4 v[144:145], off
	s_add_u32 m0, s88, 49152
	v_lshl_add_u64 v[148:149], v[148:149], 0, s[92:93]
	v_xor_b32_e32 v148, v159, v148
	global_load_lds_dwordx4 v[148:149], off
	s_add_u32 m0, s88, 24576
	v_lshl_add_u64 v[152:153], v[152:153], 0, s[92:93]
	v_xor_b32_e32 v152, v159, v152
	global_load_lds_dwordx4 v[152:153], off
	s_add_u32 m0, s88, 57344
	v_lshl_add_u64 v[156:157], v[156:157], 0, s[92:93]
	v_xor_b32_e32 v156, v159, v156
	global_load_lds_dwordx4 v[156:157], off
.LBB0_1470:
	ds_read_b128 v[128:131], v208
	ds_read_b128 v[136:139], v253
	ds_read_b128 v[132:135], v208 offset:4096
	ds_read_b128 v[140:143], v253 offset:4096
	ds_read_b128 v[144:147], v253 offset:8192
	ds_read_b128 v[148:151], v253 offset:12288
	s_waitcnt lgkmcnt(6)
	v_mfma_f32_32x32x16_bf16 v[112:127], v[188:191], v[216:219], v[112:127]
	v_mfma_f32_32x32x16_bf16 v[96:111], v[188:191], v[220:223], v[96:111]
	v_mfma_f32_32x32x16_bf16 v[80:95], v[188:191], v[224:227], v[80:95]
	v_mfma_f32_32x32x16_bf16 v[64:79], v[188:191], v[228:231], v[64:79]
	v_mfma_f32_32x32x16_bf16 v[48:63], v[212:215], v[216:219], v[48:63]
	v_mfma_f32_32x32x16_bf16 v[32:47], v[212:215], v[220:223], v[32:47]
	v_mfma_f32_32x32x16_bf16 v[16:31], v[212:215], v[224:227], v[16:31]
	v_mfma_f32_32x32x16_bf16 v[0:15], v[212:215], v[228:231], v[0:15]
	ds_read_b128 v[188:191], v209
	ds_read_b128 v[216:219], v254
	ds_read_b128 v[212:215], v209 offset:4096
	ds_read_b128 v[220:223], v254 offset:4096
	ds_read_b128 v[224:227], v254 offset:8192
	ds_read_b128 v[228:231], v254 offset:12288
	s_waitcnt lgkmcnt(6)
	v_mfma_f32_32x32x16_bf16 v[112:127], v[128:131], v[136:139], v[112:127]
	v_mfma_f32_32x32x16_bf16 v[96:111], v[128:131], v[140:143], v[96:111]
	v_mfma_f32_32x32x16_bf16 v[80:95], v[128:131], v[144:147], v[80:95]
	v_mfma_f32_32x32x16_bf16 v[64:79], v[128:131], v[148:151], v[64:79]
	v_mfma_f32_32x32x16_bf16 v[48:63], v[132:135], v[136:139], v[48:63]
	v_mfma_f32_32x32x16_bf16 v[32:47], v[132:135], v[140:143], v[32:47]
	v_mfma_f32_32x32x16_bf16 v[16:31], v[132:135], v[144:147], v[16:31]
	v_mfma_f32_32x32x16_bf16 v[0:15], v[132:135], v[148:151], v[0:15]
	ds_read_b128 v[128:131], v240
	ds_read_b128 v[136:139], v255
	ds_read_b128 v[132:135], v240 offset:4096
	ds_read_b128 v[140:143], v255 offset:4096
	ds_read_b128 v[144:147], v255 offset:8192
	ds_read_b128 v[148:151], v255 offset:12288
	s_waitcnt lgkmcnt(6)
	v_mfma_f32_32x32x16_bf16 v[112:127], v[188:191], v[216:219], v[112:127]
	v_mfma_f32_32x32x16_bf16 v[96:111], v[188:191], v[220:223], v[96:111]
	v_mfma_f32_32x32x16_bf16 v[80:95], v[188:191], v[224:227], v[80:95]
	v_mfma_f32_32x32x16_bf16 v[64:79], v[188:191], v[228:231], v[64:79]
	v_mfma_f32_32x32x16_bf16 v[48:63], v[212:215], v[216:219], v[48:63]
	v_mfma_f32_32x32x16_bf16 v[32:47], v[212:215], v[220:223], v[32:47]
	v_mfma_f32_32x32x16_bf16 v[16:31], v[212:215], v[224:227], v[16:31]
	v_mfma_f32_32x32x16_bf16 v[0:15], v[212:215], v[228:231], v[0:15]
	s_waitcnt vmcnt(0) lgkmcnt(0)
	s_barrier
	v_mfma_f32_32x32x16_bf16 v[112:127], v[128:131], v[136:139], v[112:127]
	v_mfma_f32_32x32x16_bf16 v[96:111], v[128:131], v[140:143], v[96:111]
	v_mfma_f32_32x32x16_bf16 v[80:95], v[128:131], v[144:147], v[80:95]
	v_mfma_f32_32x32x16_bf16 v[64:79], v[128:131], v[148:151], v[64:79]
	v_mfma_f32_32x32x16_bf16 v[48:63], v[132:135], v[136:139], v[48:63]
	v_mfma_f32_32x32x16_bf16 v[32:47], v[132:135], v[140:143], v[32:47]
	v_mfma_f32_32x32x16_bf16 v[16:31], v[132:135], v[144:147], v[16:31]
	v_mfma_f32_32x32x16_bf16 v[0:15], v[132:135], v[148:151], v[0:15]
	v_mbcnt_hi_u32_b32 v226, -1, v210
	v_and_b32_e32 v227, 31, v226
	v_lshrrev_b32_e32 v228, 5, v226
	v_lshlrev_b32_e32 v160, 3, v227
	v_lshlrev_b32_e32 v209, 2, v228
	s_lshr_b32 s90, s70, 6
	s_mul_i32 s91, s90, 0x1200
	s_add_u32 s91, s91, 0x12000
	v_mul_u32_u24_e32 v229, 0x240, v228
	v_lshl_add_u32 v229, v227, 1, v229
	v_add_u32_e32 v207, s91, v229
	v_lshrrev_b32_e32 v224, 3, v226
	v_and_b32_e32 v230, 7, v226
	v_lshlrev_b32_e32 v225, 4, v230
	v_mul_u32_u24_e32 v229, 0x90, v224
	v_add3_u32 v208, v229, v225, s91
	s_mul_i32 s92, s4, 9
	s_sub_u32 s93, s8, s92
	s_lshl_b32 s93, s93, 8
	s_lshl_b32 s92, s4, 8
	s_lshr_b32 s94, s90, 1
	s_lshl_b32 s94, s94, 6
	s_add_u32 s92, s92, s94
	s_and_b32 s94, s90, 1
	s_lshl_b32 s94, s94, 7
	s_add_u32 s93, s93, s94

.LBB0_2223:
	ds_read_b128 v[128:131], v238
	ds_read_b128 v[136:139], v253
	ds_read_b128 v[132:135], v238 offset:4096
	ds_read_b128 v[140:143], v253 offset:4096
	ds_read_b128 v[144:147], v253 offset:8192
	ds_read_b128 v[148:151], v253 offset:12288
	s_waitcnt lgkmcnt(6)
	v_mfma_f32_32x32x16_bf16 v[112:127], v[188:191], v[196:199], v[112:127]
	v_mfma_f32_32x32x16_bf16 v[96:111], v[188:191], v[200:203], v[96:111]
	v_mfma_f32_32x32x16_bf16 v[80:95], v[188:191], v[204:207], v[80:95]
	v_mfma_f32_32x32x16_bf16 v[64:79], v[188:191], v[226:229], v[64:79]
	v_mfma_f32_32x32x16_bf16 v[48:63], v[192:195], v[196:199], v[48:63]
	v_mfma_f32_32x32x16_bf16 v[32:47], v[192:195], v[200:203], v[32:47]
	v_mfma_f32_32x32x16_bf16 v[16:31], v[192:195], v[204:207], v[16:31]
	v_mfma_f32_32x32x16_bf16 v[0:15], v[192:195], v[226:229], v[0:15]
	ds_read_b128 v[188:191], v239
	ds_read_b128 v[196:199], v254
	ds_read_b128 v[192:195], v239 offset:4096
	ds_read_b128 v[200:203], v254 offset:4096
	ds_read_b128 v[204:207], v254 offset:8192
	ds_read_b128 v[226:229], v254 offset:12288
	s_waitcnt lgkmcnt(6)
	v_mfma_f32_32x32x16_bf16 v[112:127], v[128:131], v[136:139], v[112:127]
	v_mfma_f32_32x32x16_bf16 v[96:111], v[128:131], v[140:143], v[96:111]
	v_mfma_f32_32x32x16_bf16 v[80:95], v[128:131], v[144:147], v[80:95]
	v_mfma_f32_32x32x16_bf16 v[64:79], v[128:131], v[148:151], v[64:79]
	v_mfma_f32_32x32x16_bf16 v[48:63], v[132:135], v[136:139], v[48:63]
	v_mfma_f32_32x32x16_bf16 v[32:47], v[132:135], v[140:143], v[32:47]
	v_mfma_f32_32x32x16_bf16 v[16:31], v[132:135], v[144:147], v[16:31]
	v_mfma_f32_32x32x16_bf16 v[0:15], v[132:135], v[148:151], v[0:15]
	ds_read_b128 v[128:131], v240
	ds_read_b128 v[136:139], v255
	ds_read_b128 v[132:135], v240 offset:4096
	ds_read_b128 v[140:143], v255 offset:4096
	ds_read_b128 v[144:147], v255 offset:8192
	ds_read_b128 v[148:151], v255 offset:12288
	s_waitcnt lgkmcnt(6)
	v_mfma_f32_32x32x16_bf16 v[112:127], v[188:191], v[196:199], v[112:127]
	v_mfma_f32_32x32x16_bf16 v[96:111], v[188:191], v[200:203], v[96:111]
	v_mfma_f32_32x32x16_bf16 v[80:95], v[188:191], v[204:207], v[80:95]
	v_mfma_f32_32x32x16_bf16 v[64:79], v[188:191], v[226:229], v[64:79]
	v_mfma_f32_32x32x16_bf16 v[48:63], v[192:195], v[196:199], v[48:63]
	v_mfma_f32_32x32x16_bf16 v[32:47], v[192:195], v[200:203], v[32:47]
	v_mfma_f32_32x32x16_bf16 v[16:31], v[192:195], v[204:207], v[16:31]
	v_mfma_f32_32x32x16_bf16 v[0:15], v[192:195], v[226:229], v[0:15]
	s_waitcnt vmcnt(0) lgkmcnt(0)
	s_barrier
	v_mfma_f32_32x32x16_bf16 v[112:127], v[128:131], v[136:139], v[112:127]
	v_mfma_f32_32x32x16_bf16 v[96:111], v[128:131], v[140:143], v[96:111]
	v_mfma_f32_32x32x16_bf16 v[80:95], v[128:131], v[144:147], v[80:95]
	v_mfma_f32_32x32x16_bf16 v[64:79], v[128:131], v[148:151], v[64:79]
	v_mfma_f32_32x32x16_bf16 v[48:63], v[132:135], v[136:139], v[48:63]
	v_mfma_f32_32x32x16_bf16 v[32:47], v[132:135], v[140:143], v[32:47]
	v_mfma_f32_32x32x16_bf16 v[16:31], v[132:135], v[144:147], v[16:31]
	v_mfma_f32_32x32x16_bf16 v[0:15], v[132:135], v[148:151], v[0:15]
	s_lshl_b32 s2, s5, 8
	s_sub_i32 s2, s2, s6
	v_mov_b32_e32 v168, v214
	s_add_i32 s55, s4, s30
	s_or_b32 s26, s2, s31
	s_ashr_i32 s27, s26, 31
	s_load_dwordx2 s[24:25], s[0:1], 0x140
	v_ashrrev_i32_e32 v180, 3, v168
	v_and_b32_e32 v183, -4, v180
	v_add_u32_e32 v225, s55, v183
	v_add_u32_e32 v190, 8, v225
	v_min_i32_e32 v190, 0x7fff, v190
	v_ashrrev_i32_e32 v190, 12, v190
	v_add_u32_e32 v190, 8, v190
	v_mul_hi_i32_i24_e32 v191, 0x3000, v190
	v_mul_i32_i24_e32 v190, 0x3000, v190
	v_min_i32_e32 v184, 0x7fff, v225
	v_ashrrev_i32_e32 v184, 12, v184
	v_and_b32_e32 v182, 31, v168
	v_add_u32_e32 v184, 8, v184
	v_or_b32_e32 v180, s26, v182
	v_mul_hi_i32_i24_e32 v185, 0x3000, v184
	v_mul_i32_i24_e32 v184, 0x3000, v184
	v_ashrrev_i32_e32 v181, 31, v180
	s_waitcnt lgkmcnt(0)
	v_lshl_add_u64 v[184:185], s[24:25], 0, v[184:185]
	v_lshl_add_u64 v[184:185], v[184:185], 0, s[18:19]
	v_lshlrev_b64 v[180:181], 2, v[180:181]
	v_lshl_add_u64 v[196:197], v[184:185], 0, v[180:181]
	v_lshl_add_u64 v[186:187], s[24:25], 0, v[190:191]
	v_add_u32_e32 v188, 9, v225
	v_add_u32_e32 v190, 10, v225
	v_min_i32_e32 v188, 0x7fff, v188
	v_min_i32_e32 v190, 0x7fff, v190
	v_ashrrev_i32_e32 v188, 12, v188
	v_ashrrev_i32_e32 v190, 12, v190
	v_add_u32_e32 v188, 8, v188
	v_add_u32_e32 v190, 8, v190
	v_mul_hi_i32_i24_e32 v189, 0x3000, v188
	v_mul_i32_i24_e32 v188, 0x3000, v188
	v_mul_hi_i32_i24_e32 v191, 0x3000, v190
	v_mul_i32_i24_e32 v190, 0x3000, v190
	v_lshl_add_u64 v[188:189], s[24:25], 0, v[188:189]
	v_lshl_add_u64 v[190:191], s[24:25], 0, v[190:191]
	v_lshl_add_u64 v[186:187], v[186:187], 0, s[18:19]
	v_lshl_add_u64 v[188:189], v[188:189], 0, s[18:19]
	v_lshl_add_u64 v[190:191], v[190:191], 0, s[18:19]
	v_lshl_add_u64 v[206:207], v[186:187], 0, v[180:181]
	v_add_u32_e32 v208, 18, v225
	v_min_i32_e32 v208, 0x7fff, v208
	v_ashrrev_i32_e32 v208, 12, v208
	v_add_u32_e32 v208, 8, v208
	v_mul_hi_i32_i24_e32 v209, 0x3000, v208
	v_mul_i32_i24_e32 v208, 0x3000, v208
	v_lshl_add_u64 v[208:209], s[24:25], 0, v[208:209]
	v_lshl_add_u64 v[202:203], v[188:189], 0, v[180:181]
	v_lshl_add_u64 v[204:205], v[190:191], 0, v[180:181]
	global_load_dword v232, v[196:197], off
	global_load_dword v233, v[196:197], off offset:128
	global_load_dword v242, v[206:207], off
	global_load_dword v243, v[206:207], off offset:128
	global_load_dword v244, v[202:203], off
	global_load_dword v245, v[202:203], off offset:128
	global_load_dword v246, v[204:205], off
	global_load_dword v247, v[204:205], off offset:128
	v_add_u32_e32 v196, 17, v225
	v_min_i32_e32 v196, 0x7fff, v196
	v_ashrrev_i32_e32 v196, 12, v196
	v_add_u32_e32 v196, 8, v196
	v_mul_hi_i32_i24_e32 v197, 0x3000, v196
	v_mul_i32_i24_e32 v196, 0x3000, v196
	v_lshl_add_u64 v[196:197], s[24:25], 0, v[196:197]
	v_lshl_add_u64 v[196:197], v[196:197], 0, s[18:19]
	v_lshl_add_u64 v[206:207], v[196:197], 0, v[180:181]
	s_waitcnt vmcnt(7)
	s_nop 5
	v_mul_f32_e32 v112, v112, v232
	v_add_u32_e32 v192, 11, v225
	v_add_u32_e32 v194, 16, v225
	v_min_i32_e32 v192, 0x7fff, v192
	v_min_i32_e32 v194, 0x7fff, v194
	v_ashrrev_i32_e32 v192, 12, v192
	v_ashrrev_i32_e32 v194, 12, v194
	v_add_u32_e32 v192, 8, v192
	v_add_u32_e32 v194, 8, v194
	v_mul_hi_i32_i24_e32 v193, 0x3000, v192
	v_mul_i32_i24_e32 v192, 0x3000, v192
	v_mul_hi_i32_i24_e32 v195, 0x3000, v194
	v_mul_i32_i24_e32 v194, 0x3000, v194
	v_lshl_add_u64 v[192:193], s[24:25], 0, v[192:193]
	v_lshl_add_u64 v[194:195], s[24:25], 0, v[194:195]
	v_lshl_add_u64 v[192:193], v[192:193], 0, s[18:19]
	v_lshl_add_u64 v[194:195], v[194:195], 0, s[18:19]
	v_lshl_add_u64 v[202:203], v[192:193], 0, v[180:181]
	v_lshl_add_u64 v[204:205], v[194:195], 0, v[180:181]
	s_waitcnt vmcnt(6)
	s_nop 5
	v_mul_f32_e32 v96, v96, v233
	v_mul_f32_e32 v97, v97, v233
	v_lshl_add_u64 v[198:199], v[208:209], 0, s[18:19]
	v_lshl_add_u64 v[200:201], v[198:199], 0, v[180:181]
	global_load_dword v234, v[202:203], off
	global_load_dword v235, v[202:203], off offset:128
	global_load_dword v236, v[204:205], off
	global_load_dword v237, v[204:205], off offset:128
	global_load_dword v238, v[206:207], off
	global_load_dword v239, v[206:207], off offset:128
	global_load_dword v240, v[200:201], off
	global_load_dword v241, v[200:201], off offset:128
	v_add_u32_e32 v200, 19, v225
	v_add_u32_e32 v204, 25, v225
	v_add_u32_e32 v206, 26, v225
	v_min_i32_e32 v200, 0x7fff, v200
	v_add_u32_e32 v202, 24, v225
	v_min_i32_e32 v204, 0x7fff, v204
	v_min_i32_e32 v206, 0x7fff, v206
	v_ashrrev_i32_e32 v200, 12, v200
	v_min_i32_e32 v202, 0x7fff, v202
	v_ashrrev_i32_e32 v204, 12, v204
	v_ashrrev_i32_e32 v206, 12, v206
	v_add_u32_e32 v200, 8, v200
	v_ashrrev_i32_e32 v202, 12, v202
	v_add_u32_e32 v204, 8, v204
	v_add_u32_e32 v206, 8, v206
	v_mul_hi_i32_i24_e32 v201, 0x3000, v200
	v_mul_i32_i24_e32 v200, 0x3000, v200
	v_add_u32_e32 v202, 8, v202
	v_mul_hi_i32_i24_e32 v205, 0x3000, v204
	v_mul_i32_i24_e32 v204, 0x3000, v204
	v_mul_hi_i32_i24_e32 v207, 0x3000, v206
	v_mul_i32_i24_e32 v206, 0x3000, v206
	v_lshl_add_u64 v[200:201], s[24:25], 0, v[200:201]
	v_mul_hi_i32_i24_e32 v203, 0x3000, v202
	v_mul_i32_i24_e32 v202, 0x3000, v202
	v_lshl_add_u64 v[204:205], s[24:25], 0, v[204:205]
	v_lshl_add_u64 v[206:207], s[24:25], 0, v[206:207]
	v_lshl_add_u64 v[200:201], v[200:201], 0, s[18:19]
	v_lshl_add_u64 v[202:203], s[24:25], 0, v[202:203]
	v_lshl_add_u64 v[204:205], v[204:205], 0, s[18:19]
	v_lshl_add_u64 v[206:207], v[206:207], 0, s[18:19]
	v_lshl_add_u64 v[208:209], v[200:201], 0, v[180:181]
	v_lshl_add_u64 v[202:203], v[202:203], 0, s[18:19]
	v_lshl_add_u64 v[228:229], v[204:205], 0, v[180:181]
	v_lshl_add_u64 v[230:231], v[206:207], 0, v[180:181]
	v_lshl_add_u64 v[226:227], v[202:203], 0, v[180:181]
	global_load_dword v248, v[208:209], off
	global_load_dword v249, v[208:209], off offset:128
	global_load_dword v250, v[226:227], off
	global_load_dword v251, v[226:227], off offset:128
	global_load_dword v252, v[228:229], off
	s_nop 0
	global_load_dword v228, v[228:229], off offset:128
	s_nop 0
	global_load_dword v229, v[230:231], off
	s_nop 0
	global_load_dword v230, v[230:231], off offset:128
	v_add_u32_e32 v208, 27, v225
	v_min_i32_e32 v208, 0x7fff, v208
	v_ashrrev_i32_e32 v208, 12, v208
	v_add_u32_e32 v208, 8, v208
	v_mul_hi_i32_i24_e32 v209, 0x3000, v208
	v_mul_i32_i24_e32 v208, 0x3000, v208
	v_lshl_add_u64 v[208:209], s[24:25], 0, v[208:209]
	v_lshl_add_u64 v[208:209], v[208:209], 0, s[18:19]
	v_lshl_add_u64 v[226:227], v[208:209], 0, v[180:181]
	global_load_dword v225, v[226:227], off
	s_nop 0
	global_load_dword v226, v[226:227], off offset:128
	v_mad_u64_u32 v[160:161], s[2:3], v183, s36, v[182:183]
	v_lshl_add_u32 v162, v160, 2, s34
	ds_write2_b32 v162, v112, v96 offset1:32
	v_mul_f32_e32 v96, v113, v232
	ds_write2_b32 v162, v96, v97 offset0:68 offset1:100
	v_mul_f32_e32 v96, v114, v232
	v_mul_f32_e32 v97, v98, v233
	ds_write2_b32 v162, v96, v97 offset0:136 offset1:168
	v_mul_f32_e32 v96, v115, v232
	v_mul_f32_e32 v97, v99, v233
	ds_write2_b32 v162, v96, v97 offset0:204 offset1:236
	s_waitcnt vmcnt(23)
	v_mul_f32_e32 v96, v116, v242
	s_waitcnt vmcnt(22)
	v_mul_f32_e32 v97, v100, v243
	v_add_u32_e32 v115, 0x800, v162
	ds_write2_b32 v115, v96, v97 offset0:32 offset1:64
	s_waitcnt vmcnt(21)
	v_mul_f32_e32 v96, v117, v244
	s_waitcnt vmcnt(20)
	v_mul_f32_e32 v97, v101, v245
	ds_write2_b32 v115, v96, v97 offset0:100 offset1:132
	s_waitcnt vmcnt(19)
	v_mul_f32_e32 v96, v118, v246
	s_waitcnt vmcnt(18)
	v_mul_f32_e32 v97, v102, v247
	ds_write2_b32 v115, v96, v97 offset0:168 offset1:200
	v_add_u32_e32 v116, 0xa00, v162
	v_add_u32_e32 v117, 0x1000, v162
	s_waitcnt vmcnt(17)
	v_mul_f32_e32 v96, v119, v234
	s_waitcnt vmcnt(16)
	v_mul_f32_e32 v97, v103, v235
	ds_write2_b32 v116, v96, v97 offset0:108 offset1:140
	s_waitcnt vmcnt(15)
	v_mul_f32_e32 v96, v120, v236
	s_waitcnt vmcnt(14)
	v_mul_f32_e32 v97, v104, v237
	ds_write2_b32 v117, v96, v97 offset0:64 offset1:96
	s_waitcnt vmcnt(13)
	v_mul_f32_e32 v96, v121, v238
	s_waitcnt vmcnt(12)
	v_mul_f32_e32 v97, v105, v239
	ds_write2_b32 v117, v96, v97 offset0:132 offset1:164
	s_waitcnt vmcnt(11)
	v_mul_f32_e32 v96, v122, v240
	s_waitcnt vmcnt(10)
	v_mul_f32_e32 v97, v106, v241
	ds_write2_b32 v117, v96, v97 offset0:200 offset1:232
	v_add_u32_e32 v118, 0x1400, v162
	v_add_u32_e32 v119, 0x1800, v162
	v_ashrrev_i32_e32 v163, 4, v168
	v_and_b32_e32 v160, 15, v168
	v_add_u32_e32 v120, 0x1a00, v162
	v_mul_lo_u32 v164, v163, s37
	v_lshl_add_u32 v165, v160, 4, s34
	v_lshlrev_b32_e32 v168, 2, v160
	v_add_u32_e32 v160, s55, v163
	v_add_u32_e32 v121, 0x1c00, v162
	v_cmp_gt_i32_e32 vcc, s38, v160
	v_ashrrev_i32_e32 v161, 31, v160
	v_add_u32_e32 v114, v165, v164
	s_waitcnt vmcnt(9)
	v_mul_f32_e32 v96, v123, v248
	s_waitcnt vmcnt(8)
	v_mul_f32_e32 v97, v107, v249
	ds_write2_b32 v118, v96, v97 offset0:12 offset1:44
	s_waitcnt vmcnt(7)
	v_mul_f32_e32 v96, v124, v250
	s_waitcnt vmcnt(6)
	v_mul_f32_e32 v97, v108, v251
	ds_write2_b32 v119, v96, v97 offset0:96 offset1:128
	s_waitcnt vmcnt(5)
	v_mul_f32_e32 v96, v125, v252
	s_waitcnt vmcnt(4)
	v_mul_f32_e32 v97, v109, v228
	ds_write2_b32 v119, v96, v97 offset0:164 offset1:196
	s_waitcnt vmcnt(3)
	v_mul_f32_e32 v96, v126, v229
	s_waitcnt vmcnt(2)
	v_mul_f32_e32 v97, v110, v230
	ds_write2_b32 v120, v96, v97 offset0:104 offset1:136
	s_waitcnt vmcnt(1)
	v_mul_f32_e32 v96, v127, v225
	s_waitcnt vmcnt(0)
	v_mul_f32_e32 v97, v111, v226
	ds_write2_b32 v121, v96, v97 offset0:44 offset1:76
	v_or_b32_e32 v96, s26, v168
	v_mov_b32_e32 v97, s27
	v_add_u32_e32 v128, 0, v160
	v_ashrrev_i32_e32 v129, 31, v128
	v_lshlrev_b64 v[128:129], 12, v[128:129]
	v_lshl_add_u64 v[128:129], s[16:17], 0, v[128:129]
	v_lshl_add_u64 v[128:129], v[96:97], 2, v[128:129]
	global_load_dwordx4 v[128:131], v[128:129], off
	v_add_u32_e32 v132, 4, v160
	v_ashrrev_i32_e32 v133, 31, v132
	v_lshlrev_b64 v[132:133], 12, v[132:133]
	v_lshl_add_u64 v[132:133], s[16:17], 0, v[132:133]
	v_lshl_add_u64 v[132:133], v[96:97], 2, v[132:133]
	global_load_dwordx4 v[132:135], v[132:133], off
	v_add_u32_e32 v136, 8, v160
	v_ashrrev_i32_e32 v137, 31, v136
	v_lshlrev_b64 v[136:137], 12, v[136:137]
	v_lshl_add_u64 v[136:137], s[16:17], 0, v[136:137]
	v_lshl_add_u64 v[136:137], v[96:97], 2, v[136:137]
	global_load_dwordx4 v[136:139], v[136:137], off
	v_add_u32_e32 v140, 12, v160
	v_ashrrev_i32_e32 v141, 31, v140
	v_lshlrev_b64 v[140:141], 12, v[140:141]
	v_lshl_add_u64 v[140:141], s[16:17], 0, v[140:141]
	v_lshl_add_u64 v[140:141], v[96:97], 2, v[140:141]
	global_load_dwordx4 v[140:143], v[140:141], off
	v_add_u32_e32 v144, 16, v160
	v_ashrrev_i32_e32 v145, 31, v144
	v_lshlrev_b64 v[144:145], 12, v[144:145]
	v_lshl_add_u64 v[144:145], s[16:17], 0, v[144:145]
	v_lshl_add_u64 v[144:145], v[96:97], 2, v[144:145]
	global_load_dwordx4 v[144:147], v[144:145], off
	v_add_u32_e32 v148, 20, v160
	v_ashrrev_i32_e32 v149, 31, v148
	v_lshlrev_b64 v[148:149], 12, v[148:149]
	v_lshl_add_u64 v[148:149], s[16:17], 0, v[148:149]
	v_lshl_add_u64 v[148:149], v[96:97], 2, v[148:149]
	global_load_dwordx4 v[148:151], v[148:149], off
	v_add_u32_e32 v152, 24, v160
	v_ashrrev_i32_e32 v153, 31, v152
	v_lshlrev_b64 v[152:153], 12, v[152:153]
	v_lshl_add_u64 v[152:153], s[16:17], 0, v[152:153]
	v_lshl_add_u64 v[152:153], v[96:97], 2, v[152:153]
	global_load_dwordx4 v[152:155], v[152:153], off
	v_add_u32_e32 v156, 28, v160
	v_ashrrev_i32_e32 v157, 31, v156
	v_lshlrev_b64 v[156:157], 12, v[156:157]
	v_lshl_add_u64 v[156:157], s[16:17], 0, v[156:157]
	v_lshl_add_u64 v[156:157], v[96:97], 2, v[156:157]
	global_load_dwordx4 v[156:159], v[156:157], off
	s_and_saveexec_b64 s[2:3], vcc
	s_cbranch_execz .LBB0_2225
	v_lshlrev_b64 v[98:99], 12, v[160:161]
	v_lshl_add_u64 v[98:99], s[16:17], 0, v[98:99]
	v_lshl_add_u64 v[106:107], v[96:97], 2, v[98:99]
	ds_read_b128 v[102:105], v114
	s_waitcnt vmcnt(7) lgkmcnt(0)
	v_pk_add_f32 v[100:101], v[104:105], v[130:131]
	v_pk_add_f32 v[98:99], v[102:103], v[128:129]
	global_store_dwordx4 v[106:107], v[98:101], off

.Lip11_tile:
	s_mul_hi_u32 s35, s30, 0x92492493
	s_lshr_b32 s35, s35, 3
	s_mul_i32 s36, s35, 14
	s_sub_u32 s36, s30, s36
	s_sub_u32 s98, s30, 0x700
	s_cmpk_lt_u32 s30, 0x700
	s_cselect_b32 s36, s36, 14
	s_cselect_b32 s35, s35, s98
	s_waitcnt vmcnt(0)
	s_barrier
	s_add_u32 s20, s16, 128
	s_addc_u32 s21, s17, 0
	s_add_u32 s24, s18, 128
	s_addc_u32 s25, s19, 0
	s_add_u32 m0, s27, 65536
	s_nop 0
	global_load_lds_dwordx4 v192, s[20:21]
	s_add_u32 m0, s27, 98304
	s_nop 0
	global_load_lds_dwordx4 v192, s[24:25]
	s_add_u32 m0, s27, 73728
	s_nop 0
	global_load_lds_dwordx4 v194, s[20:21]
	s_add_u32 m0, s27, 106496
	s_nop 0
	global_load_lds_dwordx4 v194, s[24:25]
	s_add_u32 m0, s27, 81920
	s_nop 0
	global_load_lds_dwordx4 v196, s[20:21]
	s_add_u32 m0, s27, 114688
	s_nop 0
	global_load_lds_dwordx4 v196, s[24:25]
	s_add_u32 m0, s27, 90112
	s_nop 0
	global_load_lds_dwordx4 v198, s[20:21]
	s_add_u32 m0, s27, 122880
	s_nop 0
	global_load_lds_dwordx4 v198, s[24:25]
	s_cmp_eq_u32 s36, 14
	s_cbranch_scc1 .Lip11_light
	ds_read_b128 v[160:163], v184
	ds_read_b128 v[168:171], v188
	ds_read_b128 v[164:167], v184 offset:4096
	ds_read_b128 v[172:175], v188 offset:4096
	ds_read_b128 v[176:179], v188 offset:8192
	ds_read_b128 v[180:183], v188 offset:12288
	ds_read_b128 v[128:131], v185
	ds_read_b128 v[136:139], v189
	ds_read_b128 v[132:135], v185 offset:4096
	ds_read_b128 v[140:143], v189 offset:4096
	ds_read_b128 v[144:147], v189 offset:8192
	ds_read_b128 v[148:151], v189 offset:12288
	s_waitcnt lgkmcnt(6)
	v_mfma_f32_32x32x16_bf16 v[112:127], v[160:163], v[168:171], 0
	v_mfma_f32_32x32x16_bf16 v[96:111], v[160:163], v[172:175], 0
	v_mfma_f32_32x32x16_bf16 v[80:95], v[160:163], v[176:179], 0
	v_mfma_f32_32x32x16_bf16 v[64:79], v[160:163], v[180:183], 0
	v_mfma_f32_32x32x16_bf16 v[48:63], v[164:167], v[168:171], 0
	v_mfma_f32_32x32x16_bf16 v[32:47], v[164:167], v[172:175], 0
	v_mfma_f32_32x32x16_bf16 v[16:31], v[164:167], v[176:179], 0
	v_mfma_f32_32x32x16_bf16 v[0:15], v[164:167], v[180:183], 0
	ds_read_b128 v[160:163], v186
	ds_read_b128 v[168:171], v190
	ds_read_b128 v[164:167], v186 offset:4096
	ds_read_b128 v[172:175], v190 offset:4096
	ds_read_b128 v[176:179], v190 offset:8192
	ds_read_b128 v[180:183], v190 offset:12288
	s_waitcnt lgkmcnt(6)
	v_mfma_f32_32x32x16_bf16 v[112:127], v[128:131], v[136:139], v[112:127]
	v_mfma_f32_32x32x16_bf16 v[96:111], v[128:131], v[140:143], v[96:111]
	v_mfma_f32_32x32x16_bf16 v[80:95], v[128:131], v[144:147], v[80:95]
	v_mfma_f32_32x32x16_bf16 v[64:79], v[128:131], v[148:151], v[64:79]
	v_mfma_f32_32x32x16_bf16 v[48:63], v[132:135], v[136:139], v[48:63]
	v_mfma_f32_32x32x16_bf16 v[32:47], v[132:135], v[140:143], v[32:47]
	v_mfma_f32_32x32x16_bf16 v[16:31], v[132:135], v[144:147], v[16:31]
	v_mfma_f32_32x32x16_bf16 v[0:15], v[132:135], v[148:151], v[0:15]
	ds_read_b128 v[128:131], v187
	ds_read_b128 v[136:139], v191
	ds_read_b128 v[132:135], v187 offset:4096
	ds_read_b128 v[140:143], v191 offset:4096
	ds_read_b128 v[144:147], v191 offset:8192
	ds_read_b128 v[148:151], v191 offset:12288
	s_waitcnt lgkmcnt(6)
	v_mfma_f32_32x32x16_bf16 v[112:127], v[160:163], v[168:171], v[112:127]
	v_mfma_f32_32x32x16_bf16 v[96:111], v[160:163], v[172:175], v[96:111]
	v_mfma_f32_32x32x16_bf16 v[80:95], v[160:163], v[176:179], v[80:95]
	v_mfma_f32_32x32x16_bf16 v[64:79], v[160:163], v[180:183], v[64:79]
	v_mfma_f32_32x32x16_bf16 v[48:63], v[164:167], v[168:171], v[48:63]
	v_mfma_f32_32x32x16_bf16 v[32:47], v[164:167], v[172:175], v[32:47]
	v_mfma_f32_32x32x16_bf16 v[16:31], v[164:167], v[176:179], v[16:31]
	v_mfma_f32_32x32x16_bf16 v[0:15], v[164:167], v[180:183], v[0:15]
	s_waitcnt vmcnt(0) lgkmcnt(0)
	s_barrier
	ds_read_b128 v[160:163], v240
	ds_read_b128 v[168:171], v244
	ds_read_b128 v[164:167], v240 offset:4096
	ds_read_b128 v[172:175], v244 offset:4096
	ds_read_b128 v[176:179], v244 offset:8192
	ds_read_b128 v[180:183], v244 offset:12288
	s_add_u32 s20, s16, 256
	s_addc_u32 s21, s17, 0
	s_add_u32 s24, s18, 256
	s_addc_u32 s25, s19, 0
	s_add_u32 m0, s27, 0
	v_mfma_f32_32x32x16_bf16 v[112:127], v[128:131], v[136:139], v[112:127]
	global_load_lds_dwordx4 v192, s[20:21]
	s_add_u32 m0, s27, 32768
	v_mfma_f32_32x32x16_bf16 v[96:111], v[128:131], v[140:143], v[96:111]
	global_load_lds_dwordx4 v192, s[24:25]
	s_add_u32 m0, s27, 8192
	v_mfma_f32_32x32x16_bf16 v[80:95], v[128:131], v[144:147], v[80:95]
	global_load_lds_dwordx4 v194, s[20:21]
	s_add_u32 m0, s27, 40960
	v_mfma_f32_32x32x16_bf16 v[64:79], v[128:131], v[148:151], v[64:79]
	global_load_lds_dwordx4 v194, s[24:25]
	s_add_u32 m0, s27, 16384
	v_mfma_f32_32x32x16_bf16 v[48:63], v[132:135], v[136:139], v[48:63]
	global_load_lds_dwordx4 v196, s[20:21]
	s_add_u32 m0, s27, 49152
	v_mfma_f32_32x32x16_bf16 v[32:47], v[132:135], v[140:143], v[32:47]
	global_load_lds_dwordx4 v196, s[24:25]
	s_add_u32 m0, s27, 24576
	v_mfma_f32_32x32x16_bf16 v[16:31], v[132:135], v[144:147], v[16:31]
	global_load_lds_dwordx4 v198, s[20:21]
	s_add_u32 m0, s27, 57344
	v_mfma_f32_32x32x16_bf16 v[0:15], v[132:135], v[148:151], v[0:15]
	global_load_lds_dwordx4 v198, s[24:25]
	ds_read_b128 v[128:131], v241
	ds_read_b128 v[136:139], v245
	ds_read_b128 v[132:135], v241 offset:4096
	ds_read_b128 v[140:143], v245 offset:4096
	ds_read_b128 v[144:147], v245 offset:8192
	ds_read_b128 v[148:151], v245 offset:12288
	s_waitcnt lgkmcnt(6)
	v_mfma_f32_32x32x16_bf16 v[112:127], v[160:163], v[168:171], v[112:127]
	v_mfma_f32_32x32x16_bf16 v[96:111], v[160:163], v[172:175], v[96:111]
	v_mfma_f32_32x32x16_bf16 v[80:95], v[160:163], v[176:179], v[80:95]
	v_mfma_f32_32x32x16_bf16 v[64:79], v[160:163], v[180:183], v[64:79]
	v_mfma_f32_32x32x16_bf16 v[48:63], v[164:167], v[168:171], v[48:63]
	v_mfma_f32_32x32x16_bf16 v[32:47], v[164:167], v[172:175], v[32:47]
	v_mfma_f32_32x32x16_bf16 v[16:31], v[164:167], v[176:179], v[16:31]
	v_mfma_f32_32x32x16_bf16 v[0:15], v[164:167], v[180:183], v[0:15]
	ds_read_b128 v[160:163], v242
	ds_read_b128 v[168:171], v246
	ds_read_b128 v[164:167], v242 offset:4096
	ds_read_b128 v[172:175], v246 offset:4096
	ds_read_b128 v[176:179], v246 offset:8192
	ds_read_b128 v[180:183], v246 offset:12288
	s_waitcnt lgkmcnt(6)
	v_mfma_f32_32x32x16_bf16 v[112:127], v[128:131], v[136:139], v[112:127]
	v_mfma_f32_32x32x16_bf16 v[96:111], v[128:131], v[140:143], v[96:111]
	v_mfma_f32_32x32x16_bf16 v[80:95], v[128:131], v[144:147], v[80:95]
	v_mfma_f32_32x32x16_bf16 v[64:79], v[128:131], v[148:151], v[64:79]
	v_mfma_f32_32x32x16_bf16 v[48:63], v[132:135], v[136:139], v[48:63]
	v_mfma_f32_32x32x16_bf16 v[32:47], v[132:135], v[140:143], v[32:47]
	v_mfma_f32_32x32x16_bf16 v[16:31], v[132:135], v[144:147], v[16:31]
	v_mfma_f32_32x32x16_bf16 v[0:15], v[132:135], v[148:151], v[0:15]
	ds_read_b128 v[128:131], v243
	ds_read_b128 v[136:139], v247
	ds_read_b128 v[132:135], v243 offset:4096
	ds_read_b128 v[140:143], v247 offset:4096
	ds_read_b128 v[144:147], v247 offset:8192
	ds_read_b128 v[148:151], v247 offset:12288
	s_waitcnt lgkmcnt(6)
	v_mfma_f32_32x32x16_bf16 v[112:127], v[160:163], v[168:171], v[112:127]
	v_mfma_f32_32x32x16_bf16 v[96:111], v[160:163], v[172:175], v[96:111]
	v_mfma_f32_32x32x16_bf16 v[80:95], v[160:163], v[176:179], v[80:95]
	v_mfma_f32_32x32x16_bf16 v[64:79], v[160:163], v[180:183], v[64:79]
	v_mfma_f32_32x32x16_bf16 v[48:63], v[164:167], v[168:171], v[48:63]
	v_mfma_f32_32x32x16_bf16 v[32:47], v[164:167], v[172:175], v[32:47]
	v_mfma_f32_32x32x16_bf16 v[16:31], v[164:167], v[176:179], v[16:31]
	v_mfma_f32_32x32x16_bf16 v[0:15], v[164:167], v[180:183], v[0:15]
	s_waitcnt vmcnt(0) lgkmcnt(0)
	s_barrier
	ds_read_b128 v[160:163], v184
	ds_read_b128 v[168:171], v188
	ds_read_b128 v[164:167], v184 offset:4096
	ds_read_b128 v[172:175], v188 offset:4096
	ds_read_b128 v[176:179], v188 offset:8192
	ds_read_b128 v[180:183], v188 offset:12288
	s_add_u32 s20, s16, 384
	s_addc_u32 s21, s17, 0
	s_add_u32 s24, s18, 384
	s_addc_u32 s25, s19, 0
	s_add_u32 m0, s27, 65536
	v_mfma_f32_32x32x16_bf16 v[112:127], v[128:131], v[136:139], v[112:127]
	global_load_lds_dwordx4 v192, s[20:21]
	s_add_u32 m0, s27, 98304
	v_mfma_f32_32x32x16_bf16 v[96:111], v[128:131], v[140:143], v[96:111]
	global_load_lds_dwordx4 v192, s[24:25]
	s_add_u32 m0, s27, 73728
	v_mfma_f32_32x32x16_bf16 v[80:95], v[128:131], v[144:147], v[80:95]
	global_load_lds_dwordx4 v194, s[20:21]
	s_add_u32 m0, s27, 106496
	v_mfma_f32_32x32x16_bf16 v[64:79], v[128:131], v[148:151], v[64:79]
	global_load_lds_dwordx4 v194, s[24:25]
	s_add_u32 m0, s27, 81920
	v_mfma_f32_32x32x16_bf16 v[48:63], v[132:135], v[136:139], v[48:63]
	global_load_lds_dwordx4 v196, s[20:21]
	s_add_u32 m0, s27, 114688
	v_mfma_f32_32x32x16_bf16 v[32:47], v[132:135], v[140:143], v[32:47]
	global_load_lds_dwordx4 v196, s[24:25]
	s_add_u32 m0, s27, 90112
	v_mfma_f32_32x32x16_bf16 v[16:31], v[132:135], v[144:147], v[16:31]
	global_load_lds_dwordx4 v198, s[20:21]
	s_add_u32 m0, s27, 122880
	v_mfma_f32_32x32x16_bf16 v[0:15], v[132:135], v[148:151], v[0:15]
	global_load_lds_dwordx4 v198, s[24:25]
	ds_read_b128 v[128:131], v185
	ds_read_b128 v[136:139], v189
	ds_read_b128 v[132:135], v185 offset:4096
	ds_read_b128 v[140:143], v189 offset:4096
	ds_read_b128 v[144:147], v189 offset:8192
	ds_read_b128 v[148:151], v189 offset:12288
	s_waitcnt lgkmcnt(6)
	v_mfma_f32_32x32x16_bf16 v[112:127], v[160:163], v[168:171], v[112:127]
	v_mfma_f32_32x32x16_bf16 v[96:111], v[160:163], v[172:175], v[96:111]
	v_mfma_f32_32x32x16_bf16 v[80:95], v[160:163], v[176:179], v[80:95]
	v_mfma_f32_32x32x16_bf16 v[64:79], v[160:163], v[180:183], v[64:79]
	v_mfma_f32_32x32x16_bf16 v[48:63], v[164:167], v[168:171], v[48:63]
	v_mfma_f32_32x32x16_bf16 v[32:47], v[164:167], v[172:175], v[32:47]
	v_mfma_f32_32x32x16_bf16 v[16:31], v[164:167], v[176:179], v[16:31]
	v_mfma_f32_32x32x16_bf16 v[0:15], v[164:167], v[180:183], v[0:15]
	ds_read_b128 v[160:163], v186
	ds_read_b128 v[168:171], v190
	ds_read_b128 v[164:167], v186 offset:4096
	ds_read_b128 v[172:175], v190 offset:4096
	ds_read_b128 v[176:179], v190 offset:8192
	ds_read_b128 v[180:183], v190 offset:12288
	s_waitcnt lgkmcnt(6)
	v_mfma_f32_32x32x16_bf16 v[112:127], v[128:131], v[136:139], v[112:127]
	v_mfma_f32_32x32x16_bf16 v[96:111], v[128:131], v[140:143], v[96:111]
	v_mfma_f32_32x32x16_bf16 v[80:95], v[128:131], v[144:147], v[80:95]
	v_mfma_f32_32x32x16_bf16 v[64:79], v[128:131], v[148:151], v[64:79]
	v_mfma_f32_32x32x16_bf16 v[48:63], v[132:135], v[136:139], v[48:63]
	v_mfma_f32_32x32x16_bf16 v[32:47], v[132:135], v[140:143], v[32:47]
	v_mfma_f32_32x32x16_bf16 v[16:31], v[132:135], v[144:147], v[16:31]
	v_mfma_f32_32x32x16_bf16 v[0:15], v[132:135], v[148:151], v[0:15]
	ds_read_b128 v[128:131], v187
	ds_read_b128 v[136:139], v191
	ds_read_b128 v[132:135], v187 offset:4096
	ds_read_b128 v[140:143], v191 offset:4096
	ds_read_b128 v[144:147], v191 offset:8192
	ds_read_b128 v[148:151], v191 offset:12288
	s_waitcnt lgkmcnt(6)
	v_mfma_f32_32x32x16_bf16 v[112:127], v[160:163], v[168:171], v[112:127]
	v_mfma_f32_32x32x16_bf16 v[96:111], v[160:163], v[172:175], v[96:111]
	v_mfma_f32_32x32x16_bf16 v[80:95], v[160:163], v[176:179], v[80:95]
	v_mfma_f32_32x32x16_bf16 v[64:79], v[160:163], v[180:183], v[64:79]
	v_mfma_f32_32x32x16_bf16 v[48:63], v[164:167], v[168:171], v[48:63]
	v_mfma_f32_32x32x16_bf16 v[32:47], v[164:167], v[172:175], v[32:47]
	v_mfma_f32_32x32x16_bf16 v[16:31], v[164:167], v[176:179], v[16:31]
	v_mfma_f32_32x32x16_bf16 v[0:15], v[164:167], v[180:183], v[0:15]
	s_waitcnt vmcnt(0) lgkmcnt(0)
	s_barrier
	ds_read_b128 v[160:163], v240
	ds_read_b128 v[168:171], v244
	ds_read_b128 v[164:167], v240 offset:4096
	ds_read_b128 v[172:175], v244 offset:4096
	ds_read_b128 v[176:179], v244 offset:8192
	ds_read_b128 v[180:183], v244 offset:12288
	s_add_u32 s20, s16, 512
	s_addc_u32 s21, s17, 0
	s_add_u32 s24, s18, 512
	s_addc_u32 s25, s19, 0
	s_add_u32 m0, s27, 0
	v_mfma_f32_32x32x16_bf16 v[112:127], v[128:131], v[136:139], v[112:127]
	global_load_lds_dwordx4 v192, s[20:21]
	s_add_u32 m0, s27, 32768
	v_mfma_f32_32x32x16_bf16 v[96:111], v[128:131], v[140:143], v[96:111]
	global_load_lds_dwordx4 v192, s[24:25]
	s_add_u32 m0, s27, 8192
	v_mfma_f32_32x32x16_bf16 v[80:95], v[128:131], v[144:147], v[80:95]
	global_load_lds_dwordx4 v194, s[20:21]
	s_add_u32 m0, s27, 40960
	v_mfma_f32_32x32x16_bf16 v[64:79], v[128:131], v[148:151], v[64:79]
	global_load_lds_dwordx4 v194, s[24:25]
	s_add_u32 m0, s27, 16384
	v_mfma_f32_32x32x16_bf16 v[48:63], v[132:135], v[136:139], v[48:63]
	global_load_lds_dwordx4 v196, s[20:21]
	s_add_u32 m0, s27, 49152
	v_mfma_f32_32x32x16_bf16 v[32:47], v[132:135], v[140:143], v[32:47]
	global_load_lds_dwordx4 v196, s[24:25]
	s_add_u32 m0, s27, 24576
	v_mfma_f32_32x32x16_bf16 v[16:31], v[132:135], v[144:147], v[16:31]
	global_load_lds_dwordx4 v198, s[20:21]
	s_add_u32 m0, s27, 57344
	v_mfma_f32_32x32x16_bf16 v[0:15], v[132:135], v[148:151], v[0:15]
	global_load_lds_dwordx4 v198, s[24:25]
	ds_read_b128 v[128:131], v241
	ds_read_b128 v[136:139], v245
	ds_read_b128 v[132:135], v241 offset:4096
	ds_read_b128 v[140:143], v245 offset:4096
	ds_read_b128 v[144:147], v245 offset:8192
	ds_read_b128 v[148:151], v245 offset:12288
	s_waitcnt lgkmcnt(6)
	v_mfma_f32_32x32x16_bf16 v[112:127], v[160:163], v[168:171], v[112:127]
	v_mfma_f32_32x32x16_bf16 v[96:111], v[160:163], v[172:175], v[96:111]
	v_mfma_f32_32x32x16_bf16 v[80:95], v[160:163], v[176:179], v[80:95]
	v_mfma_f32_32x32x16_bf16 v[64:79], v[160:163], v[180:183], v[64:79]
	v_mfma_f32_32x32x16_bf16 v[48:63], v[164:167], v[168:171], v[48:63]
	v_mfma_f32_32x32x16_bf16 v[32:47], v[164:167], v[172:175], v[32:47]
	v_mfma_f32_32x32x16_bf16 v[16:31], v[164:167], v[176:179], v[16:31]
	v_mfma_f32_32x32x16_bf16 v[0:15], v[164:167], v[180:183], v[0:15]
	ds_read_b128 v[160:163], v242
	ds_read_b128 v[168:171], v246
	ds_read_b128 v[164:167], v242 offset:4096
	ds_read_b128 v[172:175], v246 offset:4096
	ds_read_b128 v[176:179], v246 offset:8192
	ds_read_b128 v[180:183], v246 offset:12288
	s_waitcnt lgkmcnt(6)
	v_mfma_f32_32x32x16_bf16 v[112:127], v[128:131], v[136:139], v[112:127]
	v_mfma_f32_32x32x16_bf16 v[96:111], v[128:131], v[140:143], v[96:111]
	v_mfma_f32_32x32x16_bf16 v[80:95], v[128:131], v[144:147], v[80:95]
	v_mfma_f32_32x32x16_bf16 v[64:79], v[128:131], v[148:151], v[64:79]
	v_mfma_f32_32x32x16_bf16 v[48:63], v[132:135], v[136:139], v[48:63]
	v_mfma_f32_32x32x16_bf16 v[32:47], v[132:135], v[140:143], v[32:47]
	v_mfma_f32_32x32x16_bf16 v[16:31], v[132:135], v[144:147], v[16:31]
	v_mfma_f32_32x32x16_bf16 v[0:15], v[132:135], v[148:151], v[0:15]
	ds_read_b128 v[128:131], v243
	ds_read_b128 v[136:139], v247
	ds_read_b128 v[132:135], v243 offset:4096
	ds_read_b128 v[140:143], v247 offset:4096
	ds_read_b128 v[144:147], v247 offset:8192
	ds_read_b128 v[148:151], v247 offset:12288
	s_waitcnt lgkmcnt(6)
	v_mfma_f32_32x32x16_bf16 v[112:127], v[160:163], v[168:171], v[112:127]
	v_mfma_f32_32x32x16_bf16 v[96:111], v[160:163], v[172:175], v[96:111]
	v_mfma_f32_32x32x16_bf16 v[80:95], v[160:163], v[176:179], v[80:95]
	v_mfma_f32_32x32x16_bf16 v[64:79], v[160:163], v[180:183], v[64:79]
	v_mfma_f32_32x32x16_bf16 v[48:63], v[164:167], v[168:171], v[48:63]
	v_mfma_f32_32x32x16_bf16 v[32:47], v[164:167], v[172:175], v[32:47]
	v_mfma_f32_32x32x16_bf16 v[16:31], v[164:167], v[176:179], v[16:31]
	v_mfma_f32_32x32x16_bf16 v[0:15], v[164:167], v[180:183], v[0:15]
	s_waitcnt vmcnt(0) lgkmcnt(0)
	s_barrier
	ds_read_b128 v[160:163], v184
	ds_read_b128 v[168:171], v188
	ds_read_b128 v[164:167], v184 offset:4096
	ds_read_b128 v[172:175], v188 offset:4096
	ds_read_b128 v[176:179], v188 offset:8192
	ds_read_b128 v[180:183], v188 offset:12288
	s_add_u32 s20, s16, 640
	s_addc_u32 s21, s17, 0
	s_add_u32 s24, s18, 640
	s_addc_u32 s25, s19, 0
	s_add_u32 m0, s27, 65536
	v_mfma_f32_32x32x16_bf16 v[112:127], v[128:131], v[136:139], v[112:127]
	global_load_lds_dwordx4 v192, s[20:21]
	s_add_u32 m0, s27, 98304
	v_mfma_f32_32x32x16_bf16 v[96:111], v[128:131], v[140:143], v[96:111]
	global_load_lds_dwordx4 v192, s[24:25]
	s_add_u32 m0, s27, 73728
	v_mfma_f32_32x32x16_bf16 v[80:95], v[128:131], v[144:147], v[80:95]
	global_load_lds_dwordx4 v194, s[20:21]
	s_add_u32 m0, s27, 106496
	v_mfma_f32_32x32x16_bf16 v[64:79], v[128:131], v[148:151], v[64:79]
	global_load_lds_dwordx4 v194, s[24:25]
	s_add_u32 m0, s27, 81920
	v_mfma_f32_32x32x16_bf16 v[48:63], v[132:135], v[136:139], v[48:63]
	global_load_lds_dwordx4 v196, s[20:21]
	s_add_u32 m0, s27, 114688
	v_mfma_f32_32x32x16_bf16 v[32:47], v[132:135], v[140:143], v[32:47]
	global_load_lds_dwordx4 v196, s[24:25]
	s_add_u32 m0, s27, 90112
	v_mfma_f32_32x32x16_bf16 v[16:31], v[132:135], v[144:147], v[16:31]
	global_load_lds_dwordx4 v198, s[20:21]
	s_add_u32 m0, s27, 122880
	v_mfma_f32_32x32x16_bf16 v[0:15], v[132:135], v[148:151], v[0:15]
	global_load_lds_dwordx4 v198, s[24:25]
	ds_read_b128 v[128:131], v185
	ds_read_b128 v[136:139], v189
	ds_read_b128 v[132:135], v185 offset:4096
	ds_read_b128 v[140:143], v189 offset:4096
	ds_read_b128 v[144:147], v189 offset:8192
	ds_read_b128 v[148:151], v189 offset:12288
	s_waitcnt lgkmcnt(6)
	v_mfma_f32_32x32x16_bf16 v[112:127], v[160:163], v[168:171], v[112:127]
	v_mfma_f32_32x32x16_bf16 v[96:111], v[160:163], v[172:175], v[96:111]
	v_mfma_f32_32x32x16_bf16 v[80:95], v[160:163], v[176:179], v[80:95]
	v_mfma_f32_32x32x16_bf16 v[64:79], v[160:163], v[180:183], v[64:79]
	v_mfma_f32_32x32x16_bf16 v[48:63], v[164:167], v[168:171], v[48:63]
	v_mfma_f32_32x32x16_bf16 v[32:47], v[164:167], v[172:175], v[32:47]
	v_mfma_f32_32x32x16_bf16 v[16:31], v[164:167], v[176:179], v[16:31]
	v_mfma_f32_32x32x16_bf16 v[0:15], v[164:167], v[180:183], v[0:15]
	ds_read_b128 v[160:163], v186
	ds_read_b128 v[168:171], v190
	ds_read_b128 v[164:167], v186 offset:4096
	ds_read_b128 v[172:175], v190 offset:4096
	ds_read_b128 v[176:179], v190 offset:8192
	ds_read_b128 v[180:183], v190 offset:12288
	s_waitcnt lgkmcnt(6)
	v_mfma_f32_32x32x16_bf16 v[112:127], v[128:131], v[136:139], v[112:127]
	v_mfma_f32_32x32x16_bf16 v[96:111], v[128:131], v[140:143], v[96:111]
	v_mfma_f32_32x32x16_bf16 v[80:95], v[128:131], v[144:147], v[80:95]
	v_mfma_f32_32x32x16_bf16 v[64:79], v[128:131], v[148:151], v[64:79]
	v_mfma_f32_32x32x16_bf16 v[48:63], v[132:135], v[136:139], v[48:63]
	v_mfma_f32_32x32x16_bf16 v[32:47], v[132:135], v[140:143], v[32:47]
	v_mfma_f32_32x32x16_bf16 v[16:31], v[132:135], v[144:147], v[16:31]
	v_mfma_f32_32x32x16_bf16 v[0:15], v[132:135], v[148:151], v[0:15]
	ds_read_b128 v[128:131], v187
	ds_read_b128 v[136:139], v191
	ds_read_b128 v[132:135], v187 offset:4096
	ds_read_b128 v[140:143], v191 offset:4096
	ds_read_b128 v[144:147], v191 offset:8192
	ds_read_b128 v[148:151], v191 offset:12288
	s_waitcnt lgkmcnt(6)
	v_mfma_f32_32x32x16_bf16 v[112:127], v[160:163], v[168:171], v[112:127]
	v_mfma_f32_32x32x16_bf16 v[96:111], v[160:163], v[172:175], v[96:111]
	v_mfma_f32_32x32x16_bf16 v[80:95], v[160:163], v[176:179], v[80:95]
	v_mfma_f32_32x32x16_bf16 v[64:79], v[160:163], v[180:183], v[64:79]
	v_mfma_f32_32x32x16_bf16 v[48:63], v[164:167], v[168:171], v[48:63]
	v_mfma_f32_32x32x16_bf16 v[32:47], v[164:167], v[172:175], v[32:47]
	v_mfma_f32_32x32x16_bf16 v[16:31], v[164:167], v[176:179], v[16:31]
	v_mfma_f32_32x32x16_bf16 v[0:15], v[164:167], v[180:183], v[0:15]
	s_waitcnt vmcnt(0) lgkmcnt(0)
	s_barrier
	ds_read_b128 v[160:163], v240
	ds_read_b128 v[168:171], v244
	ds_read_b128 v[164:167], v240 offset:4096
	ds_read_b128 v[172:175], v244 offset:4096
	ds_read_b128 v[176:179], v244 offset:8192
	ds_read_b128 v[180:183], v244 offset:12288
	s_add_u32 s20, s16, 768
	s_addc_u32 s21, s17, 0
	s_add_u32 s24, s18, 768
	s_addc_u32 s25, s19, 0
	s_add_u32 m0, s27, 0
	v_mfma_f32_32x32x16_bf16 v[112:127], v[128:131], v[136:139], v[112:127]
	global_load_lds_dwordx4 v192, s[20:21]
	s_add_u32 m0, s27, 32768
	v_mfma_f32_32x32x16_bf16 v[96:111], v[128:131], v[140:143], v[96:111]
	global_load_lds_dwordx4 v192, s[24:25]
	s_add_u32 m0, s27, 8192
	v_mfma_f32_32x32x16_bf16 v[80:95], v[128:131], v[144:147], v[80:95]
	global_load_lds_dwordx4 v194, s[20:21]
	s_add_u32 m0, s27, 40960
	v_mfma_f32_32x32x16_bf16 v[64:79], v[128:131], v[148:151], v[64:79]
	global_load_lds_dwordx4 v194, s[24:25]
	s_add_u32 m0, s27, 16384
	v_mfma_f32_32x32x16_bf16 v[48:63], v[132:135], v[136:139], v[48:63]
	global_load_lds_dwordx4 v196, s[20:21]
	s_add_u32 m0, s27, 49152
	v_mfma_f32_32x32x16_bf16 v[32:47], v[132:135], v[140:143], v[32:47]
	global_load_lds_dwordx4 v196, s[24:25]
	s_add_u32 m0, s27, 24576
	v_mfma_f32_32x32x16_bf16 v[16:31], v[132:135], v[144:147], v[16:31]
	global_load_lds_dwordx4 v198, s[20:21]
	s_add_u32 m0, s27, 57344
	v_mfma_f32_32x32x16_bf16 v[0:15], v[132:135], v[148:151], v[0:15]
	global_load_lds_dwordx4 v198, s[24:25]
	ds_read_b128 v[128:131], v241
	ds_read_b128 v[136:139], v245
	ds_read_b128 v[132:135], v241 offset:4096
	ds_read_b128 v[140:143], v245 offset:4096
	ds_read_b128 v[144:147], v245 offset:8192
	ds_read_b128 v[148:151], v245 offset:12288
	s_waitcnt lgkmcnt(6)
	v_mfma_f32_32x32x16_bf16 v[112:127], v[160:163], v[168:171], v[112:127]
	v_mfma_f32_32x32x16_bf16 v[96:111], v[160:163], v[172:175], v[96:111]
	v_mfma_f32_32x32x16_bf16 v[80:95], v[160:163], v[176:179], v[80:95]
	v_mfma_f32_32x32x16_bf16 v[64:79], v[160:163], v[180:183], v[64:79]
	v_mfma_f32_32x32x16_bf16 v[48:63], v[164:167], v[168:171], v[48:63]
	v_mfma_f32_32x32x16_bf16 v[32:47], v[164:167], v[172:175], v[32:47]
	v_mfma_f32_32x32x16_bf16 v[16:31], v[164:167], v[176:179], v[16:31]
	v_mfma_f32_32x32x16_bf16 v[0:15], v[164:167], v[180:183], v[0:15]
	ds_read_b128 v[160:163], v242
	ds_read_b128 v[168:171], v246
	ds_read_b128 v[164:167], v242 offset:4096
	ds_read_b128 v[172:175], v246 offset:4096
	ds_read_b128 v[176:179], v246 offset:8192
	ds_read_b128 v[180:183], v246 offset:12288
	s_waitcnt lgkmcnt(6)
	v_mfma_f32_32x32x16_bf16 v[112:127], v[128:131], v[136:139], v[112:127]
	v_mfma_f32_32x32x16_bf16 v[96:111], v[128:131], v[140:143], v[96:111]
	v_mfma_f32_32x32x16_bf16 v[80:95], v[128:131], v[144:147], v[80:95]
	v_mfma_f32_32x32x16_bf16 v[64:79], v[128:131], v[148:151], v[64:79]
	v_mfma_f32_32x32x16_bf16 v[48:63], v[132:135], v[136:139], v[48:63]
	v_mfma_f32_32x32x16_bf16 v[32:47], v[132:135], v[140:143], v[32:47]
	v_mfma_f32_32x32x16_bf16 v[16:31], v[132:135], v[144:147], v[16:31]
	v_mfma_f32_32x32x16_bf16 v[0:15], v[132:135], v[148:151], v[0:15]
	ds_read_b128 v[128:131], v243
	ds_read_b128 v[136:139], v247
	ds_read_b128 v[132:135], v243 offset:4096
	ds_read_b128 v[140:143], v247 offset:4096
	ds_read_b128 v[144:147], v247 offset:8192
	ds_read_b128 v[148:151], v247 offset:12288
	s_waitcnt lgkmcnt(6)
	v_mfma_f32_32x32x16_bf16 v[112:127], v[160:163], v[168:171], v[112:127]
	v_mfma_f32_32x32x16_bf16 v[96:111], v[160:163], v[172:175], v[96:111]
	v_mfma_f32_32x32x16_bf16 v[80:95], v[160:163], v[176:179], v[80:95]
	v_mfma_f32_32x32x16_bf16 v[64:79], v[160:163], v[180:183], v[64:79]
	v_mfma_f32_32x32x16_bf16 v[48:63], v[164:167], v[168:171], v[48:63]
	v_mfma_f32_32x32x16_bf16 v[32:47], v[164:167], v[172:175], v[32:47]
	v_mfma_f32_32x32x16_bf16 v[16:31], v[164:167], v[176:179], v[16:31]
	v_mfma_f32_32x32x16_bf16 v[0:15], v[164:167], v[180:183], v[0:15]
	s_waitcnt vmcnt(0) lgkmcnt(0)
	s_barrier
	ds_read_b128 v[160:163], v184
	ds_read_b128 v[168:171], v188
	ds_read_b128 v[164:167], v184 offset:4096
	ds_read_b128 v[172:175], v188 offset:4096
	ds_read_b128 v[176:179], v188 offset:8192
	ds_read_b128 v[180:183], v188 offset:12288
	s_add_u32 s20, s16, 896
	s_addc_u32 s21, s17, 0
	s_add_u32 s24, s18, 896
	s_addc_u32 s25, s19, 0
	s_add_u32 m0, s27, 65536
	v_mfma_f32_32x32x16_bf16 v[112:127], v[128:131], v[136:139], v[112:127]
	global_load_lds_dwordx4 v192, s[20:21]
	s_add_u32 m0, s27, 98304
	v_mfma_f32_32x32x16_bf16 v[96:111], v[128:131], v[140:143], v[96:111]
	global_load_lds_dwordx4 v192, s[24:25]
	s_add_u32 m0, s27, 73728
	v_mfma_f32_32x32x16_bf16 v[80:95], v[128:131], v[144:147], v[80:95]
	global_load_lds_dwordx4 v194, s[20:21]
	s_add_u32 m0, s27, 106496
	v_mfma_f32_32x32x16_bf16 v[64:79], v[128:131], v[148:151], v[64:79]
	global_load_lds_dwordx4 v194, s[24:25]
	s_add_u32 m0, s27, 81920
	v_mfma_f32_32x32x16_bf16 v[48:63], v[132:135], v[136:139], v[48:63]
	global_load_lds_dwordx4 v196, s[20:21]
	s_add_u32 m0, s27, 114688
	v_mfma_f32_32x32x16_bf16 v[32:47], v[132:135], v[140:143], v[32:47]
	global_load_lds_dwordx4 v196, s[24:25]
	s_add_u32 m0, s27, 90112
	v_mfma_f32_32x32x16_bf16 v[16:31], v[132:135], v[144:147], v[16:31]
	global_load_lds_dwordx4 v198, s[20:21]
	s_add_u32 m0, s27, 122880
	v_mfma_f32_32x32x16_bf16 v[0:15], v[132:135], v[148:151], v[0:15]
	global_load_lds_dwordx4 v198, s[24:25]
	ds_read_b128 v[128:131], v185
	ds_read_b128 v[136:139], v189
	ds_read_b128 v[132:135], v185 offset:4096
	ds_read_b128 v[140:143], v189 offset:4096
	ds_read_b128 v[144:147], v189 offset:8192
	ds_read_b128 v[148:151], v189 offset:12288
	s_waitcnt lgkmcnt(6)
	v_mfma_f32_32x32x16_bf16 v[112:127], v[160:163], v[168:171], v[112:127]
	v_mfma_f32_32x32x16_bf16 v[96:111], v[160:163], v[172:175], v[96:111]
	v_mfma_f32_32x32x16_bf16 v[80:95], v[160:163], v[176:179], v[80:95]
	v_mfma_f32_32x32x16_bf16 v[64:79], v[160:163], v[180:183], v[64:79]
	v_mfma_f32_32x32x16_bf16 v[48:63], v[164:167], v[168:171], v[48:63]
	v_mfma_f32_32x32x16_bf16 v[32:47], v[164:167], v[172:175], v[32:47]
	v_mfma_f32_32x32x16_bf16 v[16:31], v[164:167], v[176:179], v[16:31]
	v_mfma_f32_32x32x16_bf16 v[0:15], v[164:167], v[180:183], v[0:15]
	ds_read_b128 v[160:163], v186
	ds_read_b128 v[168:171], v190
	ds_read_b128 v[164:167], v186 offset:4096
	ds_read_b128 v[172:175], v190 offset:4096
	ds_read_b128 v[176:179], v190 offset:8192
	ds_read_b128 v[180:183], v190 offset:12288
	s_waitcnt lgkmcnt(6)
	v_mfma_f32_32x32x16_bf16 v[112:127], v[128:131], v[136:139], v[112:127]
	v_mfma_f32_32x32x16_bf16 v[96:111], v[128:131], v[140:143], v[96:111]
	v_mfma_f32_32x32x16_bf16 v[80:95], v[128:131], v[144:147], v[80:95]
	v_mfma_f32_32x32x16_bf16 v[64:79], v[128:131], v[148:151], v[64:79]
	v_mfma_f32_32x32x16_bf16 v[48:63], v[132:135], v[136:139], v[48:63]
	v_mfma_f32_32x32x16_bf16 v[32:47], v[132:135], v[140:143], v[32:47]
	v_mfma_f32_32x32x16_bf16 v[16:31], v[132:135], v[144:147], v[16:31]
	v_mfma_f32_32x32x16_bf16 v[0:15], v[132:135], v[148:151], v[0:15]
	ds_read_b128 v[128:131], v187
	ds_read_b128 v[136:139], v191
	ds_read_b128 v[132:135], v187 offset:4096
	ds_read_b128 v[140:143], v191 offset:4096
	ds_read_b128 v[144:147], v191 offset:8192
	ds_read_b128 v[148:151], v191 offset:12288
	s_waitcnt lgkmcnt(6)
	v_mfma_f32_32x32x16_bf16 v[112:127], v[160:163], v[168:171], v[112:127]
	v_mfma_f32_32x32x16_bf16 v[96:111], v[160:163], v[172:175], v[96:111]
	v_mfma_f32_32x32x16_bf16 v[80:95], v[160:163], v[176:179], v[80:95]
	v_mfma_f32_32x32x16_bf16 v[64:79], v[160:163], v[180:183], v[64:79]
	v_mfma_f32_32x32x16_bf16 v[48:63], v[164:167], v[168:171], v[48:63]
	v_mfma_f32_32x32x16_bf16 v[32:47], v[164:167], v[172:175], v[32:47]
	v_mfma_f32_32x32x16_bf16 v[16:31], v[164:167], v[176:179], v[16:31]
	v_mfma_f32_32x32x16_bf16 v[0:15], v[164:167], v[180:183], v[0:15]
	s_waitcnt vmcnt(0) lgkmcnt(0)
	s_barrier
	ds_read_b128 v[160:163], v240
	ds_read_b128 v[168:171], v244
	ds_read_b128 v[164:167], v240 offset:4096
	ds_read_b128 v[172:175], v244 offset:4096
	ds_read_b128 v[176:179], v244 offset:8192
	ds_read_b128 v[180:183], v244 offset:12288
	s_add_u32 s20, s16, 1024
	s_addc_u32 s21, s17, 0
	s_add_u32 s24, s18, 1024
	s_addc_u32 s25, s19, 0
	s_add_u32 m0, s27, 0
	v_mfma_f32_32x32x16_bf16 v[112:127], v[128:131], v[136:139], v[112:127]
	global_load_lds_dwordx4 v192, s[20:21]
	s_add_u32 m0, s27, 32768
	v_mfma_f32_32x32x16_bf16 v[96:111], v[128:131], v[140:143], v[96:111]
	global_load_lds_dwordx4 v192, s[24:25]
	s_add_u32 m0, s27, 8192
	v_mfma_f32_32x32x16_bf16 v[80:95], v[128:131], v[144:147], v[80:95]
	global_load_lds_dwordx4 v194, s[20:21]
	s_add_u32 m0, s27, 40960
	v_mfma_f32_32x32x16_bf16 v[64:79], v[128:131], v[148:151], v[64:79]
	global_load_lds_dwordx4 v194, s[24:25]
	s_add_u32 m0, s27, 16384
	v_mfma_f32_32x32x16_bf16 v[48:63], v[132:135], v[136:139], v[48:63]
	global_load_lds_dwordx4 v196, s[20:21]
	s_add_u32 m0, s27, 49152
	v_mfma_f32_32x32x16_bf16 v[32:47], v[132:135], v[140:143], v[32:47]
	global_load_lds_dwordx4 v196, s[24:25]
	s_add_u32 m0, s27, 24576
	v_mfma_f32_32x32x16_bf16 v[16:31], v[132:135], v[144:147], v[16:31]
	global_load_lds_dwordx4 v198, s[20:21]
	s_add_u32 m0, s27, 57344
	v_mfma_f32_32x32x16_bf16 v[0:15], v[132:135], v[148:151], v[0:15]
	global_load_lds_dwordx4 v198, s[24:25]
	ds_read_b128 v[128:131], v241
	ds_read_b128 v[136:139], v245
	ds_read_b128 v[132:135], v241 offset:4096
	ds_read_b128 v[140:143], v245 offset:4096
	ds_read_b128 v[144:147], v245 offset:8192
	ds_read_b128 v[148:151], v245 offset:12288
	s_waitcnt lgkmcnt(6)
	v_mfma_f32_32x32x16_bf16 v[112:127], v[160:163], v[168:171], v[112:127]
	v_mfma_f32_32x32x16_bf16 v[96:111], v[160:163], v[172:175], v[96:111]
	v_mfma_f32_32x32x16_bf16 v[80:95], v[160:163], v[176:179], v[80:95]
	v_mfma_f32_32x32x16_bf16 v[64:79], v[160:163], v[180:183], v[64:79]
	v_mfma_f32_32x32x16_bf16 v[48:63], v[164:167], v[168:171], v[48:63]
	v_mfma_f32_32x32x16_bf16 v[32:47], v[164:167], v[172:175], v[32:47]
	v_mfma_f32_32x32x16_bf16 v[16:31], v[164:167], v[176:179], v[16:31]
	v_mfma_f32_32x32x16_bf16 v[0:15], v[164:167], v[180:183], v[0:15]
	ds_read_b128 v[160:163], v242
	ds_read_b128 v[168:171], v246
	ds_read_b128 v[164:167], v242 offset:4096
	ds_read_b128 v[172:175], v246 offset:4096
	ds_read_b128 v[176:179], v246 offset:8192
	ds_read_b128 v[180:183], v246 offset:12288
	s_waitcnt lgkmcnt(6)
	v_mfma_f32_32x32x16_bf16 v[112:127], v[128:131], v[136:139], v[112:127]
	v_mfma_f32_32x32x16_bf16 v[96:111], v[128:131], v[140:143], v[96:111]
	v_mfma_f32_32x32x16_bf16 v[80:95], v[128:131], v[144:147], v[80:95]
	v_mfma_f32_32x32x16_bf16 v[64:79], v[128:131], v[148:151], v[64:79]
	v_mfma_f32_32x32x16_bf16 v[48:63], v[132:135], v[136:139], v[48:63]
	v_mfma_f32_32x32x16_bf16 v[32:47], v[132:135], v[140:143], v[32:47]
	v_mfma_f32_32x32x16_bf16 v[16:31], v[132:135], v[144:147], v[16:31]
	v_mfma_f32_32x32x16_bf16 v[0:15], v[132:135], v[148:151], v[0:15]
	ds_read_b128 v[128:131], v243
	ds_read_b128 v[136:139], v247
	ds_read_b128 v[132:135], v243 offset:4096
	ds_read_b128 v[140:143], v247 offset:4096
	ds_read_b128 v[144:147], v247 offset:8192
	ds_read_b128 v[148:151], v247 offset:12288
	s_waitcnt lgkmcnt(6)
	v_mfma_f32_32x32x16_bf16 v[112:127], v[160:163], v[168:171], v[112:127]
	v_mfma_f32_32x32x16_bf16 v[96:111], v[160:163], v[172:175], v[96:111]
	v_mfma_f32_32x32x16_bf16 v[80:95], v[160:163], v[176:179], v[80:95]
	v_mfma_f32_32x32x16_bf16 v[64:79], v[160:163], v[180:183], v[64:79]
	v_mfma_f32_32x32x16_bf16 v[48:63], v[164:167], v[168:171], v[48:63]
	v_mfma_f32_32x32x16_bf16 v[32:47], v[164:167], v[172:175], v[32:47]
	v_mfma_f32_32x32x16_bf16 v[16:31], v[164:167], v[176:179], v[16:31]
	v_mfma_f32_32x32x16_bf16 v[0:15], v[164:167], v[180:183], v[0:15]
	s_waitcnt vmcnt(0) lgkmcnt(0)
	s_barrier
	ds_read_b128 v[160:163], v184
	ds_read_b128 v[168:171], v188
	ds_read_b128 v[164:167], v184 offset:4096
	ds_read_b128 v[172:175], v188 offset:4096
	ds_read_b128 v[176:179], v188 offset:8192
	ds_read_b128 v[180:183], v188 offset:12288
	s_add_u32 s20, s16, 1152
	s_addc_u32 s21, s17, 0
	s_add_u32 s24, s18, 1152
	s_addc_u32 s25, s19, 0
	s_add_u32 m0, s27, 65536
	v_mfma_f32_32x32x16_bf16 v[112:127], v[128:131], v[136:139], v[112:127]
	global_load_lds_dwordx4 v192, s[20:21]
	s_add_u32 m0, s27, 98304
	v_mfma_f32_32x32x16_bf16 v[96:111], v[128:131], v[140:143], v[96:111]
	global_load_lds_dwordx4 v192, s[24:25]
	s_add_u32 m0, s27, 73728
	v_mfma_f32_32x32x16_bf16 v[80:95], v[128:131], v[144:147], v[80:95]
	global_load_lds_dwordx4 v194, s[20:21]
	s_add_u32 m0, s27, 106496
	v_mfma_f32_32x32x16_bf16 v[64:79], v[128:131], v[148:151], v[64:79]
	global_load_lds_dwordx4 v194, s[24:25]
	s_add_u32 m0, s27, 81920
	v_mfma_f32_32x32x16_bf16 v[48:63], v[132:135], v[136:139], v[48:63]
	global_load_lds_dwordx4 v196, s[20:21]
	s_add_u32 m0, s27, 114688
	v_mfma_f32_32x32x16_bf16 v[32:47], v[132:135], v[140:143], v[32:47]
	global_load_lds_dwordx4 v196, s[24:25]
	s_add_u32 m0, s27, 90112
	v_mfma_f32_32x32x16_bf16 v[16:31], v[132:135], v[144:147], v[16:31]
	global_load_lds_dwordx4 v198, s[20:21]
	s_add_u32 m0, s27, 122880
	v_mfma_f32_32x32x16_bf16 v[0:15], v[132:135], v[148:151], v[0:15]
	global_load_lds_dwordx4 v198, s[24:25]
	ds_read_b128 v[128:131], v185
	ds_read_b128 v[136:139], v189
	ds_read_b128 v[132:135], v185 offset:4096
	ds_read_b128 v[140:143], v189 offset:4096
	ds_read_b128 v[144:147], v189 offset:8192
	ds_read_b128 v[148:151], v189 offset:12288
	s_waitcnt lgkmcnt(6)
	v_mfma_f32_32x32x16_bf16 v[112:127], v[160:163], v[168:171], v[112:127]
	v_mfma_f32_32x32x16_bf16 v[96:111], v[160:163], v[172:175], v[96:111]
	v_mfma_f32_32x32x16_bf16 v[80:95], v[160:163], v[176:179], v[80:95]
	v_mfma_f32_32x32x16_bf16 v[64:79], v[160:163], v[180:183], v[64:79]
	v_mfma_f32_32x32x16_bf16 v[48:63], v[164:167], v[168:171], v[48:63]
	v_mfma_f32_32x32x16_bf16 v[32:47], v[164:167], v[172:175], v[32:47]
	v_mfma_f32_32x32x16_bf16 v[16:31], v[164:167], v[176:179], v[16:31]
	v_mfma_f32_32x32x16_bf16 v[0:15], v[164:167], v[180:183], v[0:15]
	ds_read_b128 v[160:163], v186
	ds_read_b128 v[168:171], v190
	ds_read_b128 v[164:167], v186 offset:4096
	ds_read_b128 v[172:175], v190 offset:4096
	ds_read_b128 v[176:179], v190 offset:8192
	ds_read_b128 v[180:183], v190 offset:12288
	s_waitcnt lgkmcnt(6)
	v_mfma_f32_32x32x16_bf16 v[112:127], v[128:131], v[136:139], v[112:127]
	v_mfma_f32_32x32x16_bf16 v[96:111], v[128:131], v[140:143], v[96:111]
	v_mfma_f32_32x32x16_bf16 v[80:95], v[128:131], v[144:147], v[80:95]
	v_mfma_f32_32x32x16_bf16 v[64:79], v[128:131], v[148:151], v[64:79]
	v_mfma_f32_32x32x16_bf16 v[48:63], v[132:135], v[136:139], v[48:63]
	v_mfma_f32_32x32x16_bf16 v[32:47], v[132:135], v[140:143], v[32:47]
	v_mfma_f32_32x32x16_bf16 v[16:31], v[132:135], v[144:147], v[16:31]
	v_mfma_f32_32x32x16_bf16 v[0:15], v[132:135], v[148:151], v[0:15]
	ds_read_b128 v[128:131], v187
	ds_read_b128 v[136:139], v191
	ds_read_b128 v[132:135], v187 offset:4096
	ds_read_b128 v[140:143], v191 offset:4096
	ds_read_b128 v[144:147], v191 offset:8192
	ds_read_b128 v[148:151], v191 offset:12288
	s_waitcnt lgkmcnt(6)
	v_mfma_f32_32x32x16_bf16 v[112:127], v[160:163], v[168:171], v[112:127]
	v_mfma_f32_32x32x16_bf16 v[96:111], v[160:163], v[172:175], v[96:111]
	v_mfma_f32_32x32x16_bf16 v[80:95], v[160:163], v[176:179], v[80:95]
	v_mfma_f32_32x32x16_bf16 v[64:79], v[160:163], v[180:183], v[64:79]
	v_mfma_f32_32x32x16_bf16 v[48:63], v[164:167], v[168:171], v[48:63]
	v_mfma_f32_32x32x16_bf16 v[32:47], v[164:167], v[172:175], v[32:47]
	v_mfma_f32_32x32x16_bf16 v[16:31], v[164:167], v[176:179], v[16:31]
	v_mfma_f32_32x32x16_bf16 v[0:15], v[164:167], v[180:183], v[0:15]
	s_waitcnt vmcnt(0) lgkmcnt(0)
	s_barrier
	ds_read_b128 v[160:163], v240
	ds_read_b128 v[168:171], v244
	ds_read_b128 v[164:167], v240 offset:4096
	ds_read_b128 v[172:175], v244 offset:4096
	ds_read_b128 v[176:179], v244 offset:8192
	ds_read_b128 v[180:183], v244 offset:12288
	s_add_u32 s20, s16, 1280
	s_addc_u32 s21, s17, 0
	s_add_u32 s24, s18, 1280
	s_addc_u32 s25, s19, 0
	s_add_u32 m0, s27, 0
	v_mfma_f32_32x32x16_bf16 v[112:127], v[128:131], v[136:139], v[112:127]
	global_load_lds_dwordx4 v192, s[20:21]
	s_add_u32 m0, s27, 32768
	v_mfma_f32_32x32x16_bf16 v[96:111], v[128:131], v[140:143], v[96:111]
	global_load_lds_dwordx4 v192, s[24:25]
	s_add_u32 m0, s27, 8192
	v_mfma_f32_32x32x16_bf16 v[80:95], v[128:131], v[144:147], v[80:95]
	global_load_lds_dwordx4 v194, s[20:21]
	s_add_u32 m0, s27, 40960
	v_mfma_f32_32x32x16_bf16 v[64:79], v[128:131], v[148:151], v[64:79]
	global_load_lds_dwordx4 v194, s[24:25]
	s_add_u32 m0, s27, 16384
	v_mfma_f32_32x32x16_bf16 v[48:63], v[132:135], v[136:139], v[48:63]
	global_load_lds_dwordx4 v196, s[20:21]
	s_add_u32 m0, s27, 49152
	v_mfma_f32_32x32x16_bf16 v[32:47], v[132:135], v[140:143], v[32:47]
	global_load_lds_dwordx4 v196, s[24:25]
	s_add_u32 m0, s27, 24576
	v_mfma_f32_32x32x16_bf16 v[16:31], v[132:135], v[144:147], v[16:31]
	global_load_lds_dwordx4 v198, s[20:21]
	s_add_u32 m0, s27, 57344
	v_mfma_f32_32x32x16_bf16 v[0:15], v[132:135], v[148:151], v[0:15]
	global_load_lds_dwordx4 v198, s[24:25]
	ds_read_b128 v[128:131], v241
	ds_read_b128 v[136:139], v245
	ds_read_b128 v[132:135], v241 offset:4096
	ds_read_b128 v[140:143], v245 offset:4096
	ds_read_b128 v[144:147], v245 offset:8192
	ds_read_b128 v[148:151], v245 offset:12288
	s_waitcnt lgkmcnt(6)
	v_mfma_f32_32x32x16_bf16 v[112:127], v[160:163], v[168:171], v[112:127]
	v_mfma_f32_32x32x16_bf16 v[96:111], v[160:163], v[172:175], v[96:111]
	v_mfma_f32_32x32x16_bf16 v[80:95], v[160:163], v[176:179], v[80:95]
	v_mfma_f32_32x32x16_bf16 v[64:79], v[160:163], v[180:183], v[64:79]
	v_mfma_f32_32x32x16_bf16 v[48:63], v[164:167], v[168:171], v[48:63]
	v_mfma_f32_32x32x16_bf16 v[32:47], v[164:167], v[172:175], v[32:47]
	v_mfma_f32_32x32x16_bf16 v[16:31], v[164:167], v[176:179], v[16:31]
	v_mfma_f32_32x32x16_bf16 v[0:15], v[164:167], v[180:183], v[0:15]
	ds_read_b128 v[160:163], v242
	ds_read_b128 v[168:171], v246
	ds_read_b128 v[164:167], v242 offset:4096
	ds_read_b128 v[172:175], v246 offset:4096
	ds_read_b128 v[176:179], v246 offset:8192
	ds_read_b128 v[180:183], v246 offset:12288
	s_waitcnt lgkmcnt(6)
	v_mfma_f32_32x32x16_bf16 v[112:127], v[128:131], v[136:139], v[112:127]
	v_mfma_f32_32x32x16_bf16 v[96:111], v[128:131], v[140:143], v[96:111]
	v_mfma_f32_32x32x16_bf16 v[80:95], v[128:131], v[144:147], v[80:95]
	v_mfma_f32_32x32x16_bf16 v[64:79], v[128:131], v[148:151], v[64:79]
	v_mfma_f32_32x32x16_bf16 v[48:63], v[132:135], v[136:139], v[48:63]
	v_mfma_f32_32x32x16_bf16 v[32:47], v[132:135], v[140:143], v[32:47]
	v_mfma_f32_32x32x16_bf16 v[16:31], v[132:135], v[144:147], v[16:31]
	v_mfma_f32_32x32x16_bf16 v[0:15], v[132:135], v[148:151], v[0:15]
	ds_read_b128 v[128:131], v243
	ds_read_b128 v[136:139], v247
	ds_read_b128 v[132:135], v243 offset:4096
	ds_read_b128 v[140:143], v247 offset:4096
	ds_read_b128 v[144:147], v247 offset:8192
	ds_read_b128 v[148:151], v247 offset:12288
	s_waitcnt lgkmcnt(6)
	v_mfma_f32_32x32x16_bf16 v[112:127], v[160:163], v[168:171], v[112:127]
	v_mfma_f32_32x32x16_bf16 v[96:111], v[160:163], v[172:175], v[96:111]
	v_mfma_f32_32x32x16_bf16 v[80:95], v[160:163], v[176:179], v[80:95]
	v_mfma_f32_32x32x16_bf16 v[64:79], v[160:163], v[180:183], v[64:79]
	v_mfma_f32_32x32x16_bf16 v[48:63], v[164:167], v[168:171], v[48:63]
	v_mfma_f32_32x32x16_bf16 v[32:47], v[164:167], v[172:175], v[32:47]
	v_mfma_f32_32x32x16_bf16 v[16:31], v[164:167], v[176:179], v[16:31]
	v_mfma_f32_32x32x16_bf16 v[0:15], v[164:167], v[180:183], v[0:15]
	s_waitcnt vmcnt(0) lgkmcnt(0)
	s_barrier
	ds_read_b128 v[160:163], v184
	ds_read_b128 v[168:171], v188
	ds_read_b128 v[164:167], v184 offset:4096
	ds_read_b128 v[172:175], v188 offset:4096
	ds_read_b128 v[176:179], v188 offset:8192
	ds_read_b128 v[180:183], v188 offset:12288
	s_add_u32 s20, s16, 1408
	s_addc_u32 s21, s17, 0
	s_add_u32 s24, s18, 1408
	s_addc_u32 s25, s19, 0
	s_add_u32 m0, s27, 65536
	v_mfma_f32_32x32x16_bf16 v[112:127], v[128:131], v[136:139], v[112:127]
	global_load_lds_dwordx4 v192, s[20:21]
	s_add_u32 m0, s27, 98304
	v_mfma_f32_32x32x16_bf16 v[96:111], v[128:131], v[140:143], v[96:111]
	global_load_lds_dwordx4 v192, s[24:25]
	s_add_u32 m0, s27, 73728
	v_mfma_f32_32x32x16_bf16 v[80:95], v[128:131], v[144:147], v[80:95]
	global_load_lds_dwordx4 v194, s[20:21]
	s_add_u32 m0, s27, 106496
	v_mfma_f32_32x32x16_bf16 v[64:79], v[128:131], v[148:151], v[64:79]
	global_load_lds_dwordx4 v194, s[24:25]
	s_add_u32 m0, s27, 81920
	v_mfma_f32_32x32x16_bf16 v[48:63], v[132:135], v[136:139], v[48:63]
	global_load_lds_dwordx4 v196, s[20:21]
	s_add_u32 m0, s27, 114688
	v_mfma_f32_32x32x16_bf16 v[32:47], v[132:135], v[140:143], v[32:47]
	global_load_lds_dwordx4 v196, s[24:25]
	s_add_u32 m0, s27, 90112
	v_mfma_f32_32x32x16_bf16 v[16:31], v[132:135], v[144:147], v[16:31]
	global_load_lds_dwordx4 v198, s[20:21]
	s_add_u32 m0, s27, 122880
	v_mfma_f32_32x32x16_bf16 v[0:15], v[132:135], v[148:151], v[0:15]
	global_load_lds_dwordx4 v198, s[24:25]
	ds_read_b128 v[128:131], v185
	ds_read_b128 v[136:139], v189
	ds_read_b128 v[132:135], v185 offset:4096
	ds_read_b128 v[140:143], v189 offset:4096
	ds_read_b128 v[144:147], v189 offset:8192
	ds_read_b128 v[148:151], v189 offset:12288
	s_waitcnt lgkmcnt(6)
	v_mfma_f32_32x32x16_bf16 v[112:127], v[160:163], v[168:171], v[112:127]
	v_mfma_f32_32x32x16_bf16 v[96:111], v[160:163], v[172:175], v[96:111]
	v_mfma_f32_32x32x16_bf16 v[80:95], v[160:163], v[176:179], v[80:95]
	v_mfma_f32_32x32x16_bf16 v[64:79], v[160:163], v[180:183], v[64:79]
	v_mfma_f32_32x32x16_bf16 v[48:63], v[164:167], v[168:171], v[48:63]
	v_mfma_f32_32x32x16_bf16 v[32:47], v[164:167], v[172:175], v[32:47]
	v_mfma_f32_32x32x16_bf16 v[16:31], v[164:167], v[176:179], v[16:31]
	v_mfma_f32_32x32x16_bf16 v[0:15], v[164:167], v[180:183], v[0:15]
	ds_read_b128 v[160:163], v186
	ds_read_b128 v[168:171], v190
	ds_read_b128 v[164:167], v186 offset:4096
	ds_read_b128 v[172:175], v190 offset:4096
	ds_read_b128 v[176:179], v190 offset:8192
	ds_read_b128 v[180:183], v190 offset:12288
	s_waitcnt lgkmcnt(6)
	v_mfma_f32_32x32x16_bf16 v[112:127], v[128:131], v[136:139], v[112:127]
	v_mfma_f32_32x32x16_bf16 v[96:111], v[128:131], v[140:143], v[96:111]
	v_mfma_f32_32x32x16_bf16 v[80:95], v[128:131], v[144:147], v[80:95]
	v_mfma_f32_32x32x16_bf16 v[64:79], v[128:131], v[148:151], v[64:79]
	v_mfma_f32_32x32x16_bf16 v[48:63], v[132:135], v[136:139], v[48:63]
	v_mfma_f32_32x32x16_bf16 v[32:47], v[132:135], v[140:143], v[32:47]
	v_mfma_f32_32x32x16_bf16 v[16:31], v[132:135], v[144:147], v[16:31]
	v_mfma_f32_32x32x16_bf16 v[0:15], v[132:135], v[148:151], v[0:15]
	ds_read_b128 v[128:131], v187
	ds_read_b128 v[136:139], v191
	ds_read_b128 v[132:135], v187 offset:4096
	ds_read_b128 v[140:143], v191 offset:4096
	ds_read_b128 v[144:147], v191 offset:8192
	ds_read_b128 v[148:151], v191 offset:12288
	s_waitcnt lgkmcnt(6)
	v_mfma_f32_32x32x16_bf16 v[112:127], v[160:163], v[168:171], v[112:127]
	v_mfma_f32_32x32x16_bf16 v[96:111], v[160:163], v[172:175], v[96:111]
	v_mfma_f32_32x32x16_bf16 v[80:95], v[160:163], v[176:179], v[80:95]
	v_mfma_f32_32x32x16_bf16 v[64:79], v[160:163], v[180:183], v[64:79]
	v_mfma_f32_32x32x16_bf16 v[48:63], v[164:167], v[168:171], v[48:63]
	v_mfma_f32_32x32x16_bf16 v[32:47], v[164:167], v[172:175], v[32:47]
	v_mfma_f32_32x32x16_bf16 v[16:31], v[164:167], v[176:179], v[16:31]
	v_mfma_f32_32x32x16_bf16 v[0:15], v[164:167], v[180:183], v[0:15]
	s_waitcnt vmcnt(0) lgkmcnt(0)
	s_barrier
	ds_read_b128 v[160:163], v240
	ds_read_b128 v[168:171], v244
	ds_read_b128 v[164:167], v240 offset:4096
	ds_read_b128 v[172:175], v244 offset:4096
	ds_read_b128 v[176:179], v244 offset:8192
	ds_read_b128 v[180:183], v244 offset:12288
	s_add_u32 s20, s16, 1536
	s_addc_u32 s21, s17, 0
	s_add_u32 s24, s18, 1536
	s_addc_u32 s25, s19, 0
	s_add_u32 m0, s27, 0
	v_mfma_f32_32x32x16_bf16 v[112:127], v[128:131], v[136:139], v[112:127]
	global_load_lds_dwordx4 v192, s[20:21]
	s_add_u32 m0, s27, 32768
	v_mfma_f32_32x32x16_bf16 v[96:111], v[128:131], v[140:143], v[96:111]
	global_load_lds_dwordx4 v192, s[24:25]
	s_add_u32 m0, s27, 8192
	v_mfma_f32_32x32x16_bf16 v[80:95], v[128:131], v[144:147], v[80:95]
	global_load_lds_dwordx4 v194, s[20:21]
	s_add_u32 m0, s27, 40960
	v_mfma_f32_32x32x16_bf16 v[64:79], v[128:131], v[148:151], v[64:79]
	global_load_lds_dwordx4 v194, s[24:25]
	s_add_u32 m0, s27, 16384
	v_mfma_f32_32x32x16_bf16 v[48:63], v[132:135], v[136:139], v[48:63]
	global_load_lds_dwordx4 v196, s[20:21]
	s_add_u32 m0, s27, 49152
	v_mfma_f32_32x32x16_bf16 v[32:47], v[132:135], v[140:143], v[32:47]
	global_load_lds_dwordx4 v196, s[24:25]
	s_add_u32 m0, s27, 24576
	v_mfma_f32_32x32x16_bf16 v[16:31], v[132:135], v[144:147], v[16:31]
	global_load_lds_dwordx4 v198, s[20:21]
	s_add_u32 m0, s27, 57344
	v_mfma_f32_32x32x16_bf16 v[0:15], v[132:135], v[148:151], v[0:15]
	global_load_lds_dwordx4 v198, s[24:25]
	ds_read_b128 v[128:131], v241
	ds_read_b128 v[136:139], v245
	ds_read_b128 v[132:135], v241 offset:4096
	ds_read_b128 v[140:143], v245 offset:4096
	ds_read_b128 v[144:147], v245 offset:8192
	ds_read_b128 v[148:151], v245 offset:12288
	s_waitcnt lgkmcnt(6)
	v_mfma_f32_32x32x16_bf16 v[112:127], v[160:163], v[168:171], v[112:127]
	v_mfma_f32_32x32x16_bf16 v[96:111], v[160:163], v[172:175], v[96:111]
	v_mfma_f32_32x32x16_bf16 v[80:95], v[160:163], v[176:179], v[80:95]
	v_mfma_f32_32x32x16_bf16 v[64:79], v[160:163], v[180:183], v[64:79]
	v_mfma_f32_32x32x16_bf16 v[48:63], v[164:167], v[168:171], v[48:63]
	v_mfma_f32_32x32x16_bf16 v[32:47], v[164:167], v[172:175], v[32:47]
	v_mfma_f32_32x32x16_bf16 v[16:31], v[164:167], v[176:179], v[16:31]
	v_mfma_f32_32x32x16_bf16 v[0:15], v[164:167], v[180:183], v[0:15]
	ds_read_b128 v[160:163], v242
	ds_read_b128 v[168:171], v246
	ds_read_b128 v[164:167], v242 offset:4096
	ds_read_b128 v[172:175], v246 offset:4096
	ds_read_b128 v[176:179], v246 offset:8192
	ds_read_b128 v[180:183], v246 offset:12288
	s_waitcnt lgkmcnt(6)
	v_mfma_f32_32x32x16_bf16 v[112:127], v[128:131], v[136:139], v[112:127]
	v_mfma_f32_32x32x16_bf16 v[96:111], v[128:131], v[140:143], v[96:111]
	v_mfma_f32_32x32x16_bf16 v[80:95], v[128:131], v[144:147], v[80:95]
	v_mfma_f32_32x32x16_bf16 v[64:79], v[128:131], v[148:151], v[64:79]
	v_mfma_f32_32x32x16_bf16 v[48:63], v[132:135], v[136:139], v[48:63]
	v_mfma_f32_32x32x16_bf16 v[32:47], v[132:135], v[140:143], v[32:47]
	v_mfma_f32_32x32x16_bf16 v[16:31], v[132:135], v[144:147], v[16:31]
	v_mfma_f32_32x32x16_bf16 v[0:15], v[132:135], v[148:151], v[0:15]
	ds_read_b128 v[128:131], v243
	ds_read_b128 v[136:139], v247
	ds_read_b128 v[132:135], v243 offset:4096
	ds_read_b128 v[140:143], v247 offset:4096
	ds_read_b128 v[144:147], v247 offset:8192
	ds_read_b128 v[148:151], v247 offset:12288
	s_waitcnt lgkmcnt(6)
	v_mfma_f32_32x32x16_bf16 v[112:127], v[160:163], v[168:171], v[112:127]
	v_mfma_f32_32x32x16_bf16 v[96:111], v[160:163], v[172:175], v[96:111]
	v_mfma_f32_32x32x16_bf16 v[80:95], v[160:163], v[176:179], v[80:95]
	v_mfma_f32_32x32x16_bf16 v[64:79], v[160:163], v[180:183], v[64:79]
	v_mfma_f32_32x32x16_bf16 v[48:63], v[164:167], v[168:171], v[48:63]
	v_mfma_f32_32x32x16_bf16 v[32:47], v[164:167], v[172:175], v[32:47]
	v_mfma_f32_32x32x16_bf16 v[16:31], v[164:167], v[176:179], v[16:31]
	v_mfma_f32_32x32x16_bf16 v[0:15], v[164:167], v[180:183], v[0:15]
	s_waitcnt vmcnt(0) lgkmcnt(0)
	s_barrier
	ds_read_b128 v[160:163], v184
	ds_read_b128 v[168:171], v188
	ds_read_b128 v[164:167], v184 offset:4096
	ds_read_b128 v[172:175], v188 offset:4096
	ds_read_b128 v[176:179], v188 offset:8192
	ds_read_b128 v[180:183], v188 offset:12288
	s_add_u32 s20, s16, 1664
	s_addc_u32 s21, s17, 0
	s_add_u32 s24, s18, 1664
	s_addc_u32 s25, s19, 0
	s_add_u32 m0, s27, 65536
	v_mfma_f32_32x32x16_bf16 v[112:127], v[128:131], v[136:139], v[112:127]
	global_load_lds_dwordx4 v192, s[20:21]
	s_add_u32 m0, s27, 98304
	v_mfma_f32_32x32x16_bf16 v[96:111], v[128:131], v[140:143], v[96:111]
	global_load_lds_dwordx4 v192, s[24:25]
	s_add_u32 m0, s27, 73728
	v_mfma_f32_32x32x16_bf16 v[80:95], v[128:131], v[144:147], v[80:95]
	global_load_lds_dwordx4 v194, s[20:21]
	s_add_u32 m0, s27, 106496
	v_mfma_f32_32x32x16_bf16 v[64:79], v[128:131], v[148:151], v[64:79]
	global_load_lds_dwordx4 v194, s[24:25]
	s_add_u32 m0, s27, 81920
	v_mfma_f32_32x32x16_bf16 v[48:63], v[132:135], v[136:139], v[48:63]
	global_load_lds_dwordx4 v196, s[20:21]
	s_add_u32 m0, s27, 114688
	v_mfma_f32_32x32x16_bf16 v[32:47], v[132:135], v[140:143], v[32:47]
	global_load_lds_dwordx4 v196, s[24:25]
	s_add_u32 m0, s27, 90112
	v_mfma_f32_32x32x16_bf16 v[16:31], v[132:135], v[144:147], v[16:31]
	global_load_lds_dwordx4 v198, s[20:21]
	s_add_u32 m0, s27, 122880
	v_mfma_f32_32x32x16_bf16 v[0:15], v[132:135], v[148:151], v[0:15]
	global_load_lds_dwordx4 v198, s[24:25]
	ds_read_b128 v[128:131], v185
	ds_read_b128 v[136:139], v189
	ds_read_b128 v[132:135], v185 offset:4096
	ds_read_b128 v[140:143], v189 offset:4096
	ds_read_b128 v[144:147], v189 offset:8192
	ds_read_b128 v[148:151], v189 offset:12288
	s_waitcnt lgkmcnt(6)
	v_mfma_f32_32x32x16_bf16 v[112:127], v[160:163], v[168:171], v[112:127]
	v_mfma_f32_32x32x16_bf16 v[96:111], v[160:163], v[172:175], v[96:111]
	v_mfma_f32_32x32x16_bf16 v[80:95], v[160:163], v[176:179], v[80:95]
	v_mfma_f32_32x32x16_bf16 v[64:79], v[160:163], v[180:183], v[64:79]
	v_mfma_f32_32x32x16_bf16 v[48:63], v[164:167], v[168:171], v[48:63]
	v_mfma_f32_32x32x16_bf16 v[32:47], v[164:167], v[172:175], v[32:47]
	v_mfma_f32_32x32x16_bf16 v[16:31], v[164:167], v[176:179], v[16:31]
	v_mfma_f32_32x32x16_bf16 v[0:15], v[164:167], v[180:183], v[0:15]
	ds_read_b128 v[160:163], v186
	ds_read_b128 v[168:171], v190
	ds_read_b128 v[164:167], v186 offset:4096
	ds_read_b128 v[172:175], v190 offset:4096
	ds_read_b128 v[176:179], v190 offset:8192
	ds_read_b128 v[180:183], v190 offset:12288
	s_waitcnt lgkmcnt(6)
	v_mfma_f32_32x32x16_bf16 v[112:127], v[128:131], v[136:139], v[112:127]
	v_mfma_f32_32x32x16_bf16 v[96:111], v[128:131], v[140:143], v[96:111]
	v_mfma_f32_32x32x16_bf16 v[80:95], v[128:131], v[144:147], v[80:95]
	v_mfma_f32_32x32x16_bf16 v[64:79], v[128:131], v[148:151], v[64:79]
	v_mfma_f32_32x32x16_bf16 v[48:63], v[132:135], v[136:139], v[48:63]
	v_mfma_f32_32x32x16_bf16 v[32:47], v[132:135], v[140:143], v[32:47]
	v_mfma_f32_32x32x16_bf16 v[16:31], v[132:135], v[144:147], v[16:31]
	v_mfma_f32_32x32x16_bf16 v[0:15], v[132:135], v[148:151], v[0:15]
	ds_read_b128 v[128:131], v187
	ds_read_b128 v[136:139], v191
	ds_read_b128 v[132:135], v187 offset:4096
	ds_read_b128 v[140:143], v191 offset:4096
	ds_read_b128 v[144:147], v191 offset:8192
	ds_read_b128 v[148:151], v191 offset:12288
	s_waitcnt lgkmcnt(6)
	v_mfma_f32_32x32x16_bf16 v[112:127], v[160:163], v[168:171], v[112:127]
	v_mfma_f32_32x32x16_bf16 v[96:111], v[160:163], v[172:175], v[96:111]
	v_mfma_f32_32x32x16_bf16 v[80:95], v[160:163], v[176:179], v[80:95]
	v_mfma_f32_32x32x16_bf16 v[64:79], v[160:163], v[180:183], v[64:79]
	v_mfma_f32_32x32x16_bf16 v[48:63], v[164:167], v[168:171], v[48:63]
	v_mfma_f32_32x32x16_bf16 v[32:47], v[164:167], v[172:175], v[32:47]
	v_mfma_f32_32x32x16_bf16 v[16:31], v[164:167], v[176:179], v[16:31]
	v_mfma_f32_32x32x16_bf16 v[0:15], v[164:167], v[180:183], v[0:15]
	s_waitcnt vmcnt(0) lgkmcnt(0)
	s_barrier
	ds_read_b128 v[160:163], v240
	ds_read_b128 v[168:171], v244
	ds_read_b128 v[164:167], v240 offset:4096
	ds_read_b128 v[172:175], v244 offset:4096
	ds_read_b128 v[176:179], v244 offset:8192
	ds_read_b128 v[180:183], v244 offset:12288
	s_add_u32 s20, s16, 1792
	s_addc_u32 s21, s17, 0
	s_add_u32 s24, s18, 1792
	s_addc_u32 s25, s19, 0
	s_add_u32 m0, s27, 0
	v_mfma_f32_32x32x16_bf16 v[112:127], v[128:131], v[136:139], v[112:127]
	global_load_lds_dwordx4 v192, s[20:21]
	s_add_u32 m0, s27, 32768
	v_mfma_f32_32x32x16_bf16 v[96:111], v[128:131], v[140:143], v[96:111]
	global_load_lds_dwordx4 v192, s[24:25]
	s_add_u32 m0, s27, 8192
	v_mfma_f32_32x32x16_bf16 v[80:95], v[128:131], v[144:147], v[80:95]
	global_load_lds_dwordx4 v194, s[20:21]
	s_add_u32 m0, s27, 40960
	v_mfma_f32_32x32x16_bf16 v[64:79], v[128:131], v[148:151], v[64:79]
	global_load_lds_dwordx4 v194, s[24:25]
	s_add_u32 m0, s27, 16384
	v_mfma_f32_32x32x16_bf16 v[48:63], v[132:135], v[136:139], v[48:63]
	global_load_lds_dwordx4 v196, s[20:21]
	s_add_u32 m0, s27, 49152
	v_mfma_f32_32x32x16_bf16 v[32:47], v[132:135], v[140:143], v[32:47]
	global_load_lds_dwordx4 v196, s[24:25]
	s_add_u32 m0, s27, 24576
	v_mfma_f32_32x32x16_bf16 v[16:31], v[132:135], v[144:147], v[16:31]
	global_load_lds_dwordx4 v198, s[20:21]
	s_add_u32 m0, s27, 57344
	v_mfma_f32_32x32x16_bf16 v[0:15], v[132:135], v[148:151], v[0:15]
	global_load_lds_dwordx4 v198, s[24:25]
	ds_read_b128 v[128:131], v241
	ds_read_b128 v[136:139], v245
	ds_read_b128 v[132:135], v241 offset:4096
	ds_read_b128 v[140:143], v245 offset:4096
	ds_read_b128 v[144:147], v245 offset:8192
	ds_read_b128 v[148:151], v245 offset:12288
	s_waitcnt lgkmcnt(6)
	v_mfma_f32_32x32x16_bf16 v[112:127], v[160:163], v[168:171], v[112:127]
	v_mfma_f32_32x32x16_bf16 v[96:111], v[160:163], v[172:175], v[96:111]
	v_mfma_f32_32x32x16_bf16 v[80:95], v[160:163], v[176:179], v[80:95]
	v_mfma_f32_32x32x16_bf16 v[64:79], v[160:163], v[180:183], v[64:79]
	v_mfma_f32_32x32x16_bf16 v[48:63], v[164:167], v[168:171], v[48:63]
	v_mfma_f32_32x32x16_bf16 v[32:47], v[164:167], v[172:175], v[32:47]
	v_mfma_f32_32x32x16_bf16 v[16:31], v[164:167], v[176:179], v[16:31]
	v_mfma_f32_32x32x16_bf16 v[0:15], v[164:167], v[180:183], v[0:15]
	ds_read_b128 v[160:163], v242
	ds_read_b128 v[168:171], v246
	ds_read_b128 v[164:167], v242 offset:4096
	ds_read_b128 v[172:175], v246 offset:4096
	ds_read_b128 v[176:179], v246 offset:8192
	ds_read_b128 v[180:183], v246 offset:12288
	s_waitcnt lgkmcnt(6)
	v_mfma_f32_32x32x16_bf16 v[112:127], v[128:131], v[136:139], v[112:127]
	v_mfma_f32_32x32x16_bf16 v[96:111], v[128:131], v[140:143], v[96:111]
	v_mfma_f32_32x32x16_bf16 v[80:95], v[128:131], v[144:147], v[80:95]
	v_mfma_f32_32x32x16_bf16 v[64:79], v[128:131], v[148:151], v[64:79]
	v_mfma_f32_32x32x16_bf16 v[48:63], v[132:135], v[136:139], v[48:63]
	v_mfma_f32_32x32x16_bf16 v[32:47], v[132:135], v[140:143], v[32:47]
	v_mfma_f32_32x32x16_bf16 v[16:31], v[132:135], v[144:147], v[16:31]
	v_mfma_f32_32x32x16_bf16 v[0:15], v[132:135], v[148:151], v[0:15]
	ds_read_b128 v[128:131], v243
	ds_read_b128 v[136:139], v247
	ds_read_b128 v[132:135], v243 offset:4096
	ds_read_b128 v[140:143], v247 offset:4096
	ds_read_b128 v[144:147], v247 offset:8192
	ds_read_b128 v[148:151], v247 offset:12288
	s_waitcnt lgkmcnt(6)
	v_mfma_f32_32x32x16_bf16 v[112:127], v[160:163], v[168:171], v[112:127]
	v_mfma_f32_32x32x16_bf16 v[96:111], v[160:163], v[172:175], v[96:111]
	v_mfma_f32_32x32x16_bf16 v[80:95], v[160:163], v[176:179], v[80:95]
	v_mfma_f32_32x32x16_bf16 v[64:79], v[160:163], v[180:183], v[64:79]
	v_mfma_f32_32x32x16_bf16 v[48:63], v[164:167], v[168:171], v[48:63]
	v_mfma_f32_32x32x16_bf16 v[32:47], v[164:167], v[172:175], v[32:47]
	v_mfma_f32_32x32x16_bf16 v[16:31], v[164:167], v[176:179], v[16:31]
	v_mfma_f32_32x32x16_bf16 v[0:15], v[164:167], v[180:183], v[0:15]
	s_waitcnt vmcnt(0) lgkmcnt(0)
	s_barrier
	ds_read_b128 v[160:163], v184
	ds_read_b128 v[168:171], v188
	ds_read_b128 v[164:167], v184 offset:4096
	ds_read_b128 v[172:175], v188 offset:4096
	ds_read_b128 v[176:179], v188 offset:8192
	ds_read_b128 v[180:183], v188 offset:12288
	s_add_u32 s20, s16, 1920
	s_addc_u32 s21, s17, 0
	s_add_u32 s24, s18, 1920
	s_addc_u32 s25, s19, 0
	s_add_u32 m0, s27, 65536
	v_mfma_f32_32x32x16_bf16 v[112:127], v[128:131], v[136:139], v[112:127]
	global_load_lds_dwordx4 v192, s[20:21]
	s_add_u32 m0, s27, 98304
	v_mfma_f32_32x32x16_bf16 v[96:111], v[128:131], v[140:143], v[96:111]
	global_load_lds_dwordx4 v192, s[24:25]
	s_add_u32 m0, s27, 73728
	v_mfma_f32_32x32x16_bf16 v[80:95], v[128:131], v[144:147], v[80:95]
	global_load_lds_dwordx4 v194, s[20:21]
	s_add_u32 m0, s27, 106496
	v_mfma_f32_32x32x16_bf16 v[64:79], v[128:131], v[148:151], v[64:79]
	global_load_lds_dwordx4 v194, s[24:25]
	s_add_u32 m0, s27, 81920
	v_mfma_f32_32x32x16_bf16 v[48:63], v[132:135], v[136:139], v[48:63]
	global_load_lds_dwordx4 v196, s[20:21]
	s_add_u32 m0, s27, 114688
	v_mfma_f32_32x32x16_bf16 v[32:47], v[132:135], v[140:143], v[32:47]
	global_load_lds_dwordx4 v196, s[24:25]
	s_add_u32 m0, s27, 90112
	v_mfma_f32_32x32x16_bf16 v[16:31], v[132:135], v[144:147], v[16:31]
	global_load_lds_dwordx4 v198, s[20:21]
	s_add_u32 m0, s27, 122880
	v_mfma_f32_32x32x16_bf16 v[0:15], v[132:135], v[148:151], v[0:15]
	global_load_lds_dwordx4 v198, s[24:25]
	ds_read_b128 v[128:131], v185
	ds_read_b128 v[136:139], v189
	ds_read_b128 v[132:135], v185 offset:4096
	ds_read_b128 v[140:143], v189 offset:4096
	ds_read_b128 v[144:147], v189 offset:8192
	ds_read_b128 v[148:151], v189 offset:12288
	s_waitcnt lgkmcnt(6)
	v_mfma_f32_32x32x16_bf16 v[112:127], v[160:163], v[168:171], v[112:127]
	v_mfma_f32_32x32x16_bf16 v[96:111], v[160:163], v[172:175], v[96:111]
	v_mfma_f32_32x32x16_bf16 v[80:95], v[160:163], v[176:179], v[80:95]
	v_mfma_f32_32x32x16_bf16 v[64:79], v[160:163], v[180:183], v[64:79]
	v_mfma_f32_32x32x16_bf16 v[48:63], v[164:167], v[168:171], v[48:63]
	v_mfma_f32_32x32x16_bf16 v[32:47], v[164:167], v[172:175], v[32:47]
	v_mfma_f32_32x32x16_bf16 v[16:31], v[164:167], v[176:179], v[16:31]
	v_mfma_f32_32x32x16_bf16 v[0:15], v[164:167], v[180:183], v[0:15]
	ds_read_b128 v[160:163], v186
	ds_read_b128 v[168:171], v190
	ds_read_b128 v[164:167], v186 offset:4096
	ds_read_b128 v[172:175], v190 offset:4096
	ds_read_b128 v[176:179], v190 offset:8192
	ds_read_b128 v[180:183], v190 offset:12288
	s_waitcnt lgkmcnt(6)
	v_mfma_f32_32x32x16_bf16 v[112:127], v[128:131], v[136:139], v[112:127]
	v_mfma_f32_32x32x16_bf16 v[96:111], v[128:131], v[140:143], v[96:111]
	v_mfma_f32_32x32x16_bf16 v[80:95], v[128:131], v[144:147], v[80:95]
	v_mfma_f32_32x32x16_bf16 v[64:79], v[128:131], v[148:151], v[64:79]
	v_mfma_f32_32x32x16_bf16 v[48:63], v[132:135], v[136:139], v[48:63]
	v_mfma_f32_32x32x16_bf16 v[32:47], v[132:135], v[140:143], v[32:47]
	v_mfma_f32_32x32x16_bf16 v[16:31], v[132:135], v[144:147], v[16:31]
	v_mfma_f32_32x32x16_bf16 v[0:15], v[132:135], v[148:151], v[0:15]
	ds_read_b128 v[128:131], v187
	ds_read_b128 v[136:139], v191
	ds_read_b128 v[132:135], v187 offset:4096
	ds_read_b128 v[140:143], v191 offset:4096
	ds_read_b128 v[144:147], v191 offset:8192
	ds_read_b128 v[148:151], v191 offset:12288
	s_waitcnt lgkmcnt(6)
	v_mfma_f32_32x32x16_bf16 v[112:127], v[160:163], v[168:171], v[112:127]
	v_mfma_f32_32x32x16_bf16 v[96:111], v[160:163], v[172:175], v[96:111]
	v_mfma_f32_32x32x16_bf16 v[80:95], v[160:163], v[176:179], v[80:95]
	v_mfma_f32_32x32x16_bf16 v[64:79], v[160:163], v[180:183], v[64:79]
	v_mfma_f32_32x32x16_bf16 v[48:63], v[164:167], v[168:171], v[48:63]
	v_mfma_f32_32x32x16_bf16 v[32:47], v[164:167], v[172:175], v[32:47]
	v_mfma_f32_32x32x16_bf16 v[16:31], v[164:167], v[176:179], v[16:31]
	v_mfma_f32_32x32x16_bf16 v[0:15], v[164:167], v[180:183], v[0:15]
	s_waitcnt vmcnt(0) lgkmcnt(0)
	s_barrier
	ds_read_b128 v[160:163], v240
	ds_read_b128 v[168:171], v244
	ds_read_b128 v[164:167], v240 offset:4096
	ds_read_b128 v[172:175], v244 offset:4096
	ds_read_b128 v[176:179], v244 offset:8192
	ds_read_b128 v[180:183], v244 offset:12288
	s_add_u32 s37, s30, s42
	s_cmpk_ge_u32 s37, 0x780
	s_cbranch_scc1 .Lip11_full_nonext
	s_mul_hi_u32 s38, s37, 0x92492493
	s_lshr_b32 s38, s38, 3
	s_mul_i32 s39, s38, 14
	s_sub_u32 s39, s37, s39
	s_sub_u32 s98, s37, 0x700
	s_cmpk_lt_u32 s37, 0x700
	s_cselect_b32 s39, s39, 14
	s_cselect_b32 s38, s38, s98
	s_lshl_b32 s98, s38, 19
	s_add_u32 s16, s4, s98
	s_addc_u32 s17, s5, 0
	s_lshl_b32 s98, s39, 19
	s_add_u32 s18, s6, s98
	s_addc_u32 s19, s7, 0
	s_add_u32 m0, s27, 0
	v_mfma_f32_32x32x16_bf16 v[112:127], v[128:131], v[136:139], v[112:127]
	global_load_lds_dwordx4 v192, s[16:17]
	s_add_u32 m0, s27, 32768
	v_mfma_f32_32x32x16_bf16 v[96:111], v[128:131], v[140:143], v[96:111]
	global_load_lds_dwordx4 v192, s[18:19]
	s_add_u32 m0, s27, 8192
	v_mfma_f32_32x32x16_bf16 v[80:95], v[128:131], v[144:147], v[80:95]
	global_load_lds_dwordx4 v194, s[16:17]
	s_add_u32 m0, s27, 40960
	v_mfma_f32_32x32x16_bf16 v[64:79], v[128:131], v[148:151], v[64:79]
	global_load_lds_dwordx4 v194, s[18:19]
	s_add_u32 m0, s27, 16384
	v_mfma_f32_32x32x16_bf16 v[48:63], v[132:135], v[136:139], v[48:63]
	global_load_lds_dwordx4 v196, s[16:17]
	s_add_u32 m0, s27, 49152
	v_mfma_f32_32x32x16_bf16 v[32:47], v[132:135], v[140:143], v[32:47]
	global_load_lds_dwordx4 v196, s[18:19]
	s_add_u32 m0, s27, 24576
	v_mfma_f32_32x32x16_bf16 v[16:31], v[132:135], v[144:147], v[16:31]
	global_load_lds_dwordx4 v198, s[16:17]
	s_add_u32 m0, s27, 57344
	v_mfma_f32_32x32x16_bf16 v[0:15], v[132:135], v[148:151], v[0:15]
	global_load_lds_dwordx4 v198, s[18:19]
	s_branch .Lip11_full_join

.Lip11_full_join:
	ds_read_b128 v[128:131], v241
	ds_read_b128 v[136:139], v245
	ds_read_b128 v[132:135], v241 offset:4096
	ds_read_b128 v[140:143], v245 offset:4096
	ds_read_b128 v[144:147], v245 offset:8192
	ds_read_b128 v[148:151], v245 offset:12288
	s_waitcnt lgkmcnt(6)
	v_mfma_f32_32x32x16_bf16 v[112:127], v[160:163], v[168:171], v[112:127]
	v_mfma_f32_32x32x16_bf16 v[96:111], v[160:163], v[172:175], v[96:111]
	v_mfma_f32_32x32x16_bf16 v[80:95], v[160:163], v[176:179], v[80:95]
	v_mfma_f32_32x32x16_bf16 v[64:79], v[160:163], v[180:183], v[64:79]
	v_mfma_f32_32x32x16_bf16 v[48:63], v[164:167], v[168:171], v[48:63]
	v_mfma_f32_32x32x16_bf16 v[32:47], v[164:167], v[172:175], v[32:47]
	v_mfma_f32_32x32x16_bf16 v[16:31], v[164:167], v[176:179], v[16:31]
	v_mfma_f32_32x32x16_bf16 v[0:15], v[164:167], v[180:183], v[0:15]
	ds_read_b128 v[160:163], v242
	ds_read_b128 v[168:171], v246
	ds_read_b128 v[164:167], v242 offset:4096
	ds_read_b128 v[172:175], v246 offset:4096
	ds_read_b128 v[176:179], v246 offset:8192
	ds_read_b128 v[180:183], v246 offset:12288
	s_waitcnt lgkmcnt(6)
	v_mfma_f32_32x32x16_bf16 v[112:127], v[128:131], v[136:139], v[112:127]
	v_mfma_f32_32x32x16_bf16 v[96:111], v[128:131], v[140:143], v[96:111]
	v_mfma_f32_32x32x16_bf16 v[80:95], v[128:131], v[144:147], v[80:95]
	v_mfma_f32_32x32x16_bf16 v[64:79], v[128:131], v[148:151], v[64:79]
	v_mfma_f32_32x32x16_bf16 v[48:63], v[132:135], v[136:139], v[48:63]
	v_mfma_f32_32x32x16_bf16 v[32:47], v[132:135], v[140:143], v[32:47]
	v_mfma_f32_32x32x16_bf16 v[16:31], v[132:135], v[144:147], v[16:31]
	v_mfma_f32_32x32x16_bf16 v[0:15], v[132:135], v[148:151], v[0:15]
	ds_read_b128 v[128:131], v243
	ds_read_b128 v[136:139], v247
	ds_read_b128 v[132:135], v243 offset:4096
	ds_read_b128 v[140:143], v247 offset:4096
	ds_read_b128 v[144:147], v247 offset:8192
	ds_read_b128 v[148:151], v247 offset:12288
	s_waitcnt lgkmcnt(6)
	v_mfma_f32_32x32x16_bf16 v[112:127], v[160:163], v[168:171], v[112:127]
	v_mfma_f32_32x32x16_bf16 v[96:111], v[160:163], v[172:175], v[96:111]
	v_mfma_f32_32x32x16_bf16 v[80:95], v[160:163], v[176:179], v[80:95]
	v_mfma_f32_32x32x16_bf16 v[64:79], v[160:163], v[180:183], v[64:79]
	v_mfma_f32_32x32x16_bf16 v[48:63], v[164:167], v[168:171], v[48:63]
	v_mfma_f32_32x32x16_bf16 v[32:47], v[164:167], v[172:175], v[32:47]
	v_mfma_f32_32x32x16_bf16 v[16:31], v[164:167], v[176:179], v[16:31]
	v_mfma_f32_32x32x16_bf16 v[0:15], v[164:167], v[180:183], v[0:15]
	s_waitcnt vmcnt(0) lgkmcnt(0)
	s_barrier
	v_mfma_f32_32x32x16_bf16 v[112:127], v[128:131], v[136:139], v[112:127]
	v_mfma_f32_32x32x16_bf16 v[96:111], v[128:131], v[140:143], v[96:111]
	v_mfma_f32_32x32x16_bf16 v[80:95], v[128:131], v[144:147], v[80:95]
	v_mfma_f32_32x32x16_bf16 v[64:79], v[128:131], v[148:151], v[64:79]
	v_mfma_f32_32x32x16_bf16 v[48:63], v[132:135], v[136:139], v[48:63]
	v_mfma_f32_32x32x16_bf16 v[32:47], v[132:135], v[140:143], v[32:47]
	v_mfma_f32_32x32x16_bf16 v[16:31], v[132:135], v[144:147], v[16:31]
	v_mfma_f32_32x32x16_bf16 v[0:15], v[132:135], v[148:151], v[0:15]
	s_branch .Lip11_epi
.Lip11_light:
	s_cmp_eq_u32 s31, 0
	s_cbranch_scc0 .Lip11_lload
	ds_read_b128 v[160:163], v184
	ds_read_b128 v[168:171], v188
	ds_read_b128 v[164:167], v184 offset:4096
	ds_read_b128 v[172:175], v188 offset:4096
	ds_read_b128 v[128:131], v185
	ds_read_b128 v[136:139], v189
	ds_read_b128 v[132:135], v185 offset:4096
	ds_read_b128 v[140:143], v189 offset:4096
	s_waitcnt lgkmcnt(4)
	v_mfma_f32_32x32x16_bf16 v[112:127], v[160:163], v[168:171], 0
	v_mfma_f32_32x32x16_bf16 v[96:111], v[160:163], v[172:175], 0
	v_mfma_f32_32x32x16_bf16 v[48:63], v[164:167], v[168:171], 0
	v_mfma_f32_32x32x16_bf16 v[32:47], v[164:167], v[172:175], 0
	ds_read_b128 v[160:163], v186
	ds_read_b128 v[168:171], v190
	ds_read_b128 v[164:167], v186 offset:4096
	ds_read_b128 v[172:175], v190 offset:4096
	s_waitcnt lgkmcnt(4)
	v_mfma_f32_32x32x16_bf16 v[112:127], v[128:131], v[136:139], v[112:127]
	v_mfma_f32_32x32x16_bf16 v[96:111], v[128:131], v[140:143], v[96:111]
	v_mfma_f32_32x32x16_bf16 v[48:63], v[132:135], v[136:139], v[48:63]
	v_mfma_f32_32x32x16_bf16 v[32:47], v[132:135], v[140:143], v[32:47]
	ds_read_b128 v[128:131], v187
	ds_read_b128 v[136:139], v191
	ds_read_b128 v[132:135], v187 offset:4096
	ds_read_b128 v[140:143], v191 offset:4096
	s_waitcnt lgkmcnt(4)
	v_mfma_f32_32x32x16_bf16 v[112:127], v[160:163], v[168:171], v[112:127]
	v_mfma_f32_32x32x16_bf16 v[96:111], v[160:163], v[172:175], v[96:111]
	v_mfma_f32_32x32x16_bf16 v[48:63], v[164:167], v[168:171], v[48:63]
	v_mfma_f32_32x32x16_bf16 v[32:47], v[164:167], v[172:175], v[32:47]
	s_waitcnt vmcnt(0) lgkmcnt(0)
	s_barrier
	ds_read_b128 v[160:163], v240
	ds_read_b128 v[168:171], v244
	ds_read_b128 v[164:167], v240 offset:4096
	ds_read_b128 v[172:175], v244 offset:4096
	s_add_u32 s20, s16, 256
	s_addc_u32 s21, s17, 0
	s_add_u32 s24, s18, 256
	s_addc_u32 s25, s19, 0
	s_add_u32 m0, s27, 0
	v_mfma_f32_32x32x16_bf16 v[112:127], v[128:131], v[136:139], v[112:127]
	global_load_lds_dwordx4 v192, s[20:21]
	s_add_u32 m0, s27, 32768
	v_mfma_f32_32x32x16_bf16 v[96:111], v[128:131], v[140:143], v[96:111]
	global_load_lds_dwordx4 v192, s[24:25]
	s_add_u32 m0, s27, 8192
	v_mfma_f32_32x32x16_bf16 v[48:63], v[132:135], v[136:139], v[48:63]
	global_load_lds_dwordx4 v194, s[20:21]
	s_add_u32 m0, s27, 40960
	v_mfma_f32_32x32x16_bf16 v[32:47], v[132:135], v[140:143], v[32:47]
	global_load_lds_dwordx4 v194, s[24:25]
	s_add_u32 m0, s27, 16384
	s_nop 0
	global_load_lds_dwordx4 v196, s[20:21]
	s_add_u32 m0, s27, 49152
	s_nop 0
	global_load_lds_dwordx4 v196, s[24:25]
	s_add_u32 m0, s27, 24576
	s_nop 0
	global_load_lds_dwordx4 v198, s[20:21]
	s_add_u32 m0, s27, 57344
	s_nop 0
	global_load_lds_dwordx4 v198, s[24:25]
	ds_read_b128 v[128:131], v241
	ds_read_b128 v[136:139], v245
	ds_read_b128 v[132:135], v241 offset:4096
	ds_read_b128 v[140:143], v245 offset:4096
	s_waitcnt lgkmcnt(4)
	v_mfma_f32_32x32x16_bf16 v[112:127], v[160:163], v[168:171], v[112:127]
	v_mfma_f32_32x32x16_bf16 v[96:111], v[160:163], v[172:175], v[96:111]
	v_mfma_f32_32x32x16_bf16 v[48:63], v[164:167], v[168:171], v[48:63]
	v_mfma_f32_32x32x16_bf16 v[32:47], v[164:167], v[172:175], v[32:47]
	ds_read_b128 v[160:163], v242
	ds_read_b128 v[168:171], v246
	ds_read_b128 v[164:167], v242 offset:4096
	ds_read_b128 v[172:175], v246 offset:4096
	s_waitcnt lgkmcnt(4)
	v_mfma_f32_32x32x16_bf16 v[112:127], v[128:131], v[136:139], v[112:127]
	v_mfma_f32_32x32x16_bf16 v[96:111], v[128:131], v[140:143], v[96:111]
	v_mfma_f32_32x32x16_bf16 v[48:63], v[132:135], v[136:139], v[48:63]
	v_mfma_f32_32x32x16_bf16 v[32:47], v[132:135], v[140:143], v[32:47]
	ds_read_b128 v[128:131], v243
	ds_read_b128 v[136:139], v247
	ds_read_b128 v[132:135], v243 offset:4096
	ds_read_b128 v[140:143], v247 offset:4096
	s_waitcnt lgkmcnt(4)
	v_mfma_f32_32x32x16_bf16 v[112:127], v[160:163], v[168:171], v[112:127]
	v_mfma_f32_32x32x16_bf16 v[96:111], v[160:163], v[172:175], v[96:111]
	v_mfma_f32_32x32x16_bf16 v[48:63], v[164:167], v[168:171], v[48:63]
	v_mfma_f32_32x32x16_bf16 v[32:47], v[164:167], v[172:175], v[32:47]
	s_waitcnt vmcnt(0) lgkmcnt(0)
	s_barrier
	ds_read_b128 v[160:163], v184
	ds_read_b128 v[168:171], v188
	ds_read_b128 v[164:167], v184 offset:4096
	ds_read_b128 v[172:175], v188 offset:4096
	s_add_u32 s20, s16, 384
	s_addc_u32 s21, s17, 0
	s_add_u32 s24, s18, 384
	s_addc_u32 s25, s19, 0
	s_add_u32 m0, s27, 65536
	v_mfma_f32_32x32x16_bf16 v[112:127], v[128:131], v[136:139], v[112:127]
	global_load_lds_dwordx4 v192, s[20:21]
	s_add_u32 m0, s27, 98304
	v_mfma_f32_32x32x16_bf16 v[96:111], v[128:131], v[140:143], v[96:111]
	global_load_lds_dwordx4 v192, s[24:25]
	s_add_u32 m0, s27, 73728
	v_mfma_f32_32x32x16_bf16 v[48:63], v[132:135], v[136:139], v[48:63]
	global_load_lds_dwordx4 v194, s[20:21]
	s_add_u32 m0, s27, 106496
	v_mfma_f32_32x32x16_bf16 v[32:47], v[132:135], v[140:143], v[32:47]
	global_load_lds_dwordx4 v194, s[24:25]
	s_add_u32 m0, s27, 81920
	s_nop 0
	global_load_lds_dwordx4 v196, s[20:21]
	s_add_u32 m0, s27, 114688
	s_nop 0
	global_load_lds_dwordx4 v196, s[24:25]
	s_add_u32 m0, s27, 90112
	s_nop 0
	global_load_lds_dwordx4 v198, s[20:21]
	s_add_u32 m0, s27, 122880
	s_nop 0
	global_load_lds_dwordx4 v198, s[24:25]
	ds_read_b128 v[128:131], v185
	ds_read_b128 v[136:139], v189
	ds_read_b128 v[132:135], v185 offset:4096
	ds_read_b128 v[140:143], v189 offset:4096
	s_waitcnt lgkmcnt(4)
	v_mfma_f32_32x32x16_bf16 v[112:127], v[160:163], v[168:171], v[112:127]
	v_mfma_f32_32x32x16_bf16 v[96:111], v[160:163], v[172:175], v[96:111]
	v_mfma_f32_32x32x16_bf16 v[48:63], v[164:167], v[168:171], v[48:63]
	v_mfma_f32_32x32x16_bf16 v[32:47], v[164:167], v[172:175], v[32:47]
	ds_read_b128 v[160:163], v186
	ds_read_b128 v[168:171], v190
	ds_read_b128 v[164:167], v186 offset:4096
	ds_read_b128 v[172:175], v190 offset:4096
	s_waitcnt lgkmcnt(4)
	v_mfma_f32_32x32x16_bf16 v[112:127], v[128:131], v[136:139], v[112:127]
	v_mfma_f32_32x32x16_bf16 v[96:111], v[128:131], v[140:143], v[96:111]
	v_mfma_f32_32x32x16_bf16 v[48:63], v[132:135], v[136:139], v[48:63]
	v_mfma_f32_32x32x16_bf16 v[32:47], v[132:135], v[140:143], v[32:47]
	ds_read_b128 v[128:131], v187
	ds_read_b128 v[136:139], v191
	ds_read_b128 v[132:135], v187 offset:4096
	ds_read_b128 v[140:143], v191 offset:4096
	s_waitcnt lgkmcnt(4)
	v_mfma_f32_32x32x16_bf16 v[112:127], v[160:163], v[168:171], v[112:127]
	v_mfma_f32_32x32x16_bf16 v[96:111], v[160:163], v[172:175], v[96:111]
	v_mfma_f32_32x32x16_bf16 v[48:63], v[164:167], v[168:171], v[48:63]
	v_mfma_f32_32x32x16_bf16 v[32:47], v[164:167], v[172:175], v[32:47]
	s_waitcnt vmcnt(0) lgkmcnt(0)
	s_barrier
	ds_read_b128 v[160:163], v240
	ds_read_b128 v[168:171], v244
	ds_read_b128 v[164:167], v240 offset:4096
	ds_read_b128 v[172:175], v244 offset:4096
	s_add_u32 s20, s16, 512
	s_addc_u32 s21, s17, 0
	s_add_u32 s24, s18, 512
	s_addc_u32 s25, s19, 0
	s_add_u32 m0, s27, 0
	v_mfma_f32_32x32x16_bf16 v[112:127], v[128:131], v[136:139], v[112:127]
	global_load_lds_dwordx4 v192, s[20:21]
	s_add_u32 m0, s27, 32768
	v_mfma_f32_32x32x16_bf16 v[96:111], v[128:131], v[140:143], v[96:111]
	global_load_lds_dwordx4 v192, s[24:25]
	s_add_u32 m0, s27, 8192
	v_mfma_f32_32x32x16_bf16 v[48:63], v[132:135], v[136:139], v[48:63]
	global_load_lds_dwordx4 v194, s[20:21]
	s_add_u32 m0, s27, 40960
	v_mfma_f32_32x32x16_bf16 v[32:47], v[132:135], v[140:143], v[32:47]
	global_load_lds_dwordx4 v194, s[24:25]
	s_add_u32 m0, s27, 16384
	s_nop 0
	global_load_lds_dwordx4 v196, s[20:21]
	s_add_u32 m0, s27, 49152
	s_nop 0
	global_load_lds_dwordx4 v196, s[24:25]
	s_add_u32 m0, s27, 24576
	s_nop 0
	global_load_lds_dwordx4 v198, s[20:21]
	s_add_u32 m0, s27, 57344
	s_nop 0
	global_load_lds_dwordx4 v198, s[24:25]
	ds_read_b128 v[128:131], v241
	ds_read_b128 v[136:139], v245
	ds_read_b128 v[132:135], v241 offset:4096
	ds_read_b128 v[140:143], v245 offset:4096
	s_waitcnt lgkmcnt(4)
	v_mfma_f32_32x32x16_bf16 v[112:127], v[160:163], v[168:171], v[112:127]
	v_mfma_f32_32x32x16_bf16 v[96:111], v[160:163], v[172:175], v[96:111]
	v_mfma_f32_32x32x16_bf16 v[48:63], v[164:167], v[168:171], v[48:63]
	v_mfma_f32_32x32x16_bf16 v[32:47], v[164:167], v[172:175], v[32:47]
	ds_read_b128 v[160:163], v242
	ds_read_b128 v[168:171], v246
	ds_read_b128 v[164:167], v242 offset:4096
	ds_read_b128 v[172:175], v246 offset:4096
	s_waitcnt lgkmcnt(4)
	v_mfma_f32_32x32x16_bf16 v[112:127], v[128:131], v[136:139], v[112:127]
	v_mfma_f32_32x32x16_bf16 v[96:111], v[128:131], v[140:143], v[96:111]
	v_mfma_f32_32x32x16_bf16 v[48:63], v[132:135], v[136:139], v[48:63]
	v_mfma_f32_32x32x16_bf16 v[32:47], v[132:135], v[140:143], v[32:47]
	ds_read_b128 v[128:131], v243
	ds_read_b128 v[136:139], v247
	ds_read_b128 v[132:135], v243 offset:4096
	ds_read_b128 v[140:143], v247 offset:4096
	s_waitcnt lgkmcnt(4)
	v_mfma_f32_32x32x16_bf16 v[112:127], v[160:163], v[168:171], v[112:127]
	v_mfma_f32_32x32x16_bf16 v[96:111], v[160:163], v[172:175], v[96:111]
	v_mfma_f32_32x32x16_bf16 v[48:63], v[164:167], v[168:171], v[48:63]
	v_mfma_f32_32x32x16_bf16 v[32:47], v[164:167], v[172:175], v[32:47]
	s_waitcnt vmcnt(0) lgkmcnt(0)
	s_barrier
	ds_read_b128 v[160:163], v184
	ds_read_b128 v[168:171], v188
	ds_read_b128 v[164:167], v184 offset:4096
	ds_read_b128 v[172:175], v188 offset:4096
	s_add_u32 s20, s16, 640
	s_addc_u32 s21, s17, 0
	s_add_u32 s24, s18, 640
	s_addc_u32 s25, s19, 0
	s_add_u32 m0, s27, 65536
	v_mfma_f32_32x32x16_bf16 v[112:127], v[128:131], v[136:139], v[112:127]
	global_load_lds_dwordx4 v192, s[20:21]
	s_add_u32 m0, s27, 98304
	v_mfma_f32_32x32x16_bf16 v[96:111], v[128:131], v[140:143], v[96:111]
	global_load_lds_dwordx4 v192, s[24:25]
	s_add_u32 m0, s27, 73728
	v_mfma_f32_32x32x16_bf16 v[48:63], v[132:135], v[136:139], v[48:63]
	global_load_lds_dwordx4 v194, s[20:21]
	s_add_u32 m0, s27, 106496
	v_mfma_f32_32x32x16_bf16 v[32:47], v[132:135], v[140:143], v[32:47]
	global_load_lds_dwordx4 v194, s[24:25]
	s_add_u32 m0, s27, 81920
	s_nop 0
	global_load_lds_dwordx4 v196, s[20:21]
	s_add_u32 m0, s27, 114688
	s_nop 0
	global_load_lds_dwordx4 v196, s[24:25]
	s_add_u32 m0, s27, 90112
	s_nop 0
	global_load_lds_dwordx4 v198, s[20:21]
	s_add_u32 m0, s27, 122880
	s_nop 0
	global_load_lds_dwordx4 v198, s[24:25]
	ds_read_b128 v[128:131], v185
	ds_read_b128 v[136:139], v189
	ds_read_b128 v[132:135], v185 offset:4096
	ds_read_b128 v[140:143], v189 offset:4096
	s_waitcnt lgkmcnt(4)
	v_mfma_f32_32x32x16_bf16 v[112:127], v[160:163], v[168:171], v[112:127]
	v_mfma_f32_32x32x16_bf16 v[96:111], v[160:163], v[172:175], v[96:111]
	v_mfma_f32_32x32x16_bf16 v[48:63], v[164:167], v[168:171], v[48:63]
	v_mfma_f32_32x32x16_bf16 v[32:47], v[164:167], v[172:175], v[32:47]
	ds_read_b128 v[160:163], v186
	ds_read_b128 v[168:171], v190
	ds_read_b128 v[164:167], v186 offset:4096
	ds_read_b128 v[172:175], v190 offset:4096
	s_waitcnt lgkmcnt(4)
	v_mfma_f32_32x32x16_bf16 v[112:127], v[128:131], v[136:139], v[112:127]
	v_mfma_f32_32x32x16_bf16 v[96:111], v[128:131], v[140:143], v[96:111]
	v_mfma_f32_32x32x16_bf16 v[48:63], v[132:135], v[136:139], v[48:63]
	v_mfma_f32_32x32x16_bf16 v[32:47], v[132:135], v[140:143], v[32:47]
	ds_read_b128 v[128:131], v187
	ds_read_b128 v[136:139], v191
	ds_read_b128 v[132:135], v187 offset:4096
	ds_read_b128 v[140:143], v191 offset:4096
	s_waitcnt lgkmcnt(4)
	v_mfma_f32_32x32x16_bf16 v[112:127], v[160:163], v[168:171], v[112:127]
	v_mfma_f32_32x32x16_bf16 v[96:111], v[160:163], v[172:175], v[96:111]
	v_mfma_f32_32x32x16_bf16 v[48:63], v[164:167], v[168:171], v[48:63]
	v_mfma_f32_32x32x16_bf16 v[32:47], v[164:167], v[172:175], v[32:47]
	s_waitcnt vmcnt(0) lgkmcnt(0)
	s_barrier
	ds_read_b128 v[160:163], v240
	ds_read_b128 v[168:171], v244
	ds_read_b128 v[164:167], v240 offset:4096
	ds_read_b128 v[172:175], v244 offset:4096
	s_add_u32 s20, s16, 768
	s_addc_u32 s21, s17, 0
	s_add_u32 s24, s18, 768
	s_addc_u32 s25, s19, 0
	s_add_u32 m0, s27, 0
	v_mfma_f32_32x32x16_bf16 v[112:127], v[128:131], v[136:139], v[112:127]
	global_load_lds_dwordx4 v192, s[20:21]
	s_add_u32 m0, s27, 32768
	v_mfma_f32_32x32x16_bf16 v[96:111], v[128:131], v[140:143], v[96:111]
	global_load_lds_dwordx4 v192, s[24:25]
	s_add_u32 m0, s27, 8192
	v_mfma_f32_32x32x16_bf16 v[48:63], v[132:135], v[136:139], v[48:63]
	global_load_lds_dwordx4 v194, s[20:21]
	s_add_u32 m0, s27, 40960
	v_mfma_f32_32x32x16_bf16 v[32:47], v[132:135], v[140:143], v[32:47]
	global_load_lds_dwordx4 v194, s[24:25]
	s_add_u32 m0, s27, 16384
	s_nop 0
	global_load_lds_dwordx4 v196, s[20:21]
	s_add_u32 m0, s27, 49152
	s_nop 0
	global_load_lds_dwordx4 v196, s[24:25]
	s_add_u32 m0, s27, 24576
	s_nop 0
	global_load_lds_dwordx4 v198, s[20:21]
	s_add_u32 m0, s27, 57344
	s_nop 0
	global_load_lds_dwordx4 v198, s[24:25]
	ds_read_b128 v[128:131], v241
	ds_read_b128 v[136:139], v245
	ds_read_b128 v[132:135], v241 offset:4096
	ds_read_b128 v[140:143], v245 offset:4096
	s_waitcnt lgkmcnt(4)
	v_mfma_f32_32x32x16_bf16 v[112:127], v[160:163], v[168:171], v[112:127]
	v_mfma_f32_32x32x16_bf16 v[96:111], v[160:163], v[172:175], v[96:111]
	v_mfma_f32_32x32x16_bf16 v[48:63], v[164:167], v[168:171], v[48:63]
	v_mfma_f32_32x32x16_bf16 v[32:47], v[164:167], v[172:175], v[32:47]
	ds_read_b128 v[160:163], v242
	ds_read_b128 v[168:171], v246
	ds_read_b128 v[164:167], v242 offset:4096
	ds_read_b128 v[172:175], v246 offset:4096
	s_waitcnt lgkmcnt(4)
	v_mfma_f32_32x32x16_bf16 v[112:127], v[128:131], v[136:139], v[112:127]
	v_mfma_f32_32x32x16_bf16 v[96:111], v[128:131], v[140:143], v[96:111]
	v_mfma_f32_32x32x16_bf16 v[48:63], v[132:135], v[136:139], v[48:63]
	v_mfma_f32_32x32x16_bf16 v[32:47], v[132:135], v[140:143], v[32:47]
	ds_read_b128 v[128:131], v243
	ds_read_b128 v[136:139], v247
	ds_read_b128 v[132:135], v243 offset:4096
	ds_read_b128 v[140:143], v247 offset:4096
	s_waitcnt lgkmcnt(4)
	v_mfma_f32_32x32x16_bf16 v[112:127], v[160:163], v[168:171], v[112:127]
	v_mfma_f32_32x32x16_bf16 v[96:111], v[160:163], v[172:175], v[96:111]
	v_mfma_f32_32x32x16_bf16 v[48:63], v[164:167], v[168:171], v[48:63]
	v_mfma_f32_32x32x16_bf16 v[32:47], v[164:167], v[172:175], v[32:47]
	s_waitcnt vmcnt(0) lgkmcnt(0)
	s_barrier
	ds_read_b128 v[160:163], v184
	ds_read_b128 v[168:171], v188
	ds_read_b128 v[164:167], v184 offset:4096
	ds_read_b128 v[172:175], v188 offset:4096
	s_add_u32 s20, s16, 896
	s_addc_u32 s21, s17, 0
	s_add_u32 s24, s18, 896
	s_addc_u32 s25, s19, 0
	s_add_u32 m0, s27, 65536
	v_mfma_f32_32x32x16_bf16 v[112:127], v[128:131], v[136:139], v[112:127]
	global_load_lds_dwordx4 v192, s[20:21]
	s_add_u32 m0, s27, 98304
	v_mfma_f32_32x32x16_bf16 v[96:111], v[128:131], v[140:143], v[96:111]
	global_load_lds_dwordx4 v192, s[24:25]
	s_add_u32 m0, s27, 73728
	v_mfma_f32_32x32x16_bf16 v[48:63], v[132:135], v[136:139], v[48:63]
	global_load_lds_dwordx4 v194, s[20:21]
	s_add_u32 m0, s27, 106496
	v_mfma_f32_32x32x16_bf16 v[32:47], v[132:135], v[140:143], v[32:47]
	global_load_lds_dwordx4 v194, s[24:25]
	s_add_u32 m0, s27, 81920
	s_nop 0
	global_load_lds_dwordx4 v196, s[20:21]
	s_add_u32 m0, s27, 114688
	s_nop 0
	global_load_lds_dwordx4 v196, s[24:25]
	s_add_u32 m0, s27, 90112
	s_nop 0
	global_load_lds_dwordx4 v198, s[20:21]
	s_add_u32 m0, s27, 122880
	s_nop 0
	global_load_lds_dwordx4 v198, s[24:25]
	ds_read_b128 v[128:131], v185
	ds_read_b128 v[136:139], v189
	ds_read_b128 v[132:135], v185 offset:4096
	ds_read_b128 v[140:143], v189 offset:4096
	s_waitcnt lgkmcnt(4)
	v_mfma_f32_32x32x16_bf16 v[112:127], v[160:163], v[168:171], v[112:127]
	v_mfma_f32_32x32x16_bf16 v[96:111], v[160:163], v[172:175], v[96:111]
	v_mfma_f32_32x32x16_bf16 v[48:63], v[164:167], v[168:171], v[48:63]
	v_mfma_f32_32x32x16_bf16 v[32:47], v[164:167], v[172:175], v[32:47]
	ds_read_b128 v[160:163], v186
	ds_read_b128 v[168:171], v190
	ds_read_b128 v[164:167], v186 offset:4096
	ds_read_b128 v[172:175], v190 offset:4096
	s_waitcnt lgkmcnt(4)
	v_mfma_f32_32x32x16_bf16 v[112:127], v[128:131], v[136:139], v[112:127]
	v_mfma_f32_32x32x16_bf16 v[96:111], v[128:131], v[140:143], v[96:111]
	v_mfma_f32_32x32x16_bf16 v[48:63], v[132:135], v[136:139], v[48:63]
	v_mfma_f32_32x32x16_bf16 v[32:47], v[132:135], v[140:143], v[32:47]
	ds_read_b128 v[128:131], v187
	ds_read_b128 v[136:139], v191
	ds_read_b128 v[132:135], v187 offset:4096
	ds_read_b128 v[140:143], v191 offset:4096
	s_waitcnt lgkmcnt(4)
	v_mfma_f32_32x32x16_bf16 v[112:127], v[160:163], v[168:171], v[112:127]
	v_mfma_f32_32x32x16_bf16 v[96:111], v[160:163], v[172:175], v[96:111]
	v_mfma_f32_32x32x16_bf16 v[48:63], v[164:167], v[168:171], v[48:63]
	v_mfma_f32_32x32x16_bf16 v[32:47], v[164:167], v[172:175], v[32:47]
	s_waitcnt vmcnt(0) lgkmcnt(0)
	s_barrier
	ds_read_b128 v[160:163], v240
	ds_read_b128 v[168:171], v244
	ds_read_b128 v[164:167], v240 offset:4096
	ds_read_b128 v[172:175], v244 offset:4096
	s_add_u32 s20, s16, 1024
	s_addc_u32 s21, s17, 0
	s_add_u32 s24, s18, 1024
	s_addc_u32 s25, s19, 0
	s_add_u32 m0, s27, 0
	v_mfma_f32_32x32x16_bf16 v[112:127], v[128:131], v[136:139], v[112:127]
	global_load_lds_dwordx4 v192, s[20:21]
	s_add_u32 m0, s27, 32768
	v_mfma_f32_32x32x16_bf16 v[96:111], v[128:131], v[140:143], v[96:111]
	global_load_lds_dwordx4 v192, s[24:25]
	s_add_u32 m0, s27, 8192
	v_mfma_f32_32x32x16_bf16 v[48:63], v[132:135], v[136:139], v[48:63]
	global_load_lds_dwordx4 v194, s[20:21]
	s_add_u32 m0, s27, 40960
	v_mfma_f32_32x32x16_bf16 v[32:47], v[132:135], v[140:143], v[32:47]
	global_load_lds_dwordx4 v194, s[24:25]
	s_add_u32 m0, s27, 16384
	s_nop 0
	global_load_lds_dwordx4 v196, s[20:21]
	s_add_u32 m0, s27, 49152
	s_nop 0
	global_load_lds_dwordx4 v196, s[24:25]
	s_add_u32 m0, s27, 24576
	s_nop 0
	global_load_lds_dwordx4 v198, s[20:21]
	s_add_u32 m0, s27, 57344
	s_nop 0
	global_load_lds_dwordx4 v198, s[24:25]
	ds_read_b128 v[128:131], v241
	ds_read_b128 v[136:139], v245
	ds_read_b128 v[132:135], v241 offset:4096
	ds_read_b128 v[140:143], v245 offset:4096
	s_waitcnt lgkmcnt(4)
	v_mfma_f32_32x32x16_bf16 v[112:127], v[160:163], v[168:171], v[112:127]
	v_mfma_f32_32x32x16_bf16 v[96:111], v[160:163], v[172:175], v[96:111]
	v_mfma_f32_32x32x16_bf16 v[48:63], v[164:167], v[168:171], v[48:63]
	v_mfma_f32_32x32x16_bf16 v[32:47], v[164:167], v[172:175], v[32:47]
	ds_read_b128 v[160:163], v242
	ds_read_b128 v[168:171], v246
	ds_read_b128 v[164:167], v242 offset:4096
	ds_read_b128 v[172:175], v246 offset:4096
	s_waitcnt lgkmcnt(4)
	v_mfma_f32_32x32x16_bf16 v[112:127], v[128:131], v[136:139], v[112:127]
	v_mfma_f32_32x32x16_bf16 v[96:111], v[128:131], v[140:143], v[96:111]
	v_mfma_f32_32x32x16_bf16 v[48:63], v[132:135], v[136:139], v[48:63]
	v_mfma_f32_32x32x16_bf16 v[32:47], v[132:135], v[140:143], v[32:47]
	ds_read_b128 v[128:131], v243
	ds_read_b128 v[136:139], v247
	ds_read_b128 v[132:135], v243 offset:4096
	ds_read_b128 v[140:143], v247 offset:4096
	s_waitcnt lgkmcnt(4)
	v_mfma_f32_32x32x16_bf16 v[112:127], v[160:163], v[168:171], v[112:127]
	v_mfma_f32_32x32x16_bf16 v[96:111], v[160:163], v[172:175], v[96:111]
	v_mfma_f32_32x32x16_bf16 v[48:63], v[164:167], v[168:171], v[48:63]
	v_mfma_f32_32x32x16_bf16 v[32:47], v[164:167], v[172:175], v[32:47]
	s_waitcnt vmcnt(0) lgkmcnt(0)
	s_barrier
	ds_read_b128 v[160:163], v184
	ds_read_b128 v[168:171], v188
	ds_read_b128 v[164:167], v184 offset:4096
	ds_read_b128 v[172:175], v188 offset:4096
	s_add_u32 s20, s16, 1152
	s_addc_u32 s21, s17, 0
	s_add_u32 s24, s18, 1152
	s_addc_u32 s25, s19, 0
	s_add_u32 m0, s27, 65536
	v_mfma_f32_32x32x16_bf16 v[112:127], v[128:131], v[136:139], v[112:127]
	global_load_lds_dwordx4 v192, s[20:21]
	s_add_u32 m0, s27, 98304
	v_mfma_f32_32x32x16_bf16 v[96:111], v[128:131], v[140:143], v[96:111]
	global_load_lds_dwordx4 v192, s[24:25]
	s_add_u32 m0, s27, 73728
	v_mfma_f32_32x32x16_bf16 v[48:63], v[132:135], v[136:139], v[48:63]
	global_load_lds_dwordx4 v194, s[20:21]
	s_add_u32 m0, s27, 106496
	v_mfma_f32_32x32x16_bf16 v[32:47], v[132:135], v[140:143], v[32:47]
	global_load_lds_dwordx4 v194, s[24:25]
	s_add_u32 m0, s27, 81920
	s_nop 0
	global_load_lds_dwordx4 v196, s[20:21]
	s_add_u32 m0, s27, 114688
	s_nop 0
	global_load_lds_dwordx4 v196, s[24:25]
	s_add_u32 m0, s27, 90112
	s_nop 0
	global_load_lds_dwordx4 v198, s[20:21]
	s_add_u32 m0, s27, 122880
	s_nop 0
	global_load_lds_dwordx4 v198, s[24:25]
	ds_read_b128 v[128:131], v185
	ds_read_b128 v[136:139], v189
	ds_read_b128 v[132:135], v185 offset:4096
	ds_read_b128 v[140:143], v189 offset:4096
	s_waitcnt lgkmcnt(4)
	v_mfma_f32_32x32x16_bf16 v[112:127], v[160:163], v[168:171], v[112:127]
	v_mfma_f32_32x32x16_bf16 v[96:111], v[160:163], v[172:175], v[96:111]
	v_mfma_f32_32x32x16_bf16 v[48:63], v[164:167], v[168:171], v[48:63]
	v_mfma_f32_32x32x16_bf16 v[32:47], v[164:167], v[172:175], v[32:47]
	ds_read_b128 v[160:163], v186
	ds_read_b128 v[168:171], v190
	ds_read_b128 v[164:167], v186 offset:4096
	ds_read_b128 v[172:175], v190 offset:4096
	s_waitcnt lgkmcnt(4)
	v_mfma_f32_32x32x16_bf16 v[112:127], v[128:131], v[136:139], v[112:127]
	v_mfma_f32_32x32x16_bf16 v[96:111], v[128:131], v[140:143], v[96:111]
	v_mfma_f32_32x32x16_bf16 v[48:63], v[132:135], v[136:139], v[48:63]
	v_mfma_f32_32x32x16_bf16 v[32:47], v[132:135], v[140:143], v[32:47]
	ds_read_b128 v[128:131], v187
	ds_read_b128 v[136:139], v191
	ds_read_b128 v[132:135], v187 offset:4096
	ds_read_b128 v[140:143], v191 offset:4096
	s_waitcnt lgkmcnt(4)
	v_mfma_f32_32x32x16_bf16 v[112:127], v[160:163], v[168:171], v[112:127]
	v_mfma_f32_32x32x16_bf16 v[96:111], v[160:163], v[172:175], v[96:111]
	v_mfma_f32_32x32x16_bf16 v[48:63], v[164:167], v[168:171], v[48:63]
	v_mfma_f32_32x32x16_bf16 v[32:47], v[164:167], v[172:175], v[32:47]
	s_waitcnt vmcnt(0) lgkmcnt(0)
	s_barrier
	ds_read_b128 v[160:163], v240
	ds_read_b128 v[168:171], v244
	ds_read_b128 v[164:167], v240 offset:4096
	ds_read_b128 v[172:175], v244 offset:4096
	s_add_u32 s20, s16, 1280
	s_addc_u32 s21, s17, 0
	s_add_u32 s24, s18, 1280
	s_addc_u32 s25, s19, 0
	s_add_u32 m0, s27, 0
	v_mfma_f32_32x32x16_bf16 v[112:127], v[128:131], v[136:139], v[112:127]
	global_load_lds_dwordx4 v192, s[20:21]
	s_add_u32 m0, s27, 32768
	v_mfma_f32_32x32x16_bf16 v[96:111], v[128:131], v[140:143], v[96:111]
	global_load_lds_dwordx4 v192, s[24:25]
	s_add_u32 m0, s27, 8192
	v_mfma_f32_32x32x16_bf16 v[48:63], v[132:135], v[136:139], v[48:63]
	global_load_lds_dwordx4 v194, s[20:21]
	s_add_u32 m0, s27, 40960
	v_mfma_f32_32x32x16_bf16 v[32:47], v[132:135], v[140:143], v[32:47]
	global_load_lds_dwordx4 v194, s[24:25]
	s_add_u32 m0, s27, 16384
	s_nop 0
	global_load_lds_dwordx4 v196, s[20:21]
	s_add_u32 m0, s27, 49152
	s_nop 0
	global_load_lds_dwordx4 v196, s[24:25]
	s_add_u32 m0, s27, 24576
	s_nop 0
	global_load_lds_dwordx4 v198, s[20:21]
	s_add_u32 m0, s27, 57344
	s_nop 0
	global_load_lds_dwordx4 v198, s[24:25]
	ds_read_b128 v[128:131], v241
	ds_read_b128 v[136:139], v245
	ds_read_b128 v[132:135], v241 offset:4096
	ds_read_b128 v[140:143], v245 offset:4096
	s_waitcnt lgkmcnt(4)
	v_mfma_f32_32x32x16_bf16 v[112:127], v[160:163], v[168:171], v[112:127]
	v_mfma_f32_32x32x16_bf16 v[96:111], v[160:163], v[172:175], v[96:111]
	v_mfma_f32_32x32x16_bf16 v[48:63], v[164:167], v[168:171], v[48:63]
	v_mfma_f32_32x32x16_bf16 v[32:47], v[164:167], v[172:175], v[32:47]
	ds_read_b128 v[160:163], v242
	ds_read_b128 v[168:171], v246
	ds_read_b128 v[164:167], v242 offset:4096
	ds_read_b128 v[172:175], v246 offset:4096
	s_waitcnt lgkmcnt(4)
	v_mfma_f32_32x32x16_bf16 v[112:127], v[128:131], v[136:139], v[112:127]
	v_mfma_f32_32x32x16_bf16 v[96:111], v[128:131], v[140:143], v[96:111]
	v_mfma_f32_32x32x16_bf16 v[48:63], v[132:135], v[136:139], v[48:63]
	v_mfma_f32_32x32x16_bf16 v[32:47], v[132:135], v[140:143], v[32:47]
	ds_read_b128 v[128:131], v243
	ds_read_b128 v[136:139], v247
	ds_read_b128 v[132:135], v243 offset:4096
	ds_read_b128 v[140:143], v247 offset:4096
	s_waitcnt lgkmcnt(4)
	v_mfma_f32_32x32x16_bf16 v[112:127], v[160:163], v[168:171], v[112:127]
	v_mfma_f32_32x32x16_bf16 v[96:111], v[160:163], v[172:175], v[96:111]
	v_mfma_f32_32x32x16_bf16 v[48:63], v[164:167], v[168:171], v[48:63]
	v_mfma_f32_32x32x16_bf16 v[32:47], v[164:167], v[172:175], v[32:47]
	s_waitcnt vmcnt(0) lgkmcnt(0)
	s_barrier
	ds_read_b128 v[160:163], v184
	ds_read_b128 v[168:171], v188
	ds_read_b128 v[164:167], v184 offset:4096
	ds_read_b128 v[172:175], v188 offset:4096
	s_add_u32 s20, s16, 1408
	s_addc_u32 s21, s17, 0
	s_add_u32 s24, s18, 1408
	s_addc_u32 s25, s19, 0
	s_add_u32 m0, s27, 65536
	v_mfma_f32_32x32x16_bf16 v[112:127], v[128:131], v[136:139], v[112:127]
	global_load_lds_dwordx4 v192, s[20:21]
	s_add_u32 m0, s27, 98304
	v_mfma_f32_32x32x16_bf16 v[96:111], v[128:131], v[140:143], v[96:111]
	global_load_lds_dwordx4 v192, s[24:25]
	s_add_u32 m0, s27, 73728
	v_mfma_f32_32x32x16_bf16 v[48:63], v[132:135], v[136:139], v[48:63]
	global_load_lds_dwordx4 v194, s[20:21]
	s_add_u32 m0, s27, 106496
	v_mfma_f32_32x32x16_bf16 v[32:47], v[132:135], v[140:143], v[32:47]
	global_load_lds_dwordx4 v194, s[24:25]
	s_add_u32 m0, s27, 81920
	s_nop 0
	global_load_lds_dwordx4 v196, s[20:21]
	s_add_u32 m0, s27, 114688
	s_nop 0
	global_load_lds_dwordx4 v196, s[24:25]
	s_add_u32 m0, s27, 90112
	s_nop 0
	global_load_lds_dwordx4 v198, s[20:21]
	s_add_u32 m0, s27, 122880
	s_nop 0
	global_load_lds_dwordx4 v198, s[24:25]
	ds_read_b128 v[128:131], v185
	ds_read_b128 v[136:139], v189
	ds_read_b128 v[132:135], v185 offset:4096
	ds_read_b128 v[140:143], v189 offset:4096
	s_waitcnt lgkmcnt(4)
	v_mfma_f32_32x32x16_bf16 v[112:127], v[160:163], v[168:171], v[112:127]
	v_mfma_f32_32x32x16_bf16 v[96:111], v[160:163], v[172:175], v[96:111]
	v_mfma_f32_32x32x16_bf16 v[48:63], v[164:167], v[168:171], v[48:63]
	v_mfma_f32_32x32x16_bf16 v[32:47], v[164:167], v[172:175], v[32:47]
	ds_read_b128 v[160:163], v186
	ds_read_b128 v[168:171], v190
	ds_read_b128 v[164:167], v186 offset:4096
	ds_read_b128 v[172:175], v190 offset:4096
	s_waitcnt lgkmcnt(4)
	v_mfma_f32_32x32x16_bf16 v[112:127], v[128:131], v[136:139], v[112:127]
	v_mfma_f32_32x32x16_bf16 v[96:111], v[128:131], v[140:143], v[96:111]
	v_mfma_f32_32x32x16_bf16 v[48:63], v[132:135], v[136:139], v[48:63]
	v_mfma_f32_32x32x16_bf16 v[32:47], v[132:135], v[140:143], v[32:47]
	ds_read_b128 v[128:131], v187
	ds_read_b128 v[136:139], v191
	ds_read_b128 v[132:135], v187 offset:4096
	ds_read_b128 v[140:143], v191 offset:4096
	s_waitcnt lgkmcnt(4)
	v_mfma_f32_32x32x16_bf16 v[112:127], v[160:163], v[168:171], v[112:127]
	v_mfma_f32_32x32x16_bf16 v[96:111], v[160:163], v[172:175], v[96:111]
	v_mfma_f32_32x32x16_bf16 v[48:63], v[164:167], v[168:171], v[48:63]
	v_mfma_f32_32x32x16_bf16 v[32:47], v[164:167], v[172:175], v[32:47]
	s_waitcnt vmcnt(0) lgkmcnt(0)
	s_barrier
	ds_read_b128 v[160:163], v240
	ds_read_b128 v[168:171], v244
	ds_read_b128 v[164:167], v240 offset:4096
	ds_read_b128 v[172:175], v244 offset:4096
	s_add_u32 s20, s16, 1536
	s_addc_u32 s21, s17, 0
	s_add_u32 s24, s18, 1536
	s_addc_u32 s25, s19, 0
	s_add_u32 m0, s27, 0
	v_mfma_f32_32x32x16_bf16 v[112:127], v[128:131], v[136:139], v[112:127]
	global_load_lds_dwordx4 v192, s[20:21]
	s_add_u32 m0, s27, 32768
	v_mfma_f32_32x32x16_bf16 v[96:111], v[128:131], v[140:143], v[96:111]
	global_load_lds_dwordx4 v192, s[24:25]
	s_add_u32 m0, s27, 8192
	v_mfma_f32_32x32x16_bf16 v[48:63], v[132:135], v[136:139], v[48:63]
	global_load_lds_dwordx4 v194, s[20:21]
	s_add_u32 m0, s27, 40960
	v_mfma_f32_32x32x16_bf16 v[32:47], v[132:135], v[140:143], v[32:47]
	global_load_lds_dwordx4 v194, s[24:25]
	s_add_u32 m0, s27, 16384
	s_nop 0
	global_load_lds_dwordx4 v196, s[20:21]
	s_add_u32 m0, s27, 49152
	s_nop 0
	global_load_lds_dwordx4 v196, s[24:25]
	s_add_u32 m0, s27, 24576
	s_nop 0
	global_load_lds_dwordx4 v198, s[20:21]
	s_add_u32 m0, s27, 57344
	s_nop 0
	global_load_lds_dwordx4 v198, s[24:25]
	ds_read_b128 v[128:131], v241
	ds_read_b128 v[136:139], v245
	ds_read_b128 v[132:135], v241 offset:4096
	ds_read_b128 v[140:143], v245 offset:4096
	s_waitcnt lgkmcnt(4)
	v_mfma_f32_32x32x16_bf16 v[112:127], v[160:163], v[168:171], v[112:127]
	v_mfma_f32_32x32x16_bf16 v[96:111], v[160:163], v[172:175], v[96:111]
	v_mfma_f32_32x32x16_bf16 v[48:63], v[164:167], v[168:171], v[48:63]
	v_mfma_f32_32x32x16_bf16 v[32:47], v[164:167], v[172:175], v[32:47]
	ds_read_b128 v[160:163], v242
	ds_read_b128 v[168:171], v246
	ds_read_b128 v[164:167], v242 offset:4096
	ds_read_b128 v[172:175], v246 offset:4096
	s_waitcnt lgkmcnt(4)
	v_mfma_f32_32x32x16_bf16 v[112:127], v[128:131], v[136:139], v[112:127]
	v_mfma_f32_32x32x16_bf16 v[96:111], v[128:131], v[140:143], v[96:111]
	v_mfma_f32_32x32x16_bf16 v[48:63], v[132:135], v[136:139], v[48:63]
	v_mfma_f32_32x32x16_bf16 v[32:47], v[132:135], v[140:143], v[32:47]
	ds_read_b128 v[128:131], v243
	ds_read_b128 v[136:139], v247
	ds_read_b128 v[132:135], v243 offset:4096
	ds_read_b128 v[140:143], v247 offset:4096
	s_waitcnt lgkmcnt(4)
	v_mfma_f32_32x32x16_bf16 v[112:127], v[160:163], v[168:171], v[112:127]
	v_mfma_f32_32x32x16_bf16 v[96:111], v[160:163], v[172:175], v[96:111]
	v_mfma_f32_32x32x16_bf16 v[48:63], v[164:167], v[168:171], v[48:63]
	v_mfma_f32_32x32x16_bf16 v[32:47], v[164:167], v[172:175], v[32:47]
	s_waitcnt vmcnt(0) lgkmcnt(0)
	s_barrier
	ds_read_b128 v[160:163], v184
	ds_read_b128 v[168:171], v188
	ds_read_b128 v[164:167], v184 offset:4096
	ds_read_b128 v[172:175], v188 offset:4096
	s_add_u32 s20, s16, 1664
	s_addc_u32 s21, s17, 0
	s_add_u32 s24, s18, 1664
	s_addc_u32 s25, s19, 0
	s_add_u32 m0, s27, 65536
	v_mfma_f32_32x32x16_bf16 v[112:127], v[128:131], v[136:139], v[112:127]
	global_load_lds_dwordx4 v192, s[20:21]
	s_add_u32 m0, s27, 98304
	v_mfma_f32_32x32x16_bf16 v[96:111], v[128:131], v[140:143], v[96:111]
	global_load_lds_dwordx4 v192, s[24:25]
	s_add_u32 m0, s27, 73728
	v_mfma_f32_32x32x16_bf16 v[48:63], v[132:135], v[136:139], v[48:63]
	global_load_lds_dwordx4 v194, s[20:21]
	s_add_u32 m0, s27, 106496
	v_mfma_f32_32x32x16_bf16 v[32:47], v[132:135], v[140:143], v[32:47]
	global_load_lds_dwordx4 v194, s[24:25]
	s_add_u32 m0, s27, 81920
	s_nop 0
	global_load_lds_dwordx4 v196, s[20:21]
	s_add_u32 m0, s27, 114688
	s_nop 0
	global_load_lds_dwordx4 v196, s[24:25]
	s_add_u32 m0, s27, 90112
	s_nop 0
	global_load_lds_dwordx4 v198, s[20:21]
	s_add_u32 m0, s27, 122880
	s_nop 0
	global_load_lds_dwordx4 v198, s[24:25]
	ds_read_b128 v[128:131], v185
	ds_read_b128 v[136:139], v189
	ds_read_b128 v[132:135], v185 offset:4096
	ds_read_b128 v[140:143], v189 offset:4096
	s_waitcnt lgkmcnt(4)
	v_mfma_f32_32x32x16_bf16 v[112:127], v[160:163], v[168:171], v[112:127]
	v_mfma_f32_32x32x16_bf16 v[96:111], v[160:163], v[172:175], v[96:111]
	v_mfma_f32_32x32x16_bf16 v[48:63], v[164:167], v[168:171], v[48:63]
	v_mfma_f32_32x32x16_bf16 v[32:47], v[164:167], v[172:175], v[32:47]
	ds_read_b128 v[160:163], v186
	ds_read_b128 v[168:171], v190
	ds_read_b128 v[164:167], v186 offset:4096
	ds_read_b128 v[172:175], v190 offset:4096
	s_waitcnt lgkmcnt(4)
	v_mfma_f32_32x32x16_bf16 v[112:127], v[128:131], v[136:139], v[112:127]
	v_mfma_f32_32x32x16_bf16 v[96:111], v[128:131], v[140:143], v[96:111]
	v_mfma_f32_32x32x16_bf16 v[48:63], v[132:135], v[136:139], v[48:63]
	v_mfma_f32_32x32x16_bf16 v[32:47], v[132:135], v[140:143], v[32:47]
	ds_read_b128 v[128:131], v187
	ds_read_b128 v[136:139], v191
	ds_read_b128 v[132:135], v187 offset:4096
	ds_read_b128 v[140:143], v191 offset:4096
	s_waitcnt lgkmcnt(4)
	v_mfma_f32_32x32x16_bf16 v[112:127], v[160:163], v[168:171], v[112:127]
	v_mfma_f32_32x32x16_bf16 v[96:111], v[160:163], v[172:175], v[96:111]
	v_mfma_f32_32x32x16_bf16 v[48:63], v[164:167], v[168:171], v[48:63]
	v_mfma_f32_32x32x16_bf16 v[32:47], v[164:167], v[172:175], v[32:47]
	s_waitcnt vmcnt(0) lgkmcnt(0)
	s_barrier
	ds_read_b128 v[160:163], v240
	ds_read_b128 v[168:171], v244
	ds_read_b128 v[164:167], v240 offset:4096
	ds_read_b128 v[172:175], v244 offset:4096
	s_add_u32 s20, s16, 1792
	s_addc_u32 s21, s17, 0
	s_add_u32 s24, s18, 1792
	s_addc_u32 s25, s19, 0
	s_add_u32 m0, s27, 0
	v_mfma_f32_32x32x16_bf16 v[112:127], v[128:131], v[136:139], v[112:127]
	global_load_lds_dwordx4 v192, s[20:21]
	s_add_u32 m0, s27, 32768
	v_mfma_f32_32x32x16_bf16 v[96:111], v[128:131], v[140:143], v[96:111]
	global_load_lds_dwordx4 v192, s[24:25]
	s_add_u32 m0, s27, 8192
	v_mfma_f32_32x32x16_bf16 v[48:63], v[132:135], v[136:139], v[48:63]
	global_load_lds_dwordx4 v194, s[20:21]
	s_add_u32 m0, s27, 40960
	v_mfma_f32_32x32x16_bf16 v[32:47], v[132:135], v[140:143], v[32:47]
	global_load_lds_dwordx4 v194, s[24:25]
	s_add_u32 m0, s27, 16384
	s_nop 0
	global_load_lds_dwordx4 v196, s[20:21]
	s_add_u32 m0, s27, 49152
	s_nop 0
	global_load_lds_dwordx4 v196, s[24:25]
	s_add_u32 m0, s27, 24576
	s_nop 0
	global_load_lds_dwordx4 v198, s[20:21]
	s_add_u32 m0, s27, 57344
	s_nop 0
	global_load_lds_dwordx4 v198, s[24:25]
	ds_read_b128 v[128:131], v241
	ds_read_b128 v[136:139], v245
	ds_read_b128 v[132:135], v241 offset:4096
	ds_read_b128 v[140:143], v245 offset:4096
	s_waitcnt lgkmcnt(4)
	v_mfma_f32_32x32x16_bf16 v[112:127], v[160:163], v[168:171], v[112:127]
	v_mfma_f32_32x32x16_bf16 v[96:111], v[160:163], v[172:175], v[96:111]
	v_mfma_f32_32x32x16_bf16 v[48:63], v[164:167], v[168:171], v[48:63]
	v_mfma_f32_32x32x16_bf16 v[32:47], v[164:167], v[172:175], v[32:47]
	ds_read_b128 v[160:163], v242
	ds_read_b128 v[168:171], v246
	ds_read_b128 v[164:167], v242 offset:4096
	ds_read_b128 v[172:175], v246 offset:4096
	s_waitcnt lgkmcnt(4)
	v_mfma_f32_32x32x16_bf16 v[112:127], v[128:131], v[136:139], v[112:127]
	v_mfma_f32_32x32x16_bf16 v[96:111], v[128:131], v[140:143], v[96:111]
	v_mfma_f32_32x32x16_bf16 v[48:63], v[132:135], v[136:139], v[48:63]
	v_mfma_f32_32x32x16_bf16 v[32:47], v[132:135], v[140:143], v[32:47]
	ds_read_b128 v[128:131], v243
	ds_read_b128 v[136:139], v247
	ds_read_b128 v[132:135], v243 offset:4096
	ds_read_b128 v[140:143], v247 offset:4096
	s_waitcnt lgkmcnt(4)
	v_mfma_f32_32x32x16_bf16 v[112:127], v[160:163], v[168:171], v[112:127]
	v_mfma_f32_32x32x16_bf16 v[96:111], v[160:163], v[172:175], v[96:111]
	v_mfma_f32_32x32x16_bf16 v[48:63], v[164:167], v[168:171], v[48:63]
	v_mfma_f32_32x32x16_bf16 v[32:47], v[164:167], v[172:175], v[32:47]
	s_waitcnt vmcnt(0) lgkmcnt(0)
	s_barrier
	ds_read_b128 v[160:163], v184
	ds_read_b128 v[168:171], v188
	ds_read_b128 v[164:167], v184 offset:4096
	ds_read_b128 v[172:175], v188 offset:4096
	s_add_u32 s20, s16, 1920
	s_addc_u32 s21, s17, 0
	s_add_u32 s24, s18, 1920
	s_addc_u32 s25, s19, 0
	s_add_u32 m0, s27, 65536
	v_mfma_f32_32x32x16_bf16 v[112:127], v[128:131], v[136:139], v[112:127]
	global_load_lds_dwordx4 v192, s[20:21]
	s_add_u32 m0, s27, 98304
	v_mfma_f32_32x32x16_bf16 v[96:111], v[128:131], v[140:143], v[96:111]
	global_load_lds_dwordx4 v192, s[24:25]
	s_add_u32 m0, s27, 73728
	v_mfma_f32_32x32x16_bf16 v[48:63], v[132:135], v[136:139], v[48:63]
	global_load_lds_dwordx4 v194, s[20:21]
	s_add_u32 m0, s27, 106496
	v_mfma_f32_32x32x16_bf16 v[32:47], v[132:135], v[140:143], v[32:47]
	global_load_lds_dwordx4 v194, s[24:25]
	s_add_u32 m0, s27, 81920
	s_nop 0
	global_load_lds_dwordx4 v196, s[20:21]
	s_add_u32 m0, s27, 114688
	s_nop 0
	global_load_lds_dwordx4 v196, s[24:25]
	s_add_u32 m0, s27, 90112
	s_nop 0
	global_load_lds_dwordx4 v198, s[20:21]
	s_add_u32 m0, s27, 122880
	s_nop 0
	global_load_lds_dwordx4 v198, s[24:25]
	ds_read_b128 v[128:131], v185
	ds_read_b128 v[136:139], v189
	ds_read_b128 v[132:135], v185 offset:4096
	ds_read_b128 v[140:143], v189 offset:4096
	s_waitcnt lgkmcnt(4)
	v_mfma_f32_32x32x16_bf16 v[112:127], v[160:163], v[168:171], v[112:127]
	v_mfma_f32_32x32x16_bf16 v[96:111], v[160:163], v[172:175], v[96:111]
	v_mfma_f32_32x32x16_bf16 v[48:63], v[164:167], v[168:171], v[48:63]
	v_mfma_f32_32x32x16_bf16 v[32:47], v[164:167], v[172:175], v[32:47]
	ds_read_b128 v[160:163], v186
	ds_read_b128 v[168:171], v190
	ds_read_b128 v[164:167], v186 offset:4096
	ds_read_b128 v[172:175], v190 offset:4096
	s_waitcnt lgkmcnt(4)
	v_mfma_f32_32x32x16_bf16 v[112:127], v[128:131], v[136:139], v[112:127]
	v_mfma_f32_32x32x16_bf16 v[96:111], v[128:131], v[140:143], v[96:111]
	v_mfma_f32_32x32x16_bf16 v[48:63], v[132:135], v[136:139], v[48:63]
	v_mfma_f32_32x32x16_bf16 v[32:47], v[132:135], v[140:143], v[32:47]
	ds_read_b128 v[128:131], v187
	ds_read_b128 v[136:139], v191
	ds_read_b128 v[132:135], v187 offset:4096
	ds_read_b128 v[140:143], v191 offset:4096
	s_waitcnt lgkmcnt(4)
	v_mfma_f32_32x32x16_bf16 v[112:127], v[160:163], v[168:171], v[112:127]
	v_mfma_f32_32x32x16_bf16 v[96:111], v[160:163], v[172:175], v[96:111]
	v_mfma_f32_32x32x16_bf16 v[48:63], v[164:167], v[168:171], v[48:63]
	v_mfma_f32_32x32x16_bf16 v[32:47], v[164:167], v[172:175], v[32:47]
	s_waitcnt vmcnt(0) lgkmcnt(0)
	s_barrier
	ds_read_b128 v[160:163], v240
	ds_read_b128 v[168:171], v244
	ds_read_b128 v[164:167], v240 offset:4096
	ds_read_b128 v[172:175], v244 offset:4096
	s_add_u32 s37, s30, s42
	s_cmpk_ge_u32 s37, 0x780
	s_cbranch_scc1 .Lip11_lc_nonext
	s_mul_hi_u32 s38, s37, 0x92492493
	s_lshr_b32 s38, s38, 3
	s_mul_i32 s39, s38, 14
	s_sub_u32 s39, s37, s39
	s_sub_u32 s98, s37, 0x700
	s_cmpk_lt_u32 s37, 0x700
	s_cselect_b32 s39, s39, 14
	s_cselect_b32 s38, s38, s98
	s_lshl_b32 s98, s38, 19
	s_add_u32 s16, s4, s98
	s_addc_u32 s17, s5, 0
	s_lshl_b32 s98, s39, 19
	s_add_u32 s18, s6, s98
	s_addc_u32 s19, s7, 0
	s_add_u32 m0, s27, 0
	v_mfma_f32_32x32x16_bf16 v[112:127], v[128:131], v[136:139], v[112:127]
	global_load_lds_dwordx4 v192, s[16:17]
	s_add_u32 m0, s27, 32768
	v_mfma_f32_32x32x16_bf16 v[96:111], v[128:131], v[140:143], v[96:111]
	global_load_lds_dwordx4 v192, s[18:19]
	s_add_u32 m0, s27, 8192
	v_mfma_f32_32x32x16_bf16 v[48:63], v[132:135], v[136:139], v[48:63]
	global_load_lds_dwordx4 v194, s[16:17]
	s_add_u32 m0, s27, 40960
	v_mfma_f32_32x32x16_bf16 v[32:47], v[132:135], v[140:143], v[32:47]
	global_load_lds_dwordx4 v194, s[18:19]
	s_add_u32 m0, s27, 16384
	s_nop 0
	global_load_lds_dwordx4 v196, s[16:17]
	s_add_u32 m0, s27, 49152
	s_nop 0
	global_load_lds_dwordx4 v196, s[18:19]
	s_add_u32 m0, s27, 24576
	s_nop 0
	global_load_lds_dwordx4 v198, s[16:17]
	s_add_u32 m0, s27, 57344
	s_nop 0
	global_load_lds_dwordx4 v198, s[18:19]
	s_branch .Lip11_lc_join
.Lip11_lc_nonext:
	v_mfma_f32_32x32x16_bf16 v[112:127], v[128:131], v[136:139], v[112:127]
	v_mfma_f32_32x32x16_bf16 v[96:111], v[128:131], v[140:143], v[96:111]
	v_mfma_f32_32x32x16_bf16 v[48:63], v[132:135], v[136:139], v[48:63]
	v_mfma_f32_32x32x16_bf16 v[32:47], v[132:135], v[140:143], v[32:47]
.Lip11_lc_join:
	ds_read_b128 v[128:131], v241
	ds_read_b128 v[136:139], v245
	ds_read_b128 v[132:135], v241 offset:4096
	ds_read_b128 v[140:143], v245 offset:4096
	s_waitcnt lgkmcnt(4)
	v_mfma_f32_32x32x16_bf16 v[112:127], v[160:163], v[168:171], v[112:127]
	v_mfma_f32_32x32x16_bf16 v[96:111], v[160:163], v[172:175], v[96:111]
	v_mfma_f32_32x32x16_bf16 v[48:63], v[164:167], v[168:171], v[48:63]
	v_mfma_f32_32x32x16_bf16 v[32:47], v[164:167], v[172:175], v[32:47]
	ds_read_b128 v[160:163], v242
	ds_read_b128 v[168:171], v246
	ds_read_b128 v[164:167], v242 offset:4096
	ds_read_b128 v[172:175], v246 offset:4096
	s_waitcnt lgkmcnt(4)
	v_mfma_f32_32x32x16_bf16 v[112:127], v[128:131], v[136:139], v[112:127]
	v_mfma_f32_32x32x16_bf16 v[96:111], v[128:131], v[140:143], v[96:111]
	v_mfma_f32_32x32x16_bf16 v[48:63], v[132:135], v[136:139], v[48:63]
	v_mfma_f32_32x32x16_bf16 v[32:47], v[132:135], v[140:143], v[32:47]
	ds_read_b128 v[128:131], v243
	ds_read_b128 v[136:139], v247
	ds_read_b128 v[132:135], v243 offset:4096
	ds_read_b128 v[140:143], v247 offset:4096
	s_waitcnt lgkmcnt(4)
	v_mfma_f32_32x32x16_bf16 v[112:127], v[160:163], v[168:171], v[112:127]
	v_mfma_f32_32x32x16_bf16 v[96:111], v[160:163], v[172:175], v[96:111]
	v_mfma_f32_32x32x16_bf16 v[48:63], v[164:167], v[168:171], v[48:63]
	v_mfma_f32_32x32x16_bf16 v[32:47], v[164:167], v[172:175], v[32:47]
	s_waitcnt vmcnt(0) lgkmcnt(0)
	s_barrier
	v_mfma_f32_32x32x16_bf16 v[112:127], v[128:131], v[136:139], v[112:127]
	v_mfma_f32_32x32x16_bf16 v[96:111], v[128:131], v[140:143], v[96:111]
	v_mfma_f32_32x32x16_bf16 v[48:63], v[132:135], v[136:139], v[48:63]
	v_mfma_f32_32x32x16_bf16 v[32:47], v[132:135], v[140:143], v[32:47]
	s_branch .Lip11_epi

.LBB0_4482:
	ds_read_b128 v[128:131], v238
	ds_read_b128 v[136:139], v253
	ds_read_b128 v[132:135], v238 offset:4096
	ds_read_b128 v[140:143], v253 offset:4096
	ds_read_b128 v[144:147], v253 offset:8192
	ds_read_b128 v[148:151], v253 offset:12288
	s_waitcnt lgkmcnt(6)
	v_mfma_f32_32x32x16_bf16 v[112:127], v[188:191], v[196:199], v[112:127]
	v_mfma_f32_32x32x16_bf16 v[96:111], v[188:191], v[200:203], v[96:111]
	v_mfma_f32_32x32x16_bf16 v[80:95], v[188:191], v[204:207], v[80:95]
	v_mfma_f32_32x32x16_bf16 v[64:79], v[188:191], v[226:229], v[64:79]
	v_mfma_f32_32x32x16_bf16 v[48:63], v[192:195], v[196:199], v[48:63]
	v_mfma_f32_32x32x16_bf16 v[32:47], v[192:195], v[200:203], v[32:47]
	v_mfma_f32_32x32x16_bf16 v[16:31], v[192:195], v[204:207], v[16:31]
	v_mfma_f32_32x32x16_bf16 v[0:15], v[192:195], v[226:229], v[0:15]
	ds_read_b128 v[188:191], v239
	ds_read_b128 v[196:199], v254
	ds_read_b128 v[192:195], v239 offset:4096
	ds_read_b128 v[200:203], v254 offset:4096
	ds_read_b128 v[204:207], v254 offset:8192
	ds_read_b128 v[226:229], v254 offset:12288
	s_waitcnt lgkmcnt(6)
	v_mfma_f32_32x32x16_bf16 v[112:127], v[128:131], v[136:139], v[112:127]
	v_mfma_f32_32x32x16_bf16 v[96:111], v[128:131], v[140:143], v[96:111]
	v_mfma_f32_32x32x16_bf16 v[80:95], v[128:131], v[144:147], v[80:95]
	v_mfma_f32_32x32x16_bf16 v[64:79], v[128:131], v[148:151], v[64:79]
	v_mfma_f32_32x32x16_bf16 v[48:63], v[132:135], v[136:139], v[48:63]
	v_mfma_f32_32x32x16_bf16 v[32:47], v[132:135], v[140:143], v[32:47]
	v_mfma_f32_32x32x16_bf16 v[16:31], v[132:135], v[144:147], v[16:31]
	v_mfma_f32_32x32x16_bf16 v[0:15], v[132:135], v[148:151], v[0:15]
	ds_read_b128 v[128:131], v240
	ds_read_b128 v[136:139], v255
	ds_read_b128 v[132:135], v240 offset:4096
	ds_read_b128 v[140:143], v255 offset:4096
	ds_read_b128 v[144:147], v255 offset:8192
	ds_read_b128 v[148:151], v255 offset:12288
	s_waitcnt lgkmcnt(6)
	v_mfma_f32_32x32x16_bf16 v[112:127], v[188:191], v[196:199], v[112:127]
	v_mfma_f32_32x32x16_bf16 v[96:111], v[188:191], v[200:203], v[96:111]
	v_mfma_f32_32x32x16_bf16 v[80:95], v[188:191], v[204:207], v[80:95]
	v_mfma_f32_32x32x16_bf16 v[64:79], v[188:191], v[226:229], v[64:79]
	v_mfma_f32_32x32x16_bf16 v[48:63], v[192:195], v[196:199], v[48:63]
	v_mfma_f32_32x32x16_bf16 v[32:47], v[192:195], v[200:203], v[32:47]
	v_mfma_f32_32x32x16_bf16 v[16:31], v[192:195], v[204:207], v[16:31]
	v_mfma_f32_32x32x16_bf16 v[0:15], v[192:195], v[226:229], v[0:15]
	s_waitcnt vmcnt(0) lgkmcnt(0)
	s_barrier
	v_mfma_f32_32x32x16_bf16 v[112:127], v[128:131], v[136:139], v[112:127]
	v_mfma_f32_32x32x16_bf16 v[96:111], v[128:131], v[140:143], v[96:111]
	v_mfma_f32_32x32x16_bf16 v[80:95], v[128:131], v[144:147], v[80:95]
	v_mfma_f32_32x32x16_bf16 v[64:79], v[128:131], v[148:151], v[64:79]
	v_mfma_f32_32x32x16_bf16 v[48:63], v[132:135], v[136:139], v[48:63]
	v_mfma_f32_32x32x16_bf16 v[32:47], v[132:135], v[140:143], v[32:47]
	v_mfma_f32_32x32x16_bf16 v[16:31], v[132:135], v[144:147], v[16:31]
	v_mfma_f32_32x32x16_bf16 v[0:15], v[132:135], v[148:151], v[0:15]
	s_lshl_b32 s2, s5, 8
	s_sub_i32 s2, s2, s6
	v_mov_b32_e32 v168, v214
	s_add_i32 s55, s4, s30
	s_or_b32 s26, s2, s31
	s_ashr_i32 s27, s26, 31
	s_load_dwordx2 s[24:25], s[0:1], 0x140
	v_ashrrev_i32_e32 v180, 3, v168
	v_and_b32_e32 v183, -4, v180
	v_add_u32_e32 v225, s55, v183
	v_add_u32_e32 v190, 8, v225
	v_min_i32_e32 v190, 0x7fff, v190
	v_ashrrev_i32_e32 v190, 12, v190
	v_add_u32_e32 v190, 16, v190
	v_mul_hi_i32_i24_e32 v191, 0x3000, v190
	v_mul_i32_i24_e32 v190, 0x3000, v190
	v_min_i32_e32 v184, 0x7fff, v225
	v_ashrrev_i32_e32 v184, 12, v184
	v_and_b32_e32 v182, 31, v168
	v_add_u32_e32 v184, 16, v184
	v_or_b32_e32 v180, s26, v182
	v_mul_hi_i32_i24_e32 v185, 0x3000, v184
	v_mul_i32_i24_e32 v184, 0x3000, v184
	v_ashrrev_i32_e32 v181, 31, v180
	s_waitcnt lgkmcnt(0)
	v_lshl_add_u64 v[184:185], s[24:25], 0, v[184:185]
	v_lshl_add_u64 v[184:185], v[184:185], 0, s[18:19]
	v_lshlrev_b64 v[180:181], 2, v[180:181]
	v_lshl_add_u64 v[196:197], v[184:185], 0, v[180:181]
	v_lshl_add_u64 v[186:187], s[24:25], 0, v[190:191]
	v_add_u32_e32 v188, 9, v225
	v_add_u32_e32 v190, 10, v225
	v_min_i32_e32 v188, 0x7fff, v188
	v_min_i32_e32 v190, 0x7fff, v190
	v_ashrrev_i32_e32 v188, 12, v188
	v_ashrrev_i32_e32 v190, 12, v190
	v_add_u32_e32 v188, 16, v188
	v_add_u32_e32 v190, 16, v190
	v_mul_hi_i32_i24_e32 v189, 0x3000, v188
	v_mul_i32_i24_e32 v188, 0x3000, v188
	v_mul_hi_i32_i24_e32 v191, 0x3000, v190
	v_mul_i32_i24_e32 v190, 0x3000, v190
	v_lshl_add_u64 v[188:189], s[24:25], 0, v[188:189]
	v_lshl_add_u64 v[190:191], s[24:25], 0, v[190:191]
	v_lshl_add_u64 v[186:187], v[186:187], 0, s[18:19]
	v_lshl_add_u64 v[188:189], v[188:189], 0, s[18:19]
	v_lshl_add_u64 v[190:191], v[190:191], 0, s[18:19]
	v_lshl_add_u64 v[206:207], v[186:187], 0, v[180:181]
	v_add_u32_e32 v208, 18, v225
	v_min_i32_e32 v208, 0x7fff, v208
	v_ashrrev_i32_e32 v208, 12, v208
	v_add_u32_e32 v208, 16, v208
	v_mul_hi_i32_i24_e32 v209, 0x3000, v208
	v_mul_i32_i24_e32 v208, 0x3000, v208
	v_lshl_add_u64 v[208:209], s[24:25], 0, v[208:209]
	v_lshl_add_u64 v[202:203], v[188:189], 0, v[180:181]
	v_lshl_add_u64 v[204:205], v[190:191], 0, v[180:181]
	global_load_dword v232, v[196:197], off
	global_load_dword v233, v[196:197], off offset:128
	global_load_dword v242, v[206:207], off
	global_load_dword v243, v[206:207], off offset:128
	global_load_dword v244, v[202:203], off
	global_load_dword v245, v[202:203], off offset:128
	global_load_dword v246, v[204:205], off
	global_load_dword v247, v[204:205], off offset:128
	v_add_u32_e32 v196, 17, v225
	v_min_i32_e32 v196, 0x7fff, v196
	v_ashrrev_i32_e32 v196, 12, v196
	v_add_u32_e32 v196, 16, v196
	v_mul_hi_i32_i24_e32 v197, 0x3000, v196
	v_mul_i32_i24_e32 v196, 0x3000, v196
	v_lshl_add_u64 v[196:197], s[24:25], 0, v[196:197]
	v_lshl_add_u64 v[196:197], v[196:197], 0, s[18:19]
	v_lshl_add_u64 v[206:207], v[196:197], 0, v[180:181]
	s_waitcnt vmcnt(7)
	s_nop 5
	v_mul_f32_e32 v112, v112, v232
	v_add_u32_e32 v192, 11, v225
	v_add_u32_e32 v194, 16, v225
	v_min_i32_e32 v192, 0x7fff, v192
	v_min_i32_e32 v194, 0x7fff, v194
	v_ashrrev_i32_e32 v192, 12, v192
	v_ashrrev_i32_e32 v194, 12, v194
	v_add_u32_e32 v192, 16, v192
	v_add_u32_e32 v194, 16, v194
	v_mul_hi_i32_i24_e32 v193, 0x3000, v192
	v_mul_i32_i24_e32 v192, 0x3000, v192
	v_mul_hi_i32_i24_e32 v195, 0x3000, v194
	v_mul_i32_i24_e32 v194, 0x3000, v194
	v_lshl_add_u64 v[192:193], s[24:25], 0, v[192:193]
	v_lshl_add_u64 v[194:195], s[24:25], 0, v[194:195]
	v_lshl_add_u64 v[192:193], v[192:193], 0, s[18:19]
	v_lshl_add_u64 v[194:195], v[194:195], 0, s[18:19]
	v_lshl_add_u64 v[202:203], v[192:193], 0, v[180:181]
	v_lshl_add_u64 v[204:205], v[194:195], 0, v[180:181]
	s_waitcnt vmcnt(6)
	s_nop 5
	v_mul_f32_e32 v96, v96, v233
	v_mul_f32_e32 v97, v97, v233
	v_lshl_add_u64 v[198:199], v[208:209], 0, s[18:19]
	v_lshl_add_u64 v[200:201], v[198:199], 0, v[180:181]
	global_load_dword v234, v[202:203], off
	global_load_dword v235, v[202:203], off offset:128
	global_load_dword v236, v[204:205], off
	global_load_dword v237, v[204:205], off offset:128
	global_load_dword v238, v[206:207], off
	global_load_dword v239, v[206:207], off offset:128
	global_load_dword v240, v[200:201], off
	global_load_dword v241, v[200:201], off offset:128
	v_add_u32_e32 v200, 19, v225
	v_add_u32_e32 v204, 25, v225
	v_add_u32_e32 v206, 26, v225
	v_min_i32_e32 v200, 0x7fff, v200
	v_add_u32_e32 v202, 24, v225
	v_min_i32_e32 v204, 0x7fff, v204
	v_min_i32_e32 v206, 0x7fff, v206
	v_ashrrev_i32_e32 v200, 12, v200
	v_min_i32_e32 v202, 0x7fff, v202
	v_ashrrev_i32_e32 v204, 12, v204
	v_ashrrev_i32_e32 v206, 12, v206
	v_add_u32_e32 v200, 16, v200
	v_ashrrev_i32_e32 v202, 12, v202
	v_add_u32_e32 v204, 16, v204
	v_add_u32_e32 v206, 16, v206
	v_mul_hi_i32_i24_e32 v201, 0x3000, v200
	v_mul_i32_i24_e32 v200, 0x3000, v200
	v_add_u32_e32 v202, 16, v202
	v_mul_hi_i32_i24_e32 v205, 0x3000, v204
	v_mul_i32_i24_e32 v204, 0x3000, v204
	v_mul_hi_i32_i24_e32 v207, 0x3000, v206
	v_mul_i32_i24_e32 v206, 0x3000, v206
	v_lshl_add_u64 v[200:201], s[24:25], 0, v[200:201]
	v_mul_hi_i32_i24_e32 v203, 0x3000, v202
	v_mul_i32_i24_e32 v202, 0x3000, v202
	v_lshl_add_u64 v[204:205], s[24:25], 0, v[204:205]
	v_lshl_add_u64 v[206:207], s[24:25], 0, v[206:207]
	v_lshl_add_u64 v[200:201], v[200:201], 0, s[18:19]
	v_lshl_add_u64 v[202:203], s[24:25], 0, v[202:203]
	v_lshl_add_u64 v[204:205], v[204:205], 0, s[18:19]
	v_lshl_add_u64 v[206:207], v[206:207], 0, s[18:19]
	v_lshl_add_u64 v[208:209], v[200:201], 0, v[180:181]
	v_lshl_add_u64 v[202:203], v[202:203], 0, s[18:19]
	v_lshl_add_u64 v[228:229], v[204:205], 0, v[180:181]
	v_lshl_add_u64 v[230:231], v[206:207], 0, v[180:181]
	v_lshl_add_u64 v[226:227], v[202:203], 0, v[180:181]
	global_load_dword v248, v[208:209], off
	global_load_dword v249, v[208:209], off offset:128
	global_load_dword v250, v[226:227], off
	global_load_dword v251, v[226:227], off offset:128
	global_load_dword v252, v[228:229], off
	s_nop 0
	global_load_dword v228, v[228:229], off offset:128
	s_nop 0
	global_load_dword v229, v[230:231], off
	s_nop 0
	global_load_dword v230, v[230:231], off offset:128
	v_add_u32_e32 v208, 27, v225
	v_min_i32_e32 v208, 0x7fff, v208
	v_ashrrev_i32_e32 v208, 12, v208
	v_add_u32_e32 v208, 16, v208
	v_mul_hi_i32_i24_e32 v209, 0x3000, v208
	v_mul_i32_i24_e32 v208, 0x3000, v208
	v_lshl_add_u64 v[208:209], s[24:25], 0, v[208:209]
	v_lshl_add_u64 v[208:209], v[208:209], 0, s[18:19]
	v_lshl_add_u64 v[226:227], v[208:209], 0, v[180:181]
	global_load_dword v225, v[226:227], off
	s_nop 0
	global_load_dword v226, v[226:227], off offset:128
	v_mad_u64_u32 v[160:161], s[2:3], v183, s36, v[182:183]
	v_lshl_add_u32 v162, v160, 2, s34
	ds_write2_b32 v162, v112, v96 offset1:32
	v_mul_f32_e32 v96, v113, v232
	ds_write2_b32 v162, v96, v97 offset0:68 offset1:100
	v_mul_f32_e32 v96, v114, v232
	v_mul_f32_e32 v97, v98, v233
	ds_write2_b32 v162, v96, v97 offset0:136 offset1:168
	v_mul_f32_e32 v96, v115, v232
	v_mul_f32_e32 v97, v99, v233
	ds_write2_b32 v162, v96, v97 offset0:204 offset1:236
	s_waitcnt vmcnt(23)
	v_mul_f32_e32 v96, v116, v242
	s_waitcnt vmcnt(22)
	v_mul_f32_e32 v97, v100, v243
	v_add_u32_e32 v115, 0x800, v162
	ds_write2_b32 v115, v96, v97 offset0:32 offset1:64
	s_waitcnt vmcnt(21)
	v_mul_f32_e32 v96, v117, v244
	s_waitcnt vmcnt(20)
	v_mul_f32_e32 v97, v101, v245
	ds_write2_b32 v115, v96, v97 offset0:100 offset1:132
	s_waitcnt vmcnt(19)
	v_mul_f32_e32 v96, v118, v246
	s_waitcnt vmcnt(18)
	v_mul_f32_e32 v97, v102, v247
	ds_write2_b32 v115, v96, v97 offset0:168 offset1:200
	v_add_u32_e32 v116, 0xa00, v162
	v_add_u32_e32 v117, 0x1000, v162
	s_waitcnt vmcnt(17)
	v_mul_f32_e32 v96, v119, v234
	s_waitcnt vmcnt(16)
	v_mul_f32_e32 v97, v103, v235
	ds_write2_b32 v116, v96, v97 offset0:108 offset1:140
	s_waitcnt vmcnt(15)
	v_mul_f32_e32 v96, v120, v236
	s_waitcnt vmcnt(14)
	v_mul_f32_e32 v97, v104, v237
	ds_write2_b32 v117, v96, v97 offset0:64 offset1:96
	s_waitcnt vmcnt(13)
	v_mul_f32_e32 v96, v121, v238
	s_waitcnt vmcnt(12)
	v_mul_f32_e32 v97, v105, v239
	ds_write2_b32 v117, v96, v97 offset0:132 offset1:164
	s_waitcnt vmcnt(11)
	v_mul_f32_e32 v96, v122, v240
	s_waitcnt vmcnt(10)
	v_mul_f32_e32 v97, v106, v241
	ds_write2_b32 v117, v96, v97 offset0:200 offset1:232
	v_add_u32_e32 v118, 0x1400, v162
	v_add_u32_e32 v119, 0x1800, v162
	v_ashrrev_i32_e32 v163, 4, v168
	v_and_b32_e32 v160, 15, v168
	v_add_u32_e32 v120, 0x1a00, v162
	v_mul_lo_u32 v164, v163, s37
	v_lshl_add_u32 v165, v160, 4, s34
	v_lshlrev_b32_e32 v168, 2, v160
	v_add_u32_e32 v160, s55, v163
	v_add_u32_e32 v121, 0x1c00, v162
	v_cmp_gt_i32_e32 vcc, s38, v160
	v_ashrrev_i32_e32 v161, 31, v160
	v_add_u32_e32 v114, v165, v164
	s_waitcnt vmcnt(9)
	v_mul_f32_e32 v96, v123, v248
	s_waitcnt vmcnt(8)
	v_mul_f32_e32 v97, v107, v249
	ds_write2_b32 v118, v96, v97 offset0:12 offset1:44
	s_waitcnt vmcnt(7)
	v_mul_f32_e32 v96, v124, v250
	s_waitcnt vmcnt(6)
	v_mul_f32_e32 v97, v108, v251
	ds_write2_b32 v119, v96, v97 offset0:96 offset1:128
	s_waitcnt vmcnt(5)
	v_mul_f32_e32 v96, v125, v252
	s_waitcnt vmcnt(4)
	v_mul_f32_e32 v97, v109, v228
	ds_write2_b32 v119, v96, v97 offset0:164 offset1:196
	s_waitcnt vmcnt(3)
	v_mul_f32_e32 v96, v126, v229
	s_waitcnt vmcnt(2)
	v_mul_f32_e32 v97, v110, v230
	ds_write2_b32 v120, v96, v97 offset0:104 offset1:136
	s_waitcnt vmcnt(1)
	v_mul_f32_e32 v96, v127, v225
	s_waitcnt vmcnt(0)
	v_mul_f32_e32 v97, v111, v226
	ds_write2_b32 v121, v96, v97 offset0:44 offset1:76
	v_or_b32_e32 v96, s26, v168
	v_mov_b32_e32 v97, s27
	v_add_u32_e32 v128, 0, v160
	v_ashrrev_i32_e32 v129, 31, v128
	v_lshlrev_b64 v[128:129], 12, v[128:129]
	v_lshl_add_u64 v[128:129], s[16:17], 0, v[128:129]
	v_lshl_add_u64 v[128:129], v[96:97], 2, v[128:129]
	global_load_dwordx4 v[128:131], v[128:129], off
	v_add_u32_e32 v132, 4, v160
	v_ashrrev_i32_e32 v133, 31, v132
	v_lshlrev_b64 v[132:133], 12, v[132:133]
	v_lshl_add_u64 v[132:133], s[16:17], 0, v[132:133]
	v_lshl_add_u64 v[132:133], v[96:97], 2, v[132:133]
	global_load_dwordx4 v[132:135], v[132:133], off
	v_add_u32_e32 v136, 8, v160
	v_ashrrev_i32_e32 v137, 31, v136
	v_lshlrev_b64 v[136:137], 12, v[136:137]
	v_lshl_add_u64 v[136:137], s[16:17], 0, v[136:137]
	v_lshl_add_u64 v[136:137], v[96:97], 2, v[136:137]
	global_load_dwordx4 v[136:139], v[136:137], off
	v_add_u32_e32 v140, 12, v160
	v_ashrrev_i32_e32 v141, 31, v140
	v_lshlrev_b64 v[140:141], 12, v[140:141]
	v_lshl_add_u64 v[140:141], s[16:17], 0, v[140:141]
	v_lshl_add_u64 v[140:141], v[96:97], 2, v[140:141]
	global_load_dwordx4 v[140:143], v[140:141], off
	v_add_u32_e32 v144, 16, v160
	v_ashrrev_i32_e32 v145, 31, v144
	v_lshlrev_b64 v[144:145], 12, v[144:145]
	v_lshl_add_u64 v[144:145], s[16:17], 0, v[144:145]
	v_lshl_add_u64 v[144:145], v[96:97], 2, v[144:145]
	global_load_dwordx4 v[144:147], v[144:145], off
	v_add_u32_e32 v148, 20, v160
	v_ashrrev_i32_e32 v149, 31, v148
	v_lshlrev_b64 v[148:149], 12, v[148:149]
	v_lshl_add_u64 v[148:149], s[16:17], 0, v[148:149]
	v_lshl_add_u64 v[148:149], v[96:97], 2, v[148:149]
	global_load_dwordx4 v[148:151], v[148:149], off
	v_add_u32_e32 v152, 24, v160
	v_ashrrev_i32_e32 v153, 31, v152
	v_lshlrev_b64 v[152:153], 12, v[152:153]
	v_lshl_add_u64 v[152:153], s[16:17], 0, v[152:153]
	v_lshl_add_u64 v[152:153], v[96:97], 2, v[152:153]
	global_load_dwordx4 v[152:155], v[152:153], off
	v_add_u32_e32 v156, 28, v160
	v_ashrrev_i32_e32 v157, 31, v156
	v_lshlrev_b64 v[156:157], 12, v[156:157]
	v_lshl_add_u64 v[156:157], s[16:17], 0, v[156:157]
	v_lshl_add_u64 v[156:157], v[96:97], 2, v[156:157]
	global_load_dwordx4 v[156:159], v[156:157], off
	s_and_saveexec_b64 s[2:3], vcc
	s_cbranch_execz .LBB0_4484
	v_lshlrev_b64 v[98:99], 12, v[160:161]
	v_lshl_add_u64 v[98:99], s[16:17], 0, v[98:99]
	v_lshl_add_u64 v[106:107], v[96:97], 2, v[98:99]
	ds_read_b128 v[102:105], v114
	s_waitcnt vmcnt(7) lgkmcnt(0)
	v_pk_add_f32 v[100:101], v[104:105], v[130:131]
	v_pk_add_f32 v[98:99], v[102:103], v[128:129]
	global_store_dwordx4 v[106:107], v[98:101], off

.LBB0_5644:
	ds_read_b128 v[128:131], v238
	ds_read_b128 v[136:139], v253
	ds_read_b128 v[132:135], v238 offset:4096
	ds_read_b128 v[140:143], v253 offset:4096
	ds_read_b128 v[144:147], v253 offset:8192
	ds_read_b128 v[148:151], v253 offset:12288
	s_waitcnt lgkmcnt(6)
	v_mfma_f32_32x32x16_bf16 v[112:127], v[188:191], v[196:199], v[112:127]
	v_mfma_f32_32x32x16_bf16 v[96:111], v[188:191], v[200:203], v[96:111]
	v_mfma_f32_32x32x16_bf16 v[80:95], v[188:191], v[204:207], v[80:95]
	v_mfma_f32_32x32x16_bf16 v[64:79], v[188:191], v[226:229], v[64:79]
	v_mfma_f32_32x32x16_bf16 v[48:63], v[192:195], v[196:199], v[48:63]
	v_mfma_f32_32x32x16_bf16 v[32:47], v[192:195], v[200:203], v[32:47]
	v_mfma_f32_32x32x16_bf16 v[16:31], v[192:195], v[204:207], v[16:31]
	v_mfma_f32_32x32x16_bf16 v[0:15], v[192:195], v[226:229], v[0:15]
	ds_read_b128 v[188:191], v239
	ds_read_b128 v[196:199], v254
	ds_read_b128 v[192:195], v239 offset:4096
	ds_read_b128 v[200:203], v254 offset:4096
	ds_read_b128 v[204:207], v254 offset:8192
	ds_read_b128 v[226:229], v254 offset:12288
	s_waitcnt lgkmcnt(6)
	v_mfma_f32_32x32x16_bf16 v[112:127], v[128:131], v[136:139], v[112:127]
	v_mfma_f32_32x32x16_bf16 v[96:111], v[128:131], v[140:143], v[96:111]
	v_mfma_f32_32x32x16_bf16 v[80:95], v[128:131], v[144:147], v[80:95]
	v_mfma_f32_32x32x16_bf16 v[64:79], v[128:131], v[148:151], v[64:79]
	v_mfma_f32_32x32x16_bf16 v[48:63], v[132:135], v[136:139], v[48:63]
	v_mfma_f32_32x32x16_bf16 v[32:47], v[132:135], v[140:143], v[32:47]
	v_mfma_f32_32x32x16_bf16 v[16:31], v[132:135], v[144:147], v[16:31]
	v_mfma_f32_32x32x16_bf16 v[0:15], v[132:135], v[148:151], v[0:15]
	ds_read_b128 v[128:131], v240
	ds_read_b128 v[136:139], v255
	ds_read_b128 v[132:135], v240 offset:4096
	ds_read_b128 v[140:143], v255 offset:4096
	ds_read_b128 v[144:147], v255 offset:8192
	ds_read_b128 v[148:151], v255 offset:12288
	s_waitcnt lgkmcnt(6)
	v_mfma_f32_32x32x16_bf16 v[112:127], v[188:191], v[196:199], v[112:127]
	v_mfma_f32_32x32x16_bf16 v[96:111], v[188:191], v[200:203], v[96:111]
	v_mfma_f32_32x32x16_bf16 v[80:95], v[188:191], v[204:207], v[80:95]
	v_mfma_f32_32x32x16_bf16 v[64:79], v[188:191], v[226:229], v[64:79]
	v_mfma_f32_32x32x16_bf16 v[48:63], v[192:195], v[196:199], v[48:63]
	v_mfma_f32_32x32x16_bf16 v[32:47], v[192:195], v[200:203], v[32:47]
	v_mfma_f32_32x32x16_bf16 v[16:31], v[192:195], v[204:207], v[16:31]
	v_mfma_f32_32x32x16_bf16 v[0:15], v[192:195], v[226:229], v[0:15]
	s_waitcnt vmcnt(0) lgkmcnt(0)
	s_barrier
	v_mfma_f32_32x32x16_bf16 v[112:127], v[128:131], v[136:139], v[112:127]
	v_mfma_f32_32x32x16_bf16 v[96:111], v[128:131], v[140:143], v[96:111]
	v_mfma_f32_32x32x16_bf16 v[80:95], v[128:131], v[144:147], v[80:95]
	v_mfma_f32_32x32x16_bf16 v[64:79], v[128:131], v[148:151], v[64:79]
	v_mfma_f32_32x32x16_bf16 v[48:63], v[132:135], v[136:139], v[48:63]
	v_mfma_f32_32x32x16_bf16 v[32:47], v[132:135], v[140:143], v[32:47]
	v_mfma_f32_32x32x16_bf16 v[16:31], v[132:135], v[144:147], v[16:31]
	v_mfma_f32_32x32x16_bf16 v[0:15], v[132:135], v[148:151], v[0:15]
	s_lshl_b32 s2, s5, 8
	s_sub_i32 s2, s2, s6
	v_mov_b32_e32 v168, v214
	s_add_i32 s55, s4, s30
	s_or_b32 s26, s2, s31
	s_ashr_i32 s27, s26, 31
	s_load_dwordx2 s[24:25], s[0:1], 0x140
	v_ashrrev_i32_e32 v180, 3, v168
	v_and_b32_e32 v183, -4, v180
	v_add_u32_e32 v225, s55, v183
	v_add_u32_e32 v190, 8, v225
	v_min_i32_e32 v190, 0x7fff, v190
	v_ashrrev_i32_e32 v190, 12, v190
	v_add_u32_e32 v190, 24, v190
	v_mul_hi_i32_i24_e32 v191, 0x3000, v190
	v_mul_i32_i24_e32 v190, 0x3000, v190
	v_min_i32_e32 v184, 0x7fff, v225
	v_ashrrev_i32_e32 v184, 12, v184
	v_and_b32_e32 v182, 31, v168
	v_add_u32_e32 v184, 24, v184
	v_or_b32_e32 v180, s26, v182
	v_mul_hi_i32_i24_e32 v185, 0x3000, v184
	v_mul_i32_i24_e32 v184, 0x3000, v184
	v_ashrrev_i32_e32 v181, 31, v180
	s_waitcnt lgkmcnt(0)
	v_lshl_add_u64 v[184:185], s[24:25], 0, v[184:185]
	v_lshl_add_u64 v[184:185], v[184:185], 0, s[18:19]
	v_lshlrev_b64 v[180:181], 2, v[180:181]
	v_lshl_add_u64 v[196:197], v[184:185], 0, v[180:181]
	v_lshl_add_u64 v[186:187], s[24:25], 0, v[190:191]
	v_add_u32_e32 v188, 9, v225
	v_add_u32_e32 v190, 10, v225
	v_min_i32_e32 v188, 0x7fff, v188
	v_min_i32_e32 v190, 0x7fff, v190
	v_ashrrev_i32_e32 v188, 12, v188
	v_ashrrev_i32_e32 v190, 12, v190
	v_add_u32_e32 v188, 24, v188
	v_add_u32_e32 v190, 24, v190
	v_mul_hi_i32_i24_e32 v189, 0x3000, v188
	v_mul_i32_i24_e32 v188, 0x3000, v188
	v_mul_hi_i32_i24_e32 v191, 0x3000, v190
	v_mul_i32_i24_e32 v190, 0x3000, v190
	v_lshl_add_u64 v[188:189], s[24:25], 0, v[188:189]
	v_lshl_add_u64 v[190:191], s[24:25], 0, v[190:191]
	v_lshl_add_u64 v[186:187], v[186:187], 0, s[18:19]
	v_lshl_add_u64 v[188:189], v[188:189], 0, s[18:19]
	v_lshl_add_u64 v[190:191], v[190:191], 0, s[18:19]
	v_lshl_add_u64 v[206:207], v[186:187], 0, v[180:181]
	v_add_u32_e32 v208, 18, v225
	v_min_i32_e32 v208, 0x7fff, v208
	v_ashrrev_i32_e32 v208, 12, v208
	v_add_u32_e32 v208, 24, v208
	v_mul_hi_i32_i24_e32 v209, 0x3000, v208
	v_mul_i32_i24_e32 v208, 0x3000, v208
	v_lshl_add_u64 v[208:209], s[24:25], 0, v[208:209]
	v_lshl_add_u64 v[202:203], v[188:189], 0, v[180:181]
	v_lshl_add_u64 v[204:205], v[190:191], 0, v[180:181]
	global_load_dword v232, v[196:197], off
	global_load_dword v233, v[196:197], off offset:128
	global_load_dword v242, v[206:207], off
	global_load_dword v243, v[206:207], off offset:128
	global_load_dword v244, v[202:203], off
	global_load_dword v245, v[202:203], off offset:128
	global_load_dword v246, v[204:205], off
	global_load_dword v247, v[204:205], off offset:128
	v_add_u32_e32 v196, 17, v225
	v_min_i32_e32 v196, 0x7fff, v196
	v_ashrrev_i32_e32 v196, 12, v196
	v_add_u32_e32 v196, 24, v196
	v_mul_hi_i32_i24_e32 v197, 0x3000, v196
	v_mul_i32_i24_e32 v196, 0x3000, v196
	v_lshl_add_u64 v[196:197], s[24:25], 0, v[196:197]
	v_lshl_add_u64 v[196:197], v[196:197], 0, s[18:19]
	v_lshl_add_u64 v[206:207], v[196:197], 0, v[180:181]
	s_waitcnt vmcnt(7)
	s_nop 5
	v_mul_f32_e32 v112, v112, v232
	v_add_u32_e32 v192, 11, v225
	v_add_u32_e32 v194, 16, v225
	v_min_i32_e32 v192, 0x7fff, v192
	v_min_i32_e32 v194, 0x7fff, v194
	v_ashrrev_i32_e32 v192, 12, v192
	v_ashrrev_i32_e32 v194, 12, v194
	v_add_u32_e32 v192, 24, v192
	v_add_u32_e32 v194, 24, v194
	v_mul_hi_i32_i24_e32 v193, 0x3000, v192
	v_mul_i32_i24_e32 v192, 0x3000, v192
	v_mul_hi_i32_i24_e32 v195, 0x3000, v194
	v_mul_i32_i24_e32 v194, 0x3000, v194
	v_lshl_add_u64 v[192:193], s[24:25], 0, v[192:193]
	v_lshl_add_u64 v[194:195], s[24:25], 0, v[194:195]
	v_lshl_add_u64 v[192:193], v[192:193], 0, s[18:19]
	v_lshl_add_u64 v[194:195], v[194:195], 0, s[18:19]
	v_lshl_add_u64 v[202:203], v[192:193], 0, v[180:181]
	v_lshl_add_u64 v[204:205], v[194:195], 0, v[180:181]
	s_waitcnt vmcnt(6)
	s_nop 5
	v_mul_f32_e32 v96, v96, v233
	v_mul_f32_e32 v97, v97, v233
	v_lshl_add_u64 v[198:199], v[208:209], 0, s[18:19]
	v_lshl_add_u64 v[200:201], v[198:199], 0, v[180:181]
	global_load_dword v234, v[202:203], off
	global_load_dword v235, v[202:203], off offset:128
	global_load_dword v236, v[204:205], off
	global_load_dword v237, v[204:205], off offset:128
	global_load_dword v238, v[206:207], off
	global_load_dword v239, v[206:207], off offset:128
	global_load_dword v240, v[200:201], off
	global_load_dword v241, v[200:201], off offset:128
	v_add_u32_e32 v200, 19, v225
	v_add_u32_e32 v204, 25, v225
	v_add_u32_e32 v206, 26, v225
	v_min_i32_e32 v200, 0x7fff, v200
	v_add_u32_e32 v202, 24, v225
	v_min_i32_e32 v204, 0x7fff, v204
	v_min_i32_e32 v206, 0x7fff, v206
	v_ashrrev_i32_e32 v200, 12, v200
	v_min_i32_e32 v202, 0x7fff, v202
	v_ashrrev_i32_e32 v204, 12, v204
	v_ashrrev_i32_e32 v206, 12, v206
	v_add_u32_e32 v200, 24, v200
	v_ashrrev_i32_e32 v202, 12, v202
	v_add_u32_e32 v204, 24, v204
	v_add_u32_e32 v206, 24, v206
	v_mul_hi_i32_i24_e32 v201, 0x3000, v200
	v_mul_i32_i24_e32 v200, 0x3000, v200
	v_add_u32_e32 v202, 24, v202
	v_mul_hi_i32_i24_e32 v205, 0x3000, v204
	v_mul_i32_i24_e32 v204, 0x3000, v204
	v_mul_hi_i32_i24_e32 v207, 0x3000, v206
	v_mul_i32_i24_e32 v206, 0x3000, v206
	v_lshl_add_u64 v[200:201], s[24:25], 0, v[200:201]
	v_mul_hi_i32_i24_e32 v203, 0x3000, v202
	v_mul_i32_i24_e32 v202, 0x3000, v202
	v_lshl_add_u64 v[204:205], s[24:25], 0, v[204:205]
	v_lshl_add_u64 v[206:207], s[24:25], 0, v[206:207]
	v_lshl_add_u64 v[200:201], v[200:201], 0, s[18:19]
	v_lshl_add_u64 v[202:203], s[24:25], 0, v[202:203]
	v_lshl_add_u64 v[204:205], v[204:205], 0, s[18:19]
	v_lshl_add_u64 v[206:207], v[206:207], 0, s[18:19]
	v_lshl_add_u64 v[208:209], v[200:201], 0, v[180:181]
	v_lshl_add_u64 v[202:203], v[202:203], 0, s[18:19]
	v_lshl_add_u64 v[228:229], v[204:205], 0, v[180:181]
	v_lshl_add_u64 v[230:231], v[206:207], 0, v[180:181]
	v_lshl_add_u64 v[226:227], v[202:203], 0, v[180:181]
	global_load_dword v248, v[208:209], off
	global_load_dword v249, v[208:209], off offset:128
	global_load_dword v250, v[226:227], off
	global_load_dword v251, v[226:227], off offset:128
	global_load_dword v252, v[228:229], off
	s_nop 0
	global_load_dword v228, v[228:229], off offset:128
	s_nop 0
	global_load_dword v229, v[230:231], off
	s_nop 0
	global_load_dword v230, v[230:231], off offset:128
	v_add_u32_e32 v208, 27, v225
	v_min_i32_e32 v208, 0x7fff, v208
	v_ashrrev_i32_e32 v208, 12, v208
	v_add_u32_e32 v208, 24, v208
	v_mul_hi_i32_i24_e32 v209, 0x3000, v208
	v_mul_i32_i24_e32 v208, 0x3000, v208
	v_lshl_add_u64 v[208:209], s[24:25], 0, v[208:209]
	v_lshl_add_u64 v[208:209], v[208:209], 0, s[18:19]
	v_lshl_add_u64 v[226:227], v[208:209], 0, v[180:181]
	global_load_dword v225, v[226:227], off
	s_nop 0
	global_load_dword v226, v[226:227], off offset:128
	v_mad_u64_u32 v[160:161], s[2:3], v183, s36, v[182:183]
	v_lshl_add_u32 v162, v160, 2, s34
	ds_write2_b32 v162, v112, v96 offset1:32
	v_mul_f32_e32 v96, v113, v232
	ds_write2_b32 v162, v96, v97 offset0:68 offset1:100
	v_mul_f32_e32 v96, v114, v232
	v_mul_f32_e32 v97, v98, v233
	ds_write2_b32 v162, v96, v97 offset0:136 offset1:168
	v_mul_f32_e32 v96, v115, v232
	v_mul_f32_e32 v97, v99, v233
	ds_write2_b32 v162, v96, v97 offset0:204 offset1:236
	s_waitcnt vmcnt(23)
	v_mul_f32_e32 v96, v116, v242
	s_waitcnt vmcnt(22)
	v_mul_f32_e32 v97, v100, v243
	v_add_u32_e32 v115, 0x800, v162
	ds_write2_b32 v115, v96, v97 offset0:32 offset1:64
	s_waitcnt vmcnt(21)
	v_mul_f32_e32 v96, v117, v244
	s_waitcnt vmcnt(20)
	v_mul_f32_e32 v97, v101, v245
	ds_write2_b32 v115, v96, v97 offset0:100 offset1:132
	s_waitcnt vmcnt(19)
	v_mul_f32_e32 v96, v118, v246
	s_waitcnt vmcnt(18)
	v_mul_f32_e32 v97, v102, v247
	ds_write2_b32 v115, v96, v97 offset0:168 offset1:200
	v_add_u32_e32 v116, 0xa00, v162
	v_add_u32_e32 v117, 0x1000, v162
	s_waitcnt vmcnt(17)
	v_mul_f32_e32 v96, v119, v234
	s_waitcnt vmcnt(16)
	v_mul_f32_e32 v97, v103, v235
	ds_write2_b32 v116, v96, v97 offset0:108 offset1:140
	s_waitcnt vmcnt(15)
	v_mul_f32_e32 v96, v120, v236
	s_waitcnt vmcnt(14)
	v_mul_f32_e32 v97, v104, v237
	ds_write2_b32 v117, v96, v97 offset0:64 offset1:96
	s_waitcnt vmcnt(13)
	v_mul_f32_e32 v96, v121, v238
	s_waitcnt vmcnt(12)
	v_mul_f32_e32 v97, v105, v239
	ds_write2_b32 v117, v96, v97 offset0:132 offset1:164
	s_waitcnt vmcnt(11)
	v_mul_f32_e32 v96, v122, v240
	s_waitcnt vmcnt(10)
	v_mul_f32_e32 v97, v106, v241
	ds_write2_b32 v117, v96, v97 offset0:200 offset1:232
	v_add_u32_e32 v118, 0x1400, v162
	v_add_u32_e32 v119, 0x1800, v162
	v_ashrrev_i32_e32 v163, 4, v168
	v_and_b32_e32 v160, 15, v168
	v_add_u32_e32 v120, 0x1a00, v162
	v_mul_lo_u32 v164, v163, s37
	v_lshl_add_u32 v165, v160, 4, s34
	v_lshlrev_b32_e32 v168, 2, v160
	v_add_u32_e32 v160, s55, v163
	v_add_u32_e32 v121, 0x1c00, v162
	v_cmp_gt_i32_e32 vcc, s38, v160
	v_ashrrev_i32_e32 v161, 31, v160
	v_add_u32_e32 v114, v165, v164
	s_waitcnt vmcnt(9)
	v_mul_f32_e32 v96, v123, v248
	s_waitcnt vmcnt(8)
	v_mul_f32_e32 v97, v107, v249
	ds_write2_b32 v118, v96, v97 offset0:12 offset1:44
	s_waitcnt vmcnt(7)
	v_mul_f32_e32 v96, v124, v250
	s_waitcnt vmcnt(6)
	v_mul_f32_e32 v97, v108, v251
	ds_write2_b32 v119, v96, v97 offset0:96 offset1:128
	s_waitcnt vmcnt(5)
	v_mul_f32_e32 v96, v125, v252
	s_waitcnt vmcnt(4)
	v_mul_f32_e32 v97, v109, v228
	ds_write2_b32 v119, v96, v97 offset0:164 offset1:196
	s_waitcnt vmcnt(3)
	v_mul_f32_e32 v96, v126, v229
	s_waitcnt vmcnt(2)
	v_mul_f32_e32 v97, v110, v230
	ds_write2_b32 v120, v96, v97 offset0:104 offset1:136
	s_waitcnt vmcnt(1)
	v_mul_f32_e32 v96, v127, v225
	s_waitcnt vmcnt(0)
	v_mul_f32_e32 v97, v111, v226
	ds_write2_b32 v121, v96, v97 offset0:44 offset1:76
	v_or_b32_e32 v96, s26, v168
	v_mov_b32_e32 v97, s27
	v_add_u32_e32 v128, 0, v160
	v_ashrrev_i32_e32 v129, 31, v128
	v_lshlrev_b64 v[128:129], 12, v[128:129]
	v_lshl_add_u64 v[128:129], s[16:17], 0, v[128:129]
	v_lshl_add_u64 v[128:129], v[96:97], 2, v[128:129]
	global_load_dwordx4 v[128:131], v[128:129], off
	v_add_u32_e32 v132, 4, v160
	v_ashrrev_i32_e32 v133, 31, v132
	v_lshlrev_b64 v[132:133], 12, v[132:133]
	v_lshl_add_u64 v[132:133], s[16:17], 0, v[132:133]
	v_lshl_add_u64 v[132:133], v[96:97], 2, v[132:133]
	global_load_dwordx4 v[132:135], v[132:133], off
	v_add_u32_e32 v136, 8, v160
	v_ashrrev_i32_e32 v137, 31, v136
	v_lshlrev_b64 v[136:137], 12, v[136:137]
	v_lshl_add_u64 v[136:137], s[16:17], 0, v[136:137]
	v_lshl_add_u64 v[136:137], v[96:97], 2, v[136:137]
	global_load_dwordx4 v[136:139], v[136:137], off
	v_add_u32_e32 v140, 12, v160
	v_ashrrev_i32_e32 v141, 31, v140
	v_lshlrev_b64 v[140:141], 12, v[140:141]
	v_lshl_add_u64 v[140:141], s[16:17], 0, v[140:141]
	v_lshl_add_u64 v[140:141], v[96:97], 2, v[140:141]
	global_load_dwordx4 v[140:143], v[140:141], off
	v_add_u32_e32 v144, 16, v160
	v_ashrrev_i32_e32 v145, 31, v144
	v_lshlrev_b64 v[144:145], 12, v[144:145]
	v_lshl_add_u64 v[144:145], s[16:17], 0, v[144:145]
	v_lshl_add_u64 v[144:145], v[96:97], 2, v[144:145]
	global_load_dwordx4 v[144:147], v[144:145], off
	v_add_u32_e32 v148, 20, v160
	v_ashrrev_i32_e32 v149, 31, v148
	v_lshlrev_b64 v[148:149], 12, v[148:149]
	v_lshl_add_u64 v[148:149], s[16:17], 0, v[148:149]
	v_lshl_add_u64 v[148:149], v[96:97], 2, v[148:149]
	global_load_dwordx4 v[148:151], v[148:149], off
	v_add_u32_e32 v152, 24, v160
	v_ashrrev_i32_e32 v153, 31, v152
	v_lshlrev_b64 v[152:153], 12, v[152:153]
	v_lshl_add_u64 v[152:153], s[16:17], 0, v[152:153]
	v_lshl_add_u64 v[152:153], v[96:97], 2, v[152:153]
	global_load_dwordx4 v[152:155], v[152:153], off
	v_add_u32_e32 v156, 28, v160
	v_ashrrev_i32_e32 v157, 31, v156
	v_lshlrev_b64 v[156:157], 12, v[156:157]
	v_lshl_add_u64 v[156:157], s[16:17], 0, v[156:157]
	v_lshl_add_u64 v[156:157], v[96:97], 2, v[156:157]
	global_load_dwordx4 v[156:159], v[156:157], off
	s_and_saveexec_b64 s[2:3], vcc
	s_cbranch_execz .LBB0_5646
	v_lshlrev_b64 v[98:99], 12, v[160:161]
	v_lshl_add_u64 v[98:99], s[16:17], 0, v[98:99]
	v_lshl_add_u64 v[106:107], v[96:97], 2, v[98:99]
	ds_read_b128 v[102:105], v114
	s_waitcnt vmcnt(7) lgkmcnt(0)
	v_pk_add_f32 v[100:101], v[104:105], v[130:131]
	v_pk_add_f32 v[98:99], v[102:103], v[128:129]
	global_store_dwordx4 v[106:107], v[98:101], off
